# v26 + packed f32 VALU (v_pk_mul/add/fma_f32) split into scalar ops in the attention loops (bit-identical)
# baseline (speedup 1.0000x reference)
.LBB0_345:
	v_add_f32_e32 v64, 0, v199
	v_add_f32_e32 v64, v200, v64
	v_add_f32_e32 v64, v201, v64
	v_add_f32_e32 v64, v202, v64
	v_add_f32_e32 v64, v203, v64
	v_add_f32_e32 v64, v204, v64
	v_add_f32_e32 v64, v205, v64
	v_add_f32_e32 v64, v206, v64
	v_add_f32_e32 v64, v207, v64
	v_add_f32_e32 v64, v208, v64
	v_add_f32_e32 v64, v209, v64
	v_add_f32_e32 v64, v210, v64
	v_add_f32_e32 v64, v211, v64
	v_add_f32_e32 v64, v212, v64
	v_add_f32_e32 v64, v214, v64
	v_add_f32_e32 v64, v215, v64
	v_add_f32_e32 v64, v216, v64
	v_add_f32_e32 v64, v217, v64
	v_add_f32_e32 v64, v218, v64
	v_add_f32_e32 v64, v219, v64
	v_add_f32_e32 v64, v237, v64
	v_add_f32_e32 v65, v238, v64
	v_add_f32_e32 v64, 0, v97
	v_add_f32_e32 v64, v81, v64
	v_add_f32_e32 v64, v82, v64
	v_add_f32_e32 v64, v83, v64
	v_add_f32_e32 v64, v84, v64
	v_add_f32_e32 v64, v85, v64
	v_add_f32_e32 v64, v86, v64
	v_add_f32_e32 v64, v87, v64
	v_add_f32_e32 v64, v88, v64
	v_add_f32_e32 v64, v89, v64
	v_add_f32_e32 v64, v90, v64
	v_add_f32_e32 v64, v91, v64
	v_add_f32_e32 v64, v92, v64
	v_add_f32_e32 v64, v93, v64
	v_add_f32_e32 v64, v94, v64
	v_add_f32_e32 v64, v95, v64
	v_add_f32_e32 v64, v98, v64
	v_add_f32_e32 v64, v99, v64
	v_add_f32_e32 v64, v100, v64
	v_add_f32_e32 v64, v101, v64
	v_add_f32_e32 v64, v102, v64
	v_add_f32_e32 v64, v103, v64
	v_add_f32_e32 v64, v190, v64
	v_add_f32_e32 v65, v191, v65
	v_mov_b32_e32 v81, v176
	v_add_f32_e32 v64, v188, v64
	v_add_f32_e32 v65, v189, v65
	s_add_i32 s10, s10, 64
	v_add_f32_e32 v64, v126, v64
	v_add_f32_e32 v65, v127, v65
	s_cmp_lg_u32 s9, s11
	v_add_f32_e32 v64, v124, v64
	v_add_f32_e32 v65, v125, v65
	v_mov_b32_e32 v188, v96
	v_add_f32_e32 v64, v122, v64
	v_add_f32_e32 v65, v123, v65
	v_mov_b32_e32 v176, v198
	v_add_f32_e32 v64, v120, v64
	v_add_f32_e32 v65, v121, v65
	s_mov_b32 s12, s11
	v_add_f32_e32 v64, v118, v64
	v_add_f32_e32 v65, v119, v65
	s_waitcnt lgkmcnt(0)
	v_add_f32_e32 v64, v116, v64
	v_add_f32_e32 v65, v117, v65
	s_barrier
	v_add_f32_e32 v64, v114, v64
	v_add_f32_e32 v65, v115, v65
	s_nop 0
	v_add_f32_e32 v64, v112, v64
	v_add_f32_e32 v65, v113, v65
	s_nop 0
	v_fma_f32 v186, v186, v80, v64
	v_fma_f32 v187, v187, v81, v65
	s_cbranch_scc0 .LBB0_350

.LBB0_348:
	s_bitcmp1_b32 s12, 0
	s_cselect_b32 s12, 0x4800, 0
	v_add_u32_e32 v190, s12, v197
	v_add_u32_e32 v189, v190, v195
	ds_read_b128 v[64:67], v189
	ds_read_b128 v[68:71], v189 offset:32
	s_waitcnt lgkmcnt(1)
	v_mfma_f32_32x32x16_bf16 v[112:127], v[64:67], v[128:131], 0
	ds_read_b128 v[198:201], v189 offset:4640
	v_mfma_f32_32x32x16_bf16 v[80:95], v[64:67], v[144:147], 0
	ds_read_b128 v[64:67], v189 offset:64
	s_waitcnt lgkmcnt(2)
	v_mfma_f32_32x32x16_bf16 v[112:127], v[68:71], v[132:135], v[112:127]
	v_mfma_f32_32x32x16_bf16 v[80:95], v[68:71], v[148:151], v[80:95]
	s_waitcnt lgkmcnt(0)
	v_mfma_f32_32x32x16_bf16 v[112:127], v[64:67], v[136:139], v[112:127]
	v_mfma_f32_32x32x16_bf16 v[80:95], v[64:67], v[152:155], v[80:95]
	ds_read_b128 v[64:67], v189 offset:96
	s_waitcnt lgkmcnt(0)
	v_mfma_f32_32x32x16_bf16 v[112:127], v[64:67], v[140:143], v[112:127]
	v_mfma_f32_32x32x16_bf16 v[80:95], v[64:67], v[156:159], v[80:95]
	ds_read_b128 v[64:67], v189 offset:4608
	s_waitcnt lgkmcnt(0)
	v_mfma_f32_32x32x16_bf16 v[96:111], v[64:67], v[128:131], 0
	v_mfma_f32_32x32x16_bf16 v[64:79], v[64:67], v[144:147], 0
	v_mfma_f32_32x32x16_bf16 v[96:111], v[198:201], v[132:135], v[96:111]
	v_mfma_f32_32x32x16_bf16 v[64:79], v[198:201], v[148:151], v[64:79]
	ds_read_b128 v[198:201], v189 offset:4672
	s_waitcnt lgkmcnt(0)
	v_mfma_f32_32x32x16_bf16 v[96:111], v[198:201], v[136:139], v[96:111]
	v_mfma_f32_32x32x16_bf16 v[64:79], v[198:201], v[152:155], v[64:79]
	ds_read_b128 v[198:201], v189 offset:4704
	s_waitcnt lgkmcnt(0)
	v_mfma_f32_32x32x16_bf16 v[96:111], v[198:201], v[140:143], v[96:111]
	v_mfma_f32_32x32x16_bf16 v[64:79], v[198:201], v[156:159], v[64:79]
	v_max_f32_e32 v189, v113, v113
	v_max_f32_e32 v191, v112, v112
	v_max_f32_e32 v189, v191, v189
	v_max3_f32 v189, v189, v114, v115
	v_max3_f32 v189, v189, v116, v117
	v_max3_f32 v189, v189, v118, v119
	v_max3_f32 v189, v189, v120, v121
	v_max3_f32 v189, v189, v122, v123
	v_max3_f32 v189, v189, v124, v125
	v_max3_f32 v189, v189, v126, v127
	s_nop 0
	v_max3_f32 v189, v189, v96, v97
	v_max3_f32 v189, v189, v98, v99
	v_max3_f32 v189, v189, v100, v101
	v_max3_f32 v189, v189, v102, v103
	v_max3_f32 v189, v189, v104, v105
	v_max3_f32 v189, v189, v106, v107
	v_max3_f32 v189, v189, v108, v109
	v_max3_f32 v189, v189, v110, v111
	ds_bpermute_b32 v191, v193, v189
	v_add_u32_e32 v239, v190, v196
	ds_read_b128 v[240:243], v239 offset:9216
	ds_read_b128 v[244:247], v239 offset:9248
	s_waitcnt lgkmcnt(2)
	v_max3_f32 v198, v176, v189, v191
	v_sub_f32_e32 v112, v112, v198
	v_exp_f32_e32 v199, v112
	v_sub_f32_e32 v112, v113, v198
	v_exp_f32_e32 v200, v112
	v_sub_f32_e32 v112, v114, v198
	v_exp_f32_e32 v201, v112
	v_sub_f32_e32 v112, v115, v198
	v_exp_f32_e32 v202, v112
	v_sub_f32_e32 v112, v116, v198
	v_exp_f32_e32 v203, v112
	v_sub_f32_e32 v112, v117, v198
	v_exp_f32_e32 v204, v112
	v_sub_f32_e32 v112, v118, v198
	v_sub_f32_e32 v96, v96, v198
	v_exp_f32_e32 v205, v112
	v_sub_f32_e32 v112, v119, v198
	v_exp_f32_e32 v216, v96
	v_sub_f32_e32 v96, v97, v198
	v_exp_f32_e32 v206, v112
	v_sub_f32_e32 v112, v120, v198
	v_exp_f32_e32 v217, v96
	v_sub_f32_e32 v96, v98, v198
	v_exp_f32_e32 v207, v112
	v_sub_f32_e32 v112, v121, v198
	v_exp_f32_e32 v218, v96
	v_sub_f32_e32 v96, v99, v198
	v_exp_f32_e32 v208, v112
	v_sub_f32_e32 v112, v122, v198
	v_exp_f32_e32 v219, v96
	v_sub_f32_e32 v96, v100, v198
	v_exp_f32_e32 v209, v112
	v_sub_f32_e32 v112, v123, v198
	v_exp_f32_e32 v237, v96
	v_sub_f32_e32 v96, v101, v198
	v_exp_f32_e32 v210, v112
	v_sub_f32_e32 v112, v124, v198
	v_exp_f32_e32 v238, v96
	v_sub_f32_e32 v96, v102, v198
	v_exp_f32_e32 v211, v112
	v_sub_f32_e32 v112, v125, v198
	v_exp_f32_e32 v191, v96
	v_sub_f32_e32 v96, v103, v198
	v_exp_f32_e32 v212, v112
	v_sub_f32_e32 v112, v126, v198
	v_exp_f32_e32 v189, v96
	v_sub_f32_e32 v96, v104, v198
	v_exp_f32_e32 v214, v112
	v_sub_f32_e32 v112, v127, v198
	v_exp_f32_e32 v127, v96
	v_sub_f32_e32 v96, v105, v198
	v_sub_f32_e32 v176, v176, v198
	v_exp_f32_e32 v125, v96
	v_sub_f32_e32 v96, v106, v198
	v_exp_f32_e32 v123, v96
	v_sub_f32_e32 v96, v107, v198
	v_exp_f32_e32 v176, v176
	v_exp_f32_e32 v121, v96
	v_sub_f32_e32 v96, v108, v198
	v_exp_f32_e32 v119, v96
	v_sub_f32_e32 v96, v109, v198
	v_exp_f32_e32 v117, v96
	v_sub_f32_e32 v96, v110, v198
	v_exp_f32_e32 v115, v96
	v_sub_f32_e32 v96, v111, v198
	v_mul_f32_e32 v62, v62, v176
	v_mul_f32_e32 v63, v63, v176
	v_mul_f32_e32 v60, v60, v176
	v_mul_f32_e32 v61, v61, v176
	v_mul_f32_e32 v58, v58, v176
	v_mul_f32_e32 v59, v59, v176
	v_mul_f32_e32 v56, v56, v176
	v_mul_f32_e32 v57, v57, v176
	v_mul_f32_e32 v54, v54, v176
	v_mul_f32_e32 v55, v55, v176
	v_mul_f32_e32 v52, v52, v176
	v_mul_f32_e32 v53, v53, v176
	v_mul_f32_e32 v50, v50, v176
	v_mul_f32_e32 v51, v51, v176
	v_mul_f32_e32 v48, v48, v176
	v_mul_f32_e32 v49, v49, v176
	v_cvt_pk_bf16_f32 v108, v199, v200
	v_cvt_pk_bf16_f32 v109, v201, v202
	v_cvt_pk_bf16_f32 v110, v203, v204
	v_cvt_pk_bf16_f32 v111, v205, v206
	v_exp_f32_e32 v215, v112
	v_cvt_pk_bf16_f32 v100, v207, v208
	s_waitcnt lgkmcnt(1)
	v_mfma_f32_32x32x16_bf16 v[48:63], v[240:243], v[108:111], v[48:63]
	v_cvt_pk_bf16_f32 v101, v209, v210
	v_cvt_pk_bf16_f32 v102, v211, v212
	v_cvt_pk_bf16_f32 v103, v214, v215
	ds_read_b128 v[240:243], v239 offset:9280
	v_cvt_pk_bf16_f32 v104, v216, v217
	v_cvt_pk_bf16_f32 v105, v218, v219
	v_cvt_pk_bf16_f32 v106, v237, v238
	s_waitcnt lgkmcnt(1)
	v_mfma_f32_32x32x16_bf16 v[48:63], v[244:247], v[100:103], v[48:63]
	v_cvt_pk_bf16_f32 v107, v191, v189
	v_exp_f32_e32 v113, v96
	v_cvt_pk_bf16_f32 v96, v127, v125
	v_cvt_pk_bf16_f32 v97, v123, v121
	v_cvt_pk_bf16_f32 v98, v119, v117
	v_cvt_pk_bf16_f32 v99, v115, v113
	v_mul_f32_e32 v46, v46, v176
	v_mul_f32_e32 v47, v47, v176
	s_waitcnt lgkmcnt(0)
	v_mfma_f32_32x32x16_bf16 v[48:63], v[240:243], v[104:107], v[48:63]
	ds_read_b128 v[240:243], v239 offset:9312
	v_mul_f32_e64 v44, v44, v176
	v_mul_f32_e64 v45, v45, v176
	v_mul_f32_e64 v42, v42, v176
	v_mul_f32_e64 v43, v43, v176
	v_mul_f32_e32 v40, v40, v176
	v_mul_f32_e32 v41, v41, v176
	v_mul_f32_e32 v38, v38, v176
	v_mul_f32_e32 v39, v39, v176
	v_mul_f32_e32 v36, v36, v176
	v_mul_f32_e32 v37, v37, v176
	v_mul_f32_e32 v34, v34, v176
	v_mul_f32_e32 v35, v35, v176
	s_waitcnt lgkmcnt(0)
	v_mfma_f32_32x32x16_bf16 v[48:63], v[240:243], v[96:99], v[48:63]
	ds_read_b128 v[240:243], v239 offset:13824
	v_mul_f32_e64 v32, v32, v176
	v_mul_f32_e64 v33, v33, v176
	s_waitcnt lgkmcnt(0)
	s_nop 0
	v_mfma_f32_32x32x16_bf16 v[32:47], v[240:243], v[108:111], v[32:47]
	ds_read_b128 v[108:111], v239 offset:13856
	s_waitcnt lgkmcnt(0)
	v_mfma_f32_32x32x16_bf16 v[32:47], v[108:111], v[100:103], v[32:47]
	ds_read_b128 v[100:103], v239 offset:13888
	s_waitcnt lgkmcnt(0)
	v_mfma_f32_32x32x16_bf16 v[32:47], v[100:103], v[104:107], v[32:47]
	ds_read_b128 v[100:103], v239 offset:13920
	s_waitcnt lgkmcnt(0)
	v_mfma_f32_32x32x16_bf16 v[32:47], v[100:103], v[96:99], v[32:47]
	v_max_f32_e32 v96, v81, v81
	v_max_f32_e32 v97, v80, v80
	v_max_f32_e32 v96, v97, v96
	v_max3_f32 v96, v96, v82, v83
	v_max3_f32 v96, v96, v84, v85
	v_max3_f32 v96, v96, v86, v87
	v_max3_f32 v96, v96, v88, v89
	v_max3_f32 v96, v96, v90, v91
	v_max3_f32 v96, v96, v92, v93
	v_max3_f32 v96, v96, v94, v95
	v_max3_f32 v96, v96, v64, v65
	v_max3_f32 v96, v96, v66, v67
	v_max3_f32 v96, v96, v68, v69
	v_max3_f32 v96, v96, v70, v71
	v_max3_f32 v96, v96, v72, v73
	v_max3_f32 v96, v96, v74, v75
	v_max3_f32 v96, v96, v76, v77
	v_max3_f32 v96, v96, v78, v79
	ds_bpermute_b32 v97, v193, v96
	s_waitcnt lgkmcnt(0)
	v_max3_f32 v96, v188, v96, v97
	v_sub_f32_e32 v80, v80, v96
	v_exp_f32_e32 v97, v80
	v_sub_f32_e32 v80, v81, v96
	v_exp_f32_e32 v81, v80
	v_sub_f32_e32 v80, v82, v96
	v_exp_f32_e32 v82, v80
	v_sub_f32_e32 v80, v83, v96
	v_exp_f32_e32 v83, v80
	v_sub_f32_e32 v80, v84, v96
	v_exp_f32_e32 v84, v80
	v_sub_f32_e32 v80, v85, v96
	v_sub_f32_e32 v64, v64, v96
	v_exp_f32_e32 v85, v80
	v_sub_f32_e32 v80, v86, v96
	v_exp_f32_e32 v98, v64
	v_sub_f32_e32 v64, v65, v96
	v_exp_f32_e32 v86, v80
	v_sub_f32_e32 v80, v87, v96
	v_exp_f32_e32 v99, v64
	v_sub_f32_e32 v64, v66, v96
	v_exp_f32_e32 v87, v80
	v_sub_f32_e32 v80, v88, v96
	v_exp_f32_e32 v100, v64
	v_sub_f32_e32 v64, v67, v96
	v_exp_f32_e32 v88, v80
	v_sub_f32_e32 v80, v89, v96
	v_exp_f32_e32 v101, v64
	v_sub_f32_e32 v64, v68, v96
	v_exp_f32_e32 v89, v80
	v_sub_f32_e32 v80, v90, v96
	v_exp_f32_e32 v102, v64
	v_sub_f32_e32 v64, v69, v96
	v_exp_f32_e32 v90, v80
	v_sub_f32_e32 v80, v91, v96
	v_exp_f32_e32 v103, v64
	v_sub_f32_e32 v64, v70, v96
	v_exp_f32_e32 v91, v80
	v_sub_f32_e32 v80, v92, v96
	v_exp_f32_e32 v190, v64
	v_sub_f32_e32 v64, v71, v96
	v_sub_f32_e32 v104, v188, v96
	v_exp_f32_e32 v92, v80
	v_sub_f32_e32 v80, v93, v96
	v_exp_f32_e32 v188, v64
	v_sub_f32_e32 v64, v72, v96
	v_exp_f32_e32 v93, v80
	v_sub_f32_e32 v80, v94, v96
	v_exp_f32_e32 v126, v64
	v_sub_f32_e32 v64, v73, v96
	v_exp_f32_e32 v94, v80
	v_sub_f32_e32 v80, v95, v96
	v_exp_f32_e32 v124, v64
	v_sub_f32_e32 v64, v74, v96
	v_exp_f32_e32 v95, v80
	v_exp_f32_e32 v122, v64
	v_sub_f32_e32 v64, v75, v96
	v_exp_f32_e32 v80, v104
	v_exp_f32_e32 v120, v64
	v_sub_f32_e32 v64, v76, v96
	ds_read_b128 v[104:107], v239 offset:9216
	ds_read_b128 v[108:111], v239 offset:9248
	v_exp_f32_e32 v118, v64
	v_sub_f32_e32 v64, v77, v96
	v_exp_f32_e32 v116, v64
	v_sub_f32_e32 v64, v78, v96
	v_exp_f32_e32 v114, v64
	v_sub_f32_e32 v64, v79, v96
	v_mul_f32_e32 v30, v30, v80
	v_mul_f32_e32 v31, v31, v80
	v_mul_f32_e32 v28, v28, v80
	v_mul_f32_e32 v29, v29, v80
	v_mul_f32_e32 v26, v26, v80
	v_mul_f32_e32 v27, v27, v80
	v_mul_f32_e32 v24, v24, v80
	v_mul_f32_e32 v25, v25, v80
	v_mul_f32_e32 v22, v22, v80
	v_mul_f32_e32 v23, v23, v80
	v_mul_f32_e32 v20, v20, v80
	v_mul_f32_e32 v21, v21, v80
	v_mul_f32_e32 v18, v18, v80
	v_mul_f32_e32 v19, v19, v80
	v_mul_f32_e32 v16, v16, v80
	v_mul_f32_e32 v17, v17, v80
	v_cvt_pk_bf16_f32 v76, v97, v81
	v_cvt_pk_bf16_f32 v77, v82, v83
	v_cvt_pk_bf16_f32 v78, v84, v85
	v_cvt_pk_bf16_f32 v79, v86, v87
	v_cvt_pk_bf16_f32 v68, v88, v89
	v_cvt_pk_bf16_f32 v69, v90, v91
	s_waitcnt lgkmcnt(1)
	v_mfma_f32_32x32x16_bf16 v[16:31], v[104:107], v[76:79], v[16:31]
	v_cvt_pk_bf16_f32 v70, v92, v93
	v_cvt_pk_bf16_f32 v71, v94, v95
	ds_read_b128 v[104:107], v239 offset:9280
	v_cvt_pk_bf16_f32 v72, v98, v99
	v_cvt_pk_bf16_f32 v73, v100, v101
	v_cvt_pk_bf16_f32 v74, v102, v103
	v_cvt_pk_bf16_f32 v75, v190, v188
	s_waitcnt lgkmcnt(1)
	v_mfma_f32_32x32x16_bf16 v[16:31], v[108:111], v[68:71], v[16:31]
	v_exp_f32_e32 v112, v64
	v_cvt_pk_bf16_f32 v64, v126, v124
	v_cvt_pk_bf16_f32 v65, v122, v120
	v_cvt_pk_bf16_f32 v66, v118, v116
	v_cvt_pk_bf16_f32 v67, v114, v112
	v_mul_f32_e32 v14, v14, v80
	v_mul_f32_e32 v15, v15, v80
	v_mul_f32_e32 v12, v12, v80
	v_mul_f32_e32 v13, v13, v80
	s_waitcnt lgkmcnt(0)
	v_mfma_f32_32x32x16_bf16 v[16:31], v[104:107], v[72:75], v[16:31]
	ds_read_b128 v[104:107], v239 offset:9312
	v_mul_f32_e64 v10, v10, v80
	v_mul_f32_e64 v11, v11, v80
	v_mul_f32_e64 v8, v8, v80
	v_mul_f32_e64 v9, v9, v80
	v_mul_f32_e32 v6, v6, v80
	v_mul_f32_e32 v7, v7, v80
	v_mul_f32_e32 v4, v4, v80
	v_mul_f32_e32 v5, v5, v80
	v_mul_f32_e32 v2, v2, v80
	v_mul_f32_e32 v3, v3, v80
	v_mul_f32_e32 v0, v0, v80
	v_mul_f32_e32 v1, v1, v80
	s_waitcnt lgkmcnt(0)
	v_mfma_f32_32x32x16_bf16 v[16:31], v[104:107], v[64:67], v[16:31]
	ds_read_b128 v[104:107], v239 offset:13824
	s_waitcnt lgkmcnt(0)
	v_mfma_f32_32x32x16_bf16 v[0:15], v[104:107], v[76:79], v[0:15]
	ds_read_b128 v[76:79], v239 offset:13856
	s_waitcnt lgkmcnt(0)
	v_mfma_f32_32x32x16_bf16 v[0:15], v[76:79], v[68:71], v[0:15]
	ds_read_b128 v[68:71], v239 offset:13888
	s_waitcnt lgkmcnt(0)
	v_mfma_f32_32x32x16_bf16 v[0:15], v[68:71], v[72:75], v[0:15]
	ds_read_b128 v[68:71], v239 offset:13920
	s_waitcnt lgkmcnt(0)
	v_mfma_f32_32x32x16_bf16 v[0:15], v[68:71], v[64:67], v[0:15]
	s_andn2_b64 vcc, exec, s[6:7]
	s_cbranch_vccnz .LBB0_345
	s_bitcmp1_b32 s11, 0
	s_cselect_b32 s6, 0x4800, 0
	v_add_u32_e32 v64, s6, v194
	s_waitcnt vmcnt(3)
	ds_write_b128 v64, v[160:163]
	s_waitcnt vmcnt(2)
	ds_write_b128 v64, v[164:167] offset:9216
	s_waitcnt vmcnt(1)
	ds_write_b128 v64, v[168:171] offset:4608
	s_waitcnt vmcnt(0)
	ds_write_b128 v64, v[172:175] offset:13824
	s_branch .LBB0_345
.LBB0_350:
	ds_bpermute_b32 v64, v193, v187
	v_lshlrev_b32_e32 v176, 3, v192
	s_waitcnt lgkmcnt(0)
	v_add_f32_e32 v66, v187, v64
	v_div_scale_f32 v67, s[6:7], v66, v66, 1.0
	v_rcp_f32_e32 v68, v67
	v_div_scale_f32 v69, vcc, 1.0, v66, 1.0
	v_lshl_add_u64 v[64:65], s[78:79], 0, v[182:183]
	v_fma_f32 v70, -v67, v68, 1.0
	v_fmac_f32_e32 v68, v70, v68
	v_mul_f32_e32 v70, v69, v68
	v_fma_f32 v71, -v67, v70, v69
	v_fmac_f32_e32 v70, v71, v68
	v_fma_f32 v67, -v67, v70, v69
	v_div_fmas_f32 v67, v67, v68, v70
	v_div_fixup_f32 v66, v67, v66, 1.0
	v_mul_f32_e32 v34, v34, v66
	v_mul_f32_e32 v35, v35, v66
	v_mul_f32_e32 v32, v32, v66
	v_mul_f32_e32 v33, v33, v66
	v_lshl_add_u64 v[64:65], v[64:65], 0, s[4:5]
	v_cvt_pk_bf16_f32 v32, v32, v33
	v_cvt_pk_bf16_f32 v33, v34, v35
	ds_bpermute_b32 v34, v193, v186
	v_mul_f32_e32 v36, v36, v66
	v_mul_f32_e32 v37, v37, v66
	v_lshl_add_u64 v[64:65], v[64:65], 0, v[176:177]
	global_store_dwordx2 v[64:65], v[32:33], off offset:64
	v_cvt_pk_bf16_f32 v32, v36, v37
	s_waitcnt lgkmcnt(0)
	v_add_f32_e32 v34, v186, v34
	v_div_scale_f32 v35, s[6:7], v34, v34, 1.0
	v_rcp_f32_e32 v36, v35
	v_mul_f32_e32 v38, v38, v66
	v_mul_f32_e32 v39, v39, v66
	v_mul_f32_e32 v42, v42, v66
	v_mul_f32_e32 v43, v43, v66
	v_cvt_pk_bf16_f32 v33, v38, v39
	v_fma_f32 v37, -v35, v36, 1.0
	v_fmac_f32_e32 v36, v37, v36
	v_div_scale_f32 v37, vcc, 1.0, v34, 1.0
	v_mul_f32_e32 v38, v37, v36
	v_fma_f32 v39, -v35, v38, v37
	v_mul_f32_e32 v40, v40, v66
	v_mul_f32_e32 v41, v41, v66
	v_fmac_f32_e32 v38, v39, v36
	v_mul_f32_e32 v46, v46, v66
	v_mul_f32_e32 v47, v47, v66
	v_mul_f32_e32 v44, v44, v66
	v_mul_f32_e32 v45, v45, v66
	global_store_dwordx2 v[64:65], v[32:33], off offset:80
	v_cvt_pk_bf16_f32 v32, v40, v41
	v_cvt_pk_bf16_f32 v33, v42, v43
	v_fma_f32 v35, -v35, v38, v37
	global_store_dwordx2 v[64:65], v[32:33], off offset:96
	v_cvt_pk_bf16_f32 v32, v44, v45
	v_cvt_pk_bf16_f32 v33, v46, v47
	v_div_fmas_f32 v35, v35, v36, v38
	global_store_dwordx2 v[64:65], v[32:33], off offset:112
	v_lshl_add_u64 v[32:33], s[78:79], 0, v[180:181]
	v_div_fixup_f32 v34, v35, v34, 1.0
	v_mul_f32_e32 v50, v50, v66
	v_mul_f32_e32 v51, v51, v66
	v_mul_f32_e32 v48, v48, v66
	v_mul_f32_e32 v49, v49, v66
	v_mul_f32_e32 v18, v18, v34
	v_mul_f32_e32 v19, v19, v34
	v_mul_f32_e32 v16, v16, v34
	v_mul_f32_e32 v17, v17, v34
	v_mul_f32_e32 v2, v2, v34
	v_mul_f32_e32 v3, v3, v34
	v_mul_f32_e32 v0, v0, v34
	v_mul_f32_e32 v1, v1, v34
	v_lshl_add_u64 v[32:33], v[32:33], 0, s[4:5]
	v_mul_f32_e32 v54, v54, v66
	v_mul_f32_e32 v55, v55, v66
	v_mul_f32_e32 v52, v52, v66
	v_mul_f32_e32 v53, v53, v66
	v_cvt_pk_bf16_f32 v48, v48, v49
	v_cvt_pk_bf16_f32 v49, v50, v51
	v_mul_f32_e32 v22, v22, v34
	v_mul_f32_e32 v23, v23, v34
	v_mul_f32_e32 v20, v20, v34
	v_mul_f32_e32 v21, v21, v34
	v_mul_f32_e32 v6, v6, v34
	v_mul_f32_e32 v7, v7, v34
	v_mul_f32_e32 v4, v4, v34
	v_mul_f32_e32 v5, v5, v34
	v_lshl_add_u64 v[32:33], v[32:33], 0, v[176:177]
	v_cvt_pk_bf16_f32 v16, v16, v17
	v_cvt_pk_bf16_f32 v17, v18, v19
	v_cvt_pk_bf16_f32 v0, v0, v1
	v_cvt_pk_bf16_f32 v1, v2, v3
	v_mul_f32_e32 v58, v58, v66
	v_mul_f32_e32 v59, v59, v66
	v_mul_f32_e32 v56, v56, v66
	v_mul_f32_e32 v57, v57, v66
	global_store_dwordx2 v[64:65], v[48:49], off
	v_cvt_pk_bf16_f32 v48, v52, v53
	v_cvt_pk_bf16_f32 v49, v54, v55
	v_mul_f32_e32 v26, v26, v34
	v_mul_f32_e32 v27, v27, v34
	v_mul_f32_e32 v24, v24, v34
	v_mul_f32_e32 v25, v25, v34
	v_mul_f32_e32 v10, v10, v34
	v_mul_f32_e32 v11, v11, v34
	v_mul_f32_e32 v8, v8, v34
	v_mul_f32_e32 v9, v9, v34
	global_store_dwordx2 v[32:33], v[16:17], off
	v_cvt_pk_bf16_f32 v16, v20, v21
	v_cvt_pk_bf16_f32 v17, v22, v23
	global_store_dwordx2 v[32:33], v[0:1], off offset:64
	v_cvt_pk_bf16_f32 v0, v4, v5
	v_cvt_pk_bf16_f32 v1, v6, v7
	v_mul_f32_e32 v62, v62, v66
	v_mul_f32_e32 v63, v63, v66
	v_mul_f32_e32 v60, v60, v66
	v_mul_f32_e32 v61, v61, v66
	global_store_dwordx2 v[64:65], v[48:49], off offset:16
	v_cvt_pk_bf16_f32 v48, v56, v57
	v_cvt_pk_bf16_f32 v49, v58, v59
	v_mul_f32_e32 v30, v30, v34
	v_mul_f32_e32 v31, v31, v34
	v_mul_f32_e32 v28, v28, v34
	v_mul_f32_e32 v29, v29, v34
	v_mul_f32_e32 v14, v14, v34
	v_mul_f32_e32 v15, v15, v34
	v_mul_f32_e32 v12, v12, v34
	v_mul_f32_e32 v13, v13, v34
	global_store_dwordx2 v[32:33], v[16:17], off offset:16
	v_cvt_pk_bf16_f32 v16, v24, v25
	v_cvt_pk_bf16_f32 v17, v26, v27
	global_store_dwordx2 v[32:33], v[0:1], off offset:80
	v_cvt_pk_bf16_f32 v0, v8, v9
	v_cvt_pk_bf16_f32 v1, v10, v11
	global_store_dwordx2 v[64:65], v[48:49], off offset:32
	v_cvt_pk_bf16_f32 v48, v60, v61
	v_cvt_pk_bf16_f32 v49, v62, v63
	global_store_dwordx2 v[32:33], v[16:17], off offset:32
	v_cvt_pk_bf16_f32 v16, v28, v29
	v_cvt_pk_bf16_f32 v17, v30, v31
	global_store_dwordx2 v[32:33], v[0:1], off offset:96
	v_cvt_pk_bf16_f32 v0, v12, v13
	v_cvt_pk_bf16_f32 v1, v14, v15
	global_store_dwordx2 v[64:65], v[48:49], off offset:48
	global_store_dwordx2 v[32:33], v[16:17], off offset:48
	global_store_dwordx2 v[32:33], v[0:1], off offset:112
	s_mov_b64 s[4:5], 0

.LBB0_358:
	s_bitcmp1_b32 s10, 0
	s_cselect_b32 s10, 0x4800, 0
	v_add_u32_e32 v249, s10, v245
	v_add_u32_e32 v192, v249, v240
	ds_read_b128 v[64:67], v192
	ds_read_b128 v[68:71], v192 offset:32
	s_waitcnt lgkmcnt(1)
	v_mfma_f32_32x32x16_bf16 v[112:127], v[64:67], v[128:131], 0
	ds_read_b128 v[188:191], v192 offset:4640
	v_mfma_f32_32x32x16_bf16 v[80:95], v[64:67], v[144:147], 0
	ds_read_b128 v[64:67], v192 offset:64
	s_waitcnt lgkmcnt(2)
	v_mfma_f32_32x32x16_bf16 v[112:127], v[68:71], v[132:135], v[112:127]
	v_mfma_f32_32x32x16_bf16 v[80:95], v[68:71], v[148:151], v[80:95]
	s_waitcnt lgkmcnt(0)
	v_mfma_f32_32x32x16_bf16 v[112:127], v[64:67], v[136:139], v[112:127]
	v_mfma_f32_32x32x16_bf16 v[80:95], v[64:67], v[152:155], v[80:95]
	ds_read_b128 v[64:67], v192 offset:96
	s_waitcnt lgkmcnt(0)
	v_mfma_f32_32x32x16_bf16 v[112:127], v[64:67], v[140:143], v[112:127]
	v_mfma_f32_32x32x16_bf16 v[80:95], v[64:67], v[156:159], v[80:95]
	ds_read_b128 v[64:67], v192 offset:4608
	s_waitcnt lgkmcnt(0)
	v_mfma_f32_32x32x16_bf16 v[96:111], v[64:67], v[128:131], 0
	v_mfma_f32_32x32x16_bf16 v[64:79], v[64:67], v[144:147], 0
	v_mfma_f32_32x32x16_bf16 v[96:111], v[188:191], v[132:135], v[96:111]
	v_mfma_f32_32x32x16_bf16 v[64:79], v[188:191], v[148:151], v[64:79]
	ds_read_b128 v[188:191], v192 offset:4672
	s_waitcnt lgkmcnt(0)
	v_mfma_f32_32x32x16_bf16 v[96:111], v[188:191], v[136:139], v[96:111]
	v_mfma_f32_32x32x16_bf16 v[64:79], v[188:191], v[152:155], v[64:79]
	ds_read_b128 v[188:191], v192 offset:4704
	s_waitcnt lgkmcnt(0)
	v_mfma_f32_32x32x16_bf16 v[96:111], v[188:191], v[140:143], v[96:111]
	v_mfma_f32_32x32x16_bf16 v[64:79], v[188:191], v[156:159], v[64:79]
	v_cvt_f32_i32_e32 v212, v247
	s_add_i32 s24, s20, 63
	v_add_u32_e32 v248, s20, v246
	v_cmp_ge_i32_e32 vcc, s24, v181
	s_and_saveexec_b64 s[10:11], vcc
	s_xor_b64 s[10:11], exec, s[10:11]
	s_cbranch_execz .LBB0_364
	v_cmp_le_i32_e32 vcc, s20, v241
	v_mul_f32_e64 v252, -v238, v212
	s_and_saveexec_b64 s[12:13], vcc
	s_xor_b64 s[12:13], exec, s[12:13]
	s_cbranch_execz .LBB0_361
	v_mul_f32_e32 v188, v237, v212
	v_min_f32_e32 v188, v188, v252
	v_exp_f32_e32 v188, v188
	s_mov_b32 s48, -1.0
	s_mov_b32 s49, -2.0
	v_add_f32_e32 v190, s48, v212
	v_add_f32_e32 v191, s49, v212
	v_cmp_ne_u32_e32 vcc, 0, v248
	v_mul_f32_e32 v192, v237, v191
	v_mul_f32_e64 v193, v191, -v238
	v_cndmask_b32_e32 v188, 2.0, v188, vcc
	v_mul_f32_e32 v189, v237, v190
	v_mul_f32_e32 v188, v188, v112
	v_mul_f32_e64 v112, v190, -v238
	v_min_f32_e32 v192, v192, v193
	v_exp_f32_e32 v192, v192
	v_min_f32_e32 v112, v189, v112
	v_exp_f32_e32 v112, v112
	v_cmp_neq_f32_e32 vcc, 0, v191
	s_mov_b32 s48, 0xc0400000
	s_mov_b32 s49, -4.0
	v_cndmask_b32_e32 v191, 2.0, v192, vcc
	v_cmp_neq_f32_e32 vcc, 0, v190
	s_nop 1
	v_cndmask_b32_e32 v190, 2.0, v112, vcc
	v_mov_b32_e32 v112, v113
	v_mov_b32_e32 v113, v114
	v_mul_f32_e32 v112, v190, v112
	v_mul_f32_e32 v113, v191, v113
	v_add_f32_e32 v190, s48, v212
	v_add_f32_e32 v191, s49, v212
	v_mul_f32_e32 v192, v237, v191
	v_mul_f32_e64 v193, v191, -v238
	v_mul_f32_e32 v114, v237, v190
	v_mul_f32_e64 v189, v190, -v238
	v_min_f32_e32 v192, v192, v193
	v_exp_f32_e32 v192, v192
	v_min_f32_e32 v114, v114, v189
	v_exp_f32_e32 v114, v114
	v_cmp_neq_f32_e32 vcc, 0, v191
	s_mov_b32 s48, 0xc0a00000
	s_mov_b32 s49, 0xc0c00000
	v_cndmask_b32_e32 v191, 2.0, v192, vcc
	v_cmp_neq_f32_e32 vcc, 0, v190
	v_mov_b32_e32 v214, v113
	s_nop 0
	v_cndmask_b32_e32 v190, 2.0, v114, vcc
	v_mov_b32_e32 v114, v115
	v_mov_b32_e32 v115, v116
	v_mul_f32_e32 v114, v190, v114
	v_mul_f32_e32 v115, v191, v115
	v_add_f32_e32 v190, s48, v212
	v_add_f32_e32 v191, s49, v212
	v_mul_f32_e32 v192, v237, v191
	v_mul_f32_e64 v193, v191, -v238
	v_mul_f32_e32 v116, v237, v190
	v_mul_f32_e64 v189, v190, -v238
	v_min_f32_e32 v192, v192, v193
	v_exp_f32_e32 v192, v192
	v_min_f32_e32 v116, v116, v189
	v_exp_f32_e32 v116, v116
	v_cmp_neq_f32_e32 vcc, 0, v191
	s_mov_b32 s48, 0xc0e00000
	s_mov_b32 s49, 0xc1800000
	v_cndmask_b32_e32 v191, 2.0, v192, vcc
	v_cmp_neq_f32_e32 vcc, 0, v190
	v_mov_b32_e32 v210, v115
	v_mov_b32_e32 v215, v114
	v_cndmask_b32_e32 v190, 2.0, v116, vcc
	v_mov_b32_e32 v116, v117
	v_mov_b32_e32 v117, v118
	v_mul_f32_e32 v116, v190, v116
	v_mul_f32_e32 v117, v191, v117
	v_add_f32_e32 v190, s48, v212
	v_add_f32_e32 v191, s49, v212
	v_mul_f32_e32 v192, v237, v191
	v_mul_f32_e64 v193, v191, -v238
	v_mul_f32_e32 v118, v237, v190
	v_mul_f32_e64 v189, v190, -v238
	v_min_f32_e32 v192, v192, v193
	v_exp_f32_e32 v192, v192
	v_min_f32_e32 v118, v118, v189
	v_exp_f32_e32 v118, v118
	v_cmp_neq_f32_e32 vcc, 0, v191
	s_mov_b32 s48, 0xc1880000
	s_mov_b32 s49, 0xc1900000
	v_cndmask_b32_e32 v191, 2.0, v192, vcc
	v_cmp_neq_f32_e32 vcc, 0, v190
	v_mov_b32_e32 v206, v117
	v_mov_b32_e32 v211, v116
	v_cndmask_b32_e32 v190, 2.0, v118, vcc
	v_mov_b32_e32 v118, v119
	v_mov_b32_e32 v119, v120
	v_mul_f32_e32 v118, v190, v118
	v_mul_f32_e32 v119, v191, v119
	v_add_f32_e32 v190, s48, v212
	v_add_f32_e32 v191, s49, v212
	v_mul_f32_e32 v192, v237, v191
	v_mul_f32_e64 v193, v191, -v238
	v_mul_f32_e32 v120, v237, v190
	v_mul_f32_e64 v189, v190, -v238
	v_min_f32_e32 v192, v192, v193
	v_exp_f32_e32 v192, v192
	v_min_f32_e32 v120, v120, v189
	v_exp_f32_e32 v120, v120
	v_cmp_neq_f32_e32 vcc, 0, v191
	s_mov_b32 s48, 0xc1980000
	s_mov_b32 s49, 0xc1a00000
	v_cndmask_b32_e32 v191, 2.0, v192, vcc
	v_cmp_neq_f32_e32 vcc, 0, v190
	v_mov_b32_e32 v204, v119
	v_mov_b32_e32 v207, v118
	v_cndmask_b32_e32 v190, 2.0, v120, vcc
	v_mov_b32_e32 v120, v121
	v_mov_b32_e32 v121, v122
	v_mul_f32_e32 v120, v190, v120
	v_mul_f32_e32 v121, v191, v121
	v_add_f32_e32 v190, s48, v212
	v_add_f32_e32 v191, s49, v212
	v_mul_f32_e32 v192, v237, v191
	v_mul_f32_e64 v193, v191, -v238
	v_mul_f32_e32 v122, v237, v190
	v_mul_f32_e64 v189, v190, -v238
	v_min_f32_e32 v192, v192, v193
	v_exp_f32_e32 v192, v192
	v_min_f32_e32 v122, v122, v189
	v_exp_f32_e32 v122, v122
	v_cmp_neq_f32_e32 vcc, 0, v191
	s_mov_b32 s48, 0xc1a80000
	s_mov_b32 s49, 0xc1b00000
	v_cndmask_b32_e32 v191, 2.0, v192, vcc
	v_cmp_neq_f32_e32 vcc, 0, v190
	v_mov_b32_e32 v200, v121
	v_mov_b32_e32 v205, v120
	v_cndmask_b32_e32 v190, 2.0, v122, vcc
	v_mov_b32_e32 v122, v123
	v_mov_b32_e32 v123, v124
	v_mul_f32_e32 v122, v190, v122
	v_mul_f32_e32 v123, v191, v123
	v_add_f32_e32 v190, s48, v212
	v_add_f32_e32 v191, s49, v212
	v_mul_f32_e32 v192, v237, v191
	v_mul_f32_e64 v193, v191, -v238
	v_mul_f32_e32 v124, v237, v190
	v_mul_f32_e64 v189, v190, -v238
	v_min_f32_e32 v192, v192, v193
	v_exp_f32_e32 v192, v192
	v_min_f32_e32 v124, v124, v189
	v_exp_f32_e32 v124, v124
	v_cmp_neq_f32_e32 vcc, 0, v191
	v_add_f32_e32 v189, 0xc1b80000, v212
	s_mov_b32 s48, 0xc2000000
	v_cndmask_b32_e32 v191, 2.0, v192, vcc
	v_cmp_neq_f32_e32 vcc, 0, v190
	v_mul_f32_e64 v192, v189, -v238
	s_mov_b32 s49, 0xc2040000
	v_cndmask_b32_e32 v190, 2.0, v124, vcc
	v_mov_b32_e32 v124, v125
	v_mul_f32_e32 v125, v237, v189
	v_min_f32_e32 v125, v125, v192
	v_exp_f32_e32 v192, v125
	v_cmp_neq_f32_e32 vcc, 0, v189
	v_mov_b32_e32 v125, v126
	v_mul_f32_e32 v124, v190, v124
	v_mul_f32_e32 v125, v191, v125
	v_cndmask_b32_e32 v126, 2.0, v192, vcc
	v_mul_f32_e32 v191, v126, v127
	v_add_f32_e32 v126, s48, v212
	v_add_f32_e32 v127, s49, v212
	v_mul_f32_e32 v192, v237, v127
	v_mul_f32_e64 v193, v127, -v238
	v_mul_f32_e32 v189, v237, v126
	v_mul_f32_e64 v190, v126, -v238
	v_min_f32_e32 v192, v192, v193
	v_exp_f32_e32 v192, v192
	v_min_f32_e32 v189, v189, v190
	v_exp_f32_e32 v189, v189
	v_cmp_neq_f32_e32 vcc, 0, v127
	s_mov_b32 s48, 0xc2080000
	s_mov_b32 s49, 0xc20c0000
	v_cndmask_b32_e32 v127, 2.0, v192, vcc
	v_cmp_neq_f32_e32 vcc, 0, v126
	v_mov_b32_e32 v201, v122
	s_nop 0
	v_cndmask_b32_e32 v126, 2.0, v189, vcc
	v_mul_f32_e32 v192, v126, v96
	v_mul_f32_e32 v193, v127, v97
	v_add_f32_e32 v126, s48, v212
	v_add_f32_e32 v127, s49, v212
	v_mul_f32_e32 v194, v237, v127
	v_mul_f32_e64 v195, v127, -v238
	v_mul_f32_e32 v189, v237, v126
	v_mul_f32_e64 v190, v126, -v238
	v_min_f32_e32 v194, v194, v195
	v_exp_f32_e32 v194, v194
	v_min_f32_e32 v189, v189, v190
	v_exp_f32_e32 v189, v189
	v_cmp_neq_f32_e32 vcc, 0, v127
	s_mov_b32 s48, 0xc2100000
	s_mov_b32 s49, 0xc2140000
	v_cndmask_b32_e32 v127, 2.0, v194, vcc
	v_cmp_neq_f32_e32 vcc, 0, v126
	s_nop 1
	v_cndmask_b32_e32 v126, 2.0, v189, vcc
	v_mul_f32_e32 v194, v126, v98
	v_mul_f32_e32 v195, v127, v99
	v_add_f32_e32 v126, s48, v212
	v_add_f32_e32 v127, s49, v212
	v_mul_f32_e32 v196, v237, v127
	v_mul_f32_e64 v197, v127, -v238
	v_mul_f32_e32 v189, v237, v126
	v_mul_f32_e64 v190, v126, -v238
	v_min_f32_e32 v196, v196, v197
	v_exp_f32_e32 v196, v196
	v_min_f32_e32 v189, v189, v190
	v_exp_f32_e32 v189, v189
	v_cmp_neq_f32_e32 vcc, 0, v127
	s_mov_b32 s48, 0xc2180000
	s_mov_b32 s49, 0xc21c0000
	v_cndmask_b32_e32 v127, 2.0, v196, vcc
	v_cmp_neq_f32_e32 vcc, 0, v126
	s_nop 1
	v_cndmask_b32_e32 v126, 2.0, v189, vcc
	v_mul_f32_e32 v196, v126, v100
	v_mul_f32_e32 v197, v127, v101
	v_add_f32_e32 v126, s48, v212
	v_add_f32_e32 v127, s49, v212
	v_mul_f32_e32 v198, v237, v127
	v_mul_f32_e64 v199, v127, -v238
	v_mul_f32_e32 v189, v237, v126
	v_mul_f32_e64 v190, v126, -v238
	v_min_f32_e32 v198, v198, v199
	v_exp_f32_e32 v198, v198
	v_min_f32_e32 v189, v189, v190
	v_exp_f32_e32 v189, v189
	v_cmp_neq_f32_e32 vcc, 0, v127
	s_mov_b32 s48, 0xc2400000
	s_mov_b32 s49, 0xc2440000
	v_cndmask_b32_e32 v127, 2.0, v198, vcc
	v_cmp_neq_f32_e32 vcc, 0, v126
	s_nop 1
	v_cndmask_b32_e32 v126, 2.0, v189, vcc
	v_mul_f32_e32 v202, v126, v102
	v_mul_f32_e32 v203, v127, v103
	v_add_f32_e32 v126, s48, v212
	v_add_f32_e32 v127, s49, v212
	v_mul_f32_e32 v198, v237, v127
	v_mul_f32_e64 v199, v127, -v238
	v_mul_f32_e32 v189, v237, v126
	v_mul_f32_e64 v190, v126, -v238
	v_min_f32_e32 v198, v198, v199
	v_exp_f32_e32 v198, v198
	v_min_f32_e32 v189, v189, v190
	v_exp_f32_e32 v189, v189
	v_cmp_neq_f32_e32 vcc, 0, v127
	s_mov_b32 s48, 0xc2480000
	s_mov_b32 s49, 0xc24c0000
	v_cndmask_b32_e32 v127, 2.0, v198, vcc
	v_cmp_neq_f32_e32 vcc, 0, v126
	s_nop 1
	v_cndmask_b32_e32 v126, 2.0, v189, vcc
	v_mul_f32_e32 v208, v126, v104
	v_mul_f32_e32 v209, v127, v105
	v_add_f32_e32 v126, s48, v212
	v_add_f32_e32 v127, s49, v212
	v_mul_f32_e32 v198, v237, v127
	v_mul_f32_e64 v199, v127, -v238
	v_mul_f32_e32 v189, v237, v126
	v_mul_f32_e64 v190, v126, -v238
	v_min_f32_e32 v198, v198, v199
	v_exp_f32_e32 v198, v198
	v_min_f32_e32 v189, v189, v190
	v_exp_f32_e32 v189, v189
	v_cmp_neq_f32_e32 vcc, 0, v127
	s_mov_b32 s48, 0xc2500000
	s_mov_b32 s49, 0xc2540000
	v_cndmask_b32_e32 v127, 2.0, v198, vcc
	v_cmp_neq_f32_e32 vcc, 0, v126
	s_nop 1
	v_cndmask_b32_e32 v126, 2.0, v189, vcc
	v_mul_f32_e32 v216, v126, v106
	v_mul_f32_e32 v217, v127, v107
	v_add_f32_e32 v126, s48, v212
	v_add_f32_e32 v127, s49, v212
	v_mul_f32_e32 v198, v237, v127
	v_mul_f32_e64 v199, v127, -v238
	v_mul_f32_e32 v189, v237, v126
	v_mul_f32_e64 v190, v126, -v238
	v_min_f32_e32 v198, v198, v199
	v_exp_f32_e32 v198, v198
	v_min_f32_e32 v189, v189, v190
	v_exp_f32_e32 v189, v189
	v_cmp_neq_f32_e32 vcc, 0, v127
	v_mov_b32_e32 v199, v124
	s_nop 0
	v_cndmask_b32_e32 v127, 2.0, v198, vcc
	v_cmp_neq_f32_e32 vcc, 0, v126
	s_nop 1
	v_cndmask_b32_e32 v126, 2.0, v189, vcc
	v_mul_f32_e32 v218, v126, v108
	v_mul_f32_e32 v219, v127, v109
	v_add_f32_e32 v126, 0xc2580000, v212
	v_mul_f32_e32 v127, v237, v126
	v_mul_f32_e64 v189, v126, -v238
	v_min_f32_e32 v127, v127, v189
	v_add_f32_e32 v189, 0xc25c0000, v212
	v_mul_f32_e32 v190, v237, v189
	v_mul_f32_e64 v198, v189, -v238
	v_exp_f32_e32 v127, v127
	v_min_f32_e32 v190, v190, v198
	v_exp_f32_e32 v190, v190
	v_cmp_neq_f32_e32 vcc, 0, v126
	v_mov_b32_e32 v198, v123
	s_nop 0
	v_cndmask_b32_e32 v126, 2.0, v127, vcc
	v_cmp_neq_f32_e32 vcc, 0, v189
	v_mul_f32_e32 v250, v126, v110
	v_mov_b32_e32 v189, v112
	v_cndmask_b32_e32 v251, 2.0, v190, vcc
	v_mov_b32_e32 v190, v125
.LBB0_361:
	s_andn2_saveexec_b64 s[12:13], s[12:13]
	s_cbranch_execz .LBB0_363
	v_exp_f32_e32 v212, v252
	ds_read_b128 v[188:191], v235 offset:41088
	ds_read_b128 v[192:195], v235 offset:41104
	ds_read_b128 v[196:199], v235 offset:41120
	ds_read_b128 v[200:203], v235 offset:41136
	s_waitcnt lgkmcnt(3)
	v_mul_f32_e32 v208, v212, v190
	v_mul_f32_e32 v209, v212, v191
	s_waitcnt lgkmcnt(2)
	v_mul_f32_e32 v194, v212, v194
	v_mul_f32_e32 v195, v212, v195
	s_waitcnt lgkmcnt(1)
	v_mul_f32_e32 v204, v212, v198
	v_mul_f32_e32 v205, v212, v199
	v_mul_f32_e32 v188, v212, v188
	v_mul_f32_e32 v189, v212, v189
	v_mul_f32_e32 v196, v212, v196
	v_mul_f32_e32 v197, v212, v197
	s_waitcnt lgkmcnt(0)
	v_mul_f32_e32 v198, v212, v200
	v_mul_f32_e32 v199, v212, v201
	v_mul_f32_e32 v200, v122, v204
	v_mul_f32_e32 v201, v123, v205
	v_mul_f32_e32 v204, v120, v196
	v_mul_f32_e32 v205, v121, v197
	v_mul_f32_e32 v206, v118, v194
	v_mul_f32_e32 v207, v119, v195
	ds_read_b128 v[118:121], v235 offset:41152
	v_mul_f32_e32 v214, v114, v208
	v_mul_f32_e32 v215, v115, v209
	v_mul_f32_e32 v188, v112, v188
	v_mul_f32_e32 v189, v113, v189
	ds_read_b128 v[112:115], v235 offset:41168
	v_mul_f32_e32 v192, v212, v192
	v_mul_f32_e32 v193, v212, v193
	v_mul_f32_e32 v210, v116, v192
	v_mul_f32_e32 v211, v117, v193
	s_waitcnt lgkmcnt(1)
	v_mul_f32_e32 v116, v212, v118
	v_mul_f32_e32 v117, v212, v119
	v_mul_f32_e32 v192, v96, v116
	v_mul_f32_e32 v193, v97, v117
	s_waitcnt lgkmcnt(0)
	v_mul_f32_e32 v112, v212, v112
	v_mul_f32_e32 v113, v212, v113
	v_mul_f32_e32 v116, v212, v120
	v_mul_f32_e32 v117, v212, v121
	v_mul_f32_e32 v196, v100, v112
	v_mul_f32_e32 v197, v101, v113
	v_mul_f32_e32 v112, v212, v114
	v_mul_f32_e32 v113, v212, v115
	v_mul_f32_e32 v190, v212, v202
	v_mul_f32_e32 v191, v212, v203
	v_mul_f32_e32 v194, v98, v116
	v_mul_f32_e32 v195, v99, v117
	ds_read_b128 v[116:119], v235 offset:41184
	v_mul_f32_e32 v202, v102, v112
	v_mul_f32_e32 v203, v103, v113
	ds_read_b128 v[112:115], v235 offset:41200
	v_mul_f32_e32 v190, v126, v190
	v_mul_f32_e32 v191, v127, v191
	v_mul_f32_e32 v198, v124, v198
	v_mul_f32_e32 v199, v125, v199
	s_waitcnt lgkmcnt(1)
	v_mul_f32_e32 v116, v212, v116
	v_mul_f32_e32 v117, v212, v117
	v_mul_f32_e32 v208, v104, v116
	v_mul_f32_e32 v209, v105, v117
	s_waitcnt lgkmcnt(0)
	v_mul_f32_e32 v112, v212, v112
	v_mul_f32_e32 v113, v212, v113
	v_mul_f32_e32 v116, v212, v118
	v_mul_f32_e32 v117, v212, v119
	v_mul_f32_e32 v218, v108, v112
	v_mul_f32_e32 v219, v109, v113
	v_mul_f32_e32 v112, v212, v114
	v_mul_f32_e32 v216, v106, v116
	v_mul_f32_e32 v217, v107, v117
	v_mul_f32_e32 v250, v110, v112
	v_mul_f32_e32 v251, v212, v115

.LBB0_364:
	s_andn2_saveexec_b64 s[10:11], s[10:11]
	s_cbranch_execz .LBB0_366
	v_mul_f32_e32 v188, v237, v212
	v_exp_f32_e32 v212, v188
	ds_read_b128 v[188:191], v235 offset:40960
	ds_read_b128 v[192:195], v235 offset:40976
	ds_read_b128 v[196:199], v235 offset:40992
	ds_read_b128 v[200:203], v235 offset:41008
	s_waitcnt lgkmcnt(2)
	v_mul_f32_e32 v194, v212, v194
	v_mul_f32_e32 v195, v212, v195
	s_waitcnt lgkmcnt(1)
	v_mul_f32_e32 v204, v212, v198
	v_mul_f32_e32 v205, v212, v199
	v_mul_f32_e32 v196, v212, v196
	v_mul_f32_e32 v197, v212, v197
	s_waitcnt lgkmcnt(0)
	v_mul_f32_e32 v198, v212, v200
	v_mul_f32_e32 v199, v212, v201
	v_mul_f32_e32 v200, v122, v204
	v_mul_f32_e32 v201, v123, v205
	v_mul_f32_e32 v204, v120, v196
	v_mul_f32_e32 v205, v121, v197
	v_mul_f32_e32 v206, v118, v194
	v_mul_f32_e32 v207, v119, v195
	ds_read_b128 v[118:121], v235 offset:41024
	v_mul_f32_e32 v208, v212, v190
	v_mul_f32_e32 v209, v212, v191
	v_mul_f32_e32 v188, v212, v188
	v_mul_f32_e32 v189, v212, v189
	v_mul_f32_e32 v214, v114, v208
	v_mul_f32_e32 v215, v115, v209
	v_mul_f32_e32 v188, v112, v188
	v_mul_f32_e32 v189, v113, v189
	ds_read_b128 v[112:115], v235 offset:41040
	v_mul_f32_e32 v192, v212, v192
	v_mul_f32_e32 v193, v212, v193
	v_mul_f32_e32 v210, v116, v192
	v_mul_f32_e32 v211, v117, v193
	s_waitcnt lgkmcnt(1)
	v_mul_f32_e32 v116, v212, v118
	v_mul_f32_e32 v117, v212, v119
	v_mul_f32_e32 v192, v96, v116
	v_mul_f32_e32 v193, v97, v117
	v_mul_f32_e32 v96, v212, v120
	v_mul_f32_e32 v97, v212, v121
	v_mul_f32_e32 v194, v98, v96
	v_mul_f32_e32 v195, v99, v97
	s_waitcnt lgkmcnt(0)
	v_mul_f32_e32 v112, v212, v112
	v_mul_f32_e32 v113, v212, v113
	ds_read_b128 v[96:99], v235 offset:41056
	v_mul_f32_e32 v196, v100, v112
	v_mul_f32_e32 v197, v101, v113
	v_mul_f32_e32 v100, v212, v114
	v_mul_f32_e32 v101, v212, v115
	v_mul_f32_e32 v190, v212, v202
	v_mul_f32_e32 v191, v212, v203
	v_mul_f32_e32 v202, v102, v100
	v_mul_f32_e32 v203, v103, v101
	ds_read_b128 v[100:103], v235 offset:41072
	s_waitcnt lgkmcnt(1)
	v_mul_f32_e32 v96, v212, v96
	v_mul_f32_e32 v97, v212, v97
	v_mul_f32_e32 v208, v104, v96
	v_mul_f32_e32 v209, v105, v97
	v_mul_f32_e32 v96, v212, v98
	v_mul_f32_e32 v97, v212, v99
	v_mul_f32_e32 v216, v106, v96
	v_mul_f32_e32 v217, v107, v97
	s_waitcnt lgkmcnt(0)
	v_mul_f32_e32 v96, v212, v100
	v_mul_f32_e32 v97, v212, v101
	v_mul_f32_e32 v218, v108, v96
	v_mul_f32_e32 v219, v109, v97
	v_mul_f32_e32 v96, v212, v102
	v_mul_f32_e32 v190, v126, v190
	v_mul_f32_e32 v191, v127, v191
	v_mul_f32_e32 v198, v124, v198
	v_mul_f32_e32 v199, v125, v199
	v_mul_f32_e32 v250, v110, v96
	v_mul_f32_e32 v251, v212, v103
.LBB0_366:
	s_or_b64 exec, exec, s[10:11]
	s_nop 0
	v_cvt_pk_bf16_f32 v108, v188, v189
	v_add_u32_e32 v188, v249, v242
	ds_read_b128 v[112:115], v188 offset:9216
	ds_read_b128 v[116:119], v188 offset:9248
	v_mul_f32_e32 v99, v111, v251
	v_cvt_pk_bf16_f32 v109, v214, v215
	v_cvt_pk_bf16_f32 v110, v210, v211
	v_cvt_pk_bf16_f32 v111, v206, v207
	v_cvt_pk_bf16_f32 v100, v204, v205
	v_cvt_pk_bf16_f32 v101, v200, v201
	s_waitcnt lgkmcnt(1)
	v_mfma_f32_32x32x16_bf16 v[48:63], v[112:115], v[108:111], v[48:63]
	v_cvt_pk_bf16_f32 v102, v198, v199
	v_cvt_pk_bf16_f32 v103, v190, v191
	ds_read_b128 v[112:115], v188 offset:9280
	v_cvt_pk_bf16_f32 v104, v192, v193
	v_cvt_pk_bf16_f32 v105, v194, v195
	v_cvt_pk_bf16_f32 v106, v196, v197
	v_cvt_pk_bf16_f32 v107, v202, v203
	s_waitcnt lgkmcnt(1)
	v_mfma_f32_32x32x16_bf16 v[48:63], v[116:119], v[100:103], v[48:63]
	v_cvt_pk_bf16_f32 v96, v208, v209
	v_cvt_pk_bf16_f32 v97, v216, v217
	v_cvt_pk_bf16_f32 v98, v218, v219
	v_cvt_pk_bf16_f32 v99, v250, v99
	s_waitcnt lgkmcnt(0)
	v_mfma_f32_32x32x16_bf16 v[48:63], v[112:115], v[104:107], v[48:63]
	ds_read_b128 v[112:115], v188 offset:9312
	s_waitcnt lgkmcnt(0)
	v_mfma_f32_32x32x16_bf16 v[48:63], v[112:115], v[96:99], v[48:63]
	ds_read_b128 v[112:115], v188 offset:13824
	s_waitcnt lgkmcnt(0)
	v_mfma_f32_32x32x16_bf16 v[32:47], v[112:115], v[108:111], v[32:47]
	ds_read_b128 v[108:111], v188 offset:13856
	s_waitcnt lgkmcnt(0)
	v_mfma_f32_32x32x16_bf16 v[32:47], v[108:111], v[100:103], v[32:47]
	ds_read_b128 v[100:103], v188 offset:13888
	s_waitcnt lgkmcnt(0)
	v_mfma_f32_32x32x16_bf16 v[32:47], v[100:103], v[104:107], v[32:47]
	ds_read_b128 v[100:103], v188 offset:13920
	s_waitcnt lgkmcnt(0)
	v_mfma_f32_32x32x16_bf16 v[32:47], v[100:103], v[96:99], v[32:47]
	v_add_u32_e32 v96, 32, v247
	v_cvt_f32_i32_e32 v98, v96
	v_cmp_ge_i32_e32 vcc, s24, v243
	s_and_saveexec_b64 s[10:11], vcc
	s_xor_b64 s[10:11], exec, s[10:11]
	s_cbranch_execz .LBB0_372
	v_cmp_le_i32_e32 vcc, s20, v244
	v_mul_f32_e64 v97, -v238, v98
	s_and_saveexec_b64 s[12:13], vcc
	s_xor_b64 s[12:13], exec, s[12:13]
	s_cbranch_execz .LBB0_369
	v_mul_f32_e32 v96, v237, v98
	v_min_f32_e32 v96, v96, v97
	v_exp_f32_e32 v96, v96
	s_mov_b32 s24, -1.0
	s_mov_b32 s25, -2.0
	v_add_f32_e32 v100, s24, v98
	v_add_f32_e32 v101, s25, v98
	v_cmp_ne_u32_e32 vcc, 32, v248
	v_mul_f32_e32 v99, v237, v101
	v_mul_f32_e64 v102, v101, -v238
	v_cndmask_b32_e32 v96, 2.0, v96, vcc
	v_mul_f32_e32 v97, v237, v100
	v_mul_f32_e32 v96, v96, v80
	v_mul_f32_e64 v80, v100, -v238
	v_min_f32_e32 v99, v99, v102
	v_exp_f32_e32 v99, v99
	v_min_f32_e32 v80, v97, v80
	v_exp_f32_e32 v80, v80
	v_cmp_neq_f32_e32 vcc, 0, v101
	s_mov_b32 s24, 0xc0400000
	s_mov_b32 s25, -4.0
	v_cndmask_b32_e32 v101, 2.0, v99, vcc
	v_cmp_neq_f32_e32 vcc, 0, v100
	s_nop 1
	v_cndmask_b32_e32 v100, 2.0, v80, vcc
	v_mov_b32_e32 v80, v81
	v_mov_b32_e32 v81, v82
	v_mul_f32_e32 v100, v100, v80
	v_mul_f32_e32 v101, v101, v81
	v_add_f32_e32 v80, s24, v98
	v_add_f32_e32 v81, s25, v98
	v_mul_f32_e32 v99, v237, v81
	v_mul_f32_e64 v102, v81, -v238
	v_mul_f32_e32 v82, v237, v80
	v_mul_f32_e64 v97, v80, -v238
	v_min_f32_e32 v99, v99, v102
	v_exp_f32_e32 v99, v99
	v_min_f32_e32 v82, v82, v97
	v_exp_f32_e32 v82, v82
	v_cmp_neq_f32_e32 vcc, 0, v81
	s_mov_b32 s24, 0xc0a00000
	s_mov_b32 s25, 0xc0c00000
	v_cndmask_b32_e32 v81, 2.0, v99, vcc
	v_cmp_neq_f32_e32 vcc, 0, v80
	s_nop 1
	v_cndmask_b32_e32 v80, 2.0, v82, vcc
	v_mov_b32_e32 v82, v83
	v_mov_b32_e32 v83, v84
	v_mul_f32_e32 v102, v80, v82
	v_mul_f32_e32 v103, v81, v83
	v_add_f32_e32 v80, s24, v98
	v_add_f32_e32 v81, s25, v98
	v_mul_f32_e32 v84, v237, v81
	v_mul_f32_e64 v97, v81, -v238
	v_mul_f32_e32 v82, v237, v80
	v_mul_f32_e64 v83, v80, -v238
	v_min_f32_e32 v84, v84, v97
	v_exp_f32_e32 v84, v84
	v_min_f32_e32 v82, v82, v83
	v_exp_f32_e32 v82, v82
	v_cmp_neq_f32_e32 vcc, 0, v81
	s_mov_b32 s24, 0xc0e00000
	v_mov_b32_e32 v83, v86
	v_cndmask_b32_e32 v81, 2.0, v84, vcc
	v_cmp_neq_f32_e32 vcc, 0, v80
	s_mov_b32 s25, 0xc1800000
	s_nop 0
	v_cndmask_b32_e32 v80, 2.0, v82, vcc
	v_mov_b32_e32 v82, v85
	v_mul_f32_e32 v106, v80, v82
	v_mul_f32_e32 v107, v81, v83
	v_add_f32_e32 v80, s24, v98
	v_add_f32_e32 v81, s25, v98
	v_mul_f32_e32 v84, v237, v81
	v_mul_f32_e64 v85, v81, -v238
	v_mul_f32_e32 v82, v237, v80
	v_mul_f32_e64 v83, v80, -v238
	v_min_f32_e32 v84, v84, v85
	v_exp_f32_e32 v84, v84
	v_min_f32_e32 v82, v82, v83
	v_exp_f32_e32 v82, v82
	v_cmp_neq_f32_e32 vcc, 0, v81
	s_mov_b32 s24, 0xc1880000
	v_mov_b32_e32 v83, v88
	v_cndmask_b32_e32 v81, 2.0, v84, vcc
	v_cmp_neq_f32_e32 vcc, 0, v80
	s_mov_b32 s25, 0xc1900000
	s_nop 0
	v_cndmask_b32_e32 v80, 2.0, v82, vcc
	v_mov_b32_e32 v82, v87
	v_mul_f32_e32 v108, v80, v82
	v_mul_f32_e32 v109, v81, v83
	v_add_f32_e32 v80, s24, v98
	v_add_f32_e32 v81, s25, v98
	v_mul_f32_e32 v84, v237, v81
	v_mul_f32_e64 v85, v81, -v238
	v_mul_f32_e32 v82, v237, v80
	v_mul_f32_e64 v83, v80, -v238
	v_min_f32_e32 v84, v84, v85
	v_exp_f32_e32 v84, v84
	v_min_f32_e32 v82, v82, v83
	v_exp_f32_e32 v82, v82
	v_cmp_neq_f32_e32 vcc, 0, v81
	s_mov_b32 s24, 0xc1980000
	v_mov_b32_e32 v83, v90
	v_cndmask_b32_e32 v81, 2.0, v84, vcc
	v_cmp_neq_f32_e32 vcc, 0, v80
	s_mov_b32 s25, 0xc1a00000
	s_nop 0
	v_cndmask_b32_e32 v80, 2.0, v82, vcc
	v_mov_b32_e32 v82, v89
	v_mul_f32_e32 v112, v80, v82
	v_mul_f32_e32 v113, v81, v83
	v_add_f32_e32 v80, s24, v98
	v_add_f32_e32 v81, s25, v98
	v_mul_f32_e32 v84, v237, v81
	v_mul_f32_e64 v85, v81, -v238
	v_mul_f32_e32 v82, v237, v80
	v_mul_f32_e64 v83, v80, -v238
	v_min_f32_e32 v84, v84, v85
	v_exp_f32_e32 v84, v84
	v_min_f32_e32 v82, v82, v83
	v_exp_f32_e32 v82, v82
	v_cmp_neq_f32_e32 vcc, 0, v81
	s_mov_b32 s24, 0xc1a80000
	v_mov_b32_e32 v83, v92
	v_cndmask_b32_e32 v81, 2.0, v84, vcc
	v_cmp_neq_f32_e32 vcc, 0, v80
	s_mov_b32 s25, 0xc1b00000
	s_nop 0
	v_cndmask_b32_e32 v80, 2.0, v82, vcc
	v_mov_b32_e32 v82, v91
	v_mul_f32_e32 v114, v80, v82
	v_mul_f32_e32 v115, v81, v83
	v_add_f32_e32 v80, s24, v98
	v_add_f32_e32 v81, s25, v98
	v_mul_f32_e32 v84, v237, v81
	v_mul_f32_e64 v85, v81, -v238
	v_min_f32_e32 v84, v84, v85
	v_exp_f32_e32 v84, v84
	v_cmp_neq_f32_e32 vcc, 0, v81
	v_mul_f32_e32 v82, v237, v80
	v_mul_f32_e64 v83, v80, -v238
	v_cndmask_b32_e32 v81, 2.0, v84, vcc
	v_add_f32_e32 v84, 0xc1b80000, v98
	v_min_f32_e32 v82, v82, v83
	v_mul_f32_e32 v83, v237, v84
	v_mul_f32_e64 v85, v84, -v238
	v_exp_f32_e32 v82, v82
	v_min_f32_e32 v83, v83, v85
	v_exp_f32_e32 v85, v83
	v_cmp_neq_f32_e32 vcc, 0, v80
	v_mov_b32_e32 v83, v94
	s_mov_b32 s24, 0xc2000000
	v_cndmask_b32_e32 v80, 2.0, v82, vcc
	v_mov_b32_e32 v82, v93
	v_cmp_neq_f32_e32 vcc, 0, v84
	v_mul_f32_e32 v120, v80, v82
	v_mul_f32_e32 v121, v81, v83
	s_mov_b32 s25, 0xc2040000
	v_cndmask_b32_e32 v80, 2.0, v85, vcc
	v_mul_f32_e32 v99, v80, v95
	v_add_f32_e32 v80, s24, v98
	v_add_f32_e32 v81, s25, v98
	v_mul_f32_e32 v84, v237, v81
	v_mul_f32_e64 v85, v81, -v238
	v_mul_f32_e32 v82, v237, v80
	v_mul_f32_e64 v83, v80, -v238
	v_min_f32_e32 v84, v84, v85
	v_exp_f32_e32 v84, v84
	v_min_f32_e32 v82, v82, v83
	v_exp_f32_e32 v82, v82
	v_cmp_neq_f32_e32 vcc, 0, v81
	s_mov_b32 s24, 0xc2080000
	s_mov_b32 s25, 0xc20c0000
	v_cndmask_b32_e32 v81, 2.0, v84, vcc
	v_cmp_neq_f32_e32 vcc, 0, v80
	s_nop 1
	v_cndmask_b32_e32 v80, 2.0, v82, vcc
	v_mul_f32_e32 v104, v80, v64
	v_mul_f32_e32 v105, v81, v65
	v_add_f32_e32 v80, s24, v98
	v_add_f32_e32 v81, s25, v98
	v_mul_f32_e32 v84, v237, v81
	v_mul_f32_e64 v85, v81, -v238
	v_mul_f32_e32 v82, v237, v80
	v_mul_f32_e64 v83, v80, -v238
	v_min_f32_e32 v84, v84, v85
	v_exp_f32_e32 v84, v84
	v_min_f32_e32 v82, v82, v83
	v_exp_f32_e32 v82, v82
	v_cmp_neq_f32_e32 vcc, 0, v81
	s_mov_b32 s24, 0xc2100000
	s_mov_b32 s25, 0xc2140000
	v_cndmask_b32_e32 v81, 2.0, v84, vcc
	v_cmp_neq_f32_e32 vcc, 0, v80
	s_nop 1
	v_cndmask_b32_e32 v80, 2.0, v82, vcc
	v_mul_f32_e32 v110, v80, v66
	v_mul_f32_e32 v111, v81, v67
	v_add_f32_e32 v80, s24, v98
	v_add_f32_e32 v81, s25, v98
	v_mul_f32_e32 v84, v237, v81
	v_mul_f32_e64 v85, v81, -v238
	v_mul_f32_e32 v82, v237, v80
	v_mul_f32_e64 v83, v80, -v238
	v_min_f32_e32 v84, v84, v85
	v_exp_f32_e32 v84, v84
	v_min_f32_e32 v82, v82, v83
	v_exp_f32_e32 v82, v82
	v_cmp_neq_f32_e32 vcc, 0, v81
	s_mov_b32 s24, 0xc2180000
	s_mov_b32 s25, 0xc21c0000
	v_cndmask_b32_e32 v81, 2.0, v84, vcc
	v_cmp_neq_f32_e32 vcc, 0, v80
	s_nop 1
	v_cndmask_b32_e32 v80, 2.0, v82, vcc
	v_mul_f32_e32 v116, v80, v68
	v_mul_f32_e32 v117, v81, v69
	v_add_f32_e32 v80, s24, v98
	v_add_f32_e32 v81, s25, v98
	v_mul_f32_e32 v84, v237, v81
	v_mul_f32_e64 v85, v81, -v238
	v_mul_f32_e32 v82, v237, v80
	v_mul_f32_e64 v83, v80, -v238
	v_min_f32_e32 v84, v84, v85
	v_exp_f32_e32 v84, v84
	v_min_f32_e32 v82, v82, v83
	v_exp_f32_e32 v82, v82
	v_cmp_neq_f32_e32 vcc, 0, v81
	s_mov_b32 s24, 0xc2400000
	s_mov_b32 s25, 0xc2440000
	v_cndmask_b32_e32 v81, 2.0, v84, vcc
	v_cmp_neq_f32_e32 vcc, 0, v80
	s_nop 1
	v_cndmask_b32_e32 v80, 2.0, v82, vcc
	v_mul_f32_e32 v118, v80, v70
	v_mul_f32_e32 v119, v81, v71
	v_add_f32_e32 v80, s24, v98
	v_add_f32_e32 v81, s25, v98
	v_mul_f32_e32 v84, v237, v81
	v_mul_f32_e64 v85, v81, -v238
	v_mul_f32_e32 v82, v237, v80
	v_mul_f32_e64 v83, v80, -v238
	v_min_f32_e32 v84, v84, v85
	v_exp_f32_e32 v84, v84
	v_min_f32_e32 v82, v82, v83
	v_exp_f32_e32 v82, v82
	v_cmp_neq_f32_e32 vcc, 0, v81
	s_mov_b32 s24, 0xc2480000
	s_mov_b32 s25, 0xc24c0000
	v_cndmask_b32_e32 v81, 2.0, v84, vcc
	v_cmp_neq_f32_e32 vcc, 0, v80
	s_nop 1
	v_cndmask_b32_e32 v80, 2.0, v82, vcc
	v_mul_f32_e32 v122, v80, v72
	v_mul_f32_e32 v123, v81, v73
	v_add_f32_e32 v80, s24, v98
	v_add_f32_e32 v81, s25, v98
	v_mul_f32_e32 v84, v237, v81
	v_mul_f32_e64 v85, v81, -v238
	v_mul_f32_e32 v82, v237, v80
	v_mul_f32_e64 v83, v80, -v238
	v_min_f32_e32 v84, v84, v85
	v_exp_f32_e32 v84, v84
	v_min_f32_e32 v82, v82, v83
	v_exp_f32_e32 v82, v82
	v_cmp_neq_f32_e32 vcc, 0, v81
	s_mov_b32 s24, 0xc2500000
	s_mov_b32 s25, 0xc2540000
	v_cndmask_b32_e32 v81, 2.0, v84, vcc
	v_cmp_neq_f32_e32 vcc, 0, v80
	s_nop 1
	v_cndmask_b32_e32 v80, 2.0, v82, vcc
	v_mul_f32_e32 v124, v80, v74
	v_mul_f32_e32 v125, v81, v75
	v_add_f32_e32 v80, s24, v98
	v_add_f32_e32 v81, s25, v98
	v_mul_f32_e32 v84, v237, v81
	v_mul_f32_e64 v85, v81, -v238
	v_mul_f32_e32 v82, v237, v80
	v_mul_f32_e64 v83, v80, -v238
	v_min_f32_e32 v84, v84, v85
	v_exp_f32_e32 v84, v84
	v_min_f32_e32 v82, v82, v83
	v_exp_f32_e32 v82, v82
	v_cmp_neq_f32_e32 vcc, 0, v81
	s_nop 1
	v_cndmask_b32_e32 v81, 2.0, v84, vcc
	v_cmp_neq_f32_e32 vcc, 0, v80
	s_nop 1
	v_cndmask_b32_e32 v80, 2.0, v82, vcc
	v_mul_f32_e32 v126, v80, v76
	v_mul_f32_e32 v127, v81, v77
	v_add_f32_e32 v80, 0xc2580000, v98
	v_mul_f32_e32 v81, v237, v80
	v_mul_f32_e64 v82, v80, -v238
	v_min_f32_e32 v81, v81, v82
	v_add_f32_e32 v82, 0xc25c0000, v98
	v_mul_f32_e32 v83, v237, v82
	v_mul_f32_e64 v84, v82, -v238
	v_exp_f32_e32 v81, v81
	v_min_f32_e32 v83, v83, v84
	v_exp_f32_e32 v83, v83
	v_cmp_neq_f32_e32 vcc, 0, v80
	s_nop 1
	v_cndmask_b32_e32 v80, 2.0, v81, vcc
	v_cmp_neq_f32_e32 vcc, 0, v82
	v_mul_f32_e32 v189, v80, v78
	s_nop 0
	v_cndmask_b32_e32 v190, 2.0, v83, vcc
.LBB0_369:
	s_andn2_saveexec_b64 s[12:13], s[12:13]
	s_cbranch_execz .LBB0_371
	v_exp_f32_e32 v112, v97
	ds_read_b128 v[96:99], v235 offset:41088
	ds_read_b128 v[100:103], v235 offset:41104
	ds_read_b128 v[104:107], v235 offset:41120
	ds_read_b128 v[108:111], v235 offset:41136
	s_waitcnt lgkmcnt(3)
	v_mul_f32_e32 v114, v112, v98
	v_mul_f32_e32 v115, v112, v99
	s_waitcnt lgkmcnt(2)
	v_mul_f32_e32 v102, v112, v102
	v_mul_f32_e32 v103, v112, v103
	s_waitcnt lgkmcnt(0)
	v_mul_f32_e32 v98, v112, v110
	v_mul_f32_e32 v99, v112, v111
	v_mul_f32_e32 v96, v112, v96
	v_mul_f32_e32 v97, v112, v97
	v_mul_f32_e32 v104, v112, v104
	v_mul_f32_e32 v105, v112, v105
	v_mul_f32_e32 v98, v94, v98
	v_mul_f32_e32 v99, v95, v99
	v_mul_f32_e32 v94, v88, v104
	v_mul_f32_e32 v95, v89, v105
	v_mul_f32_e32 v102, v86, v102
	v_mul_f32_e32 v103, v87, v103
	ds_read_b128 v[86:89], v235 offset:41152
	v_mul_f32_e32 v192, v82, v114
	v_mul_f32_e32 v193, v83, v115
	v_mul_f32_e32 v96, v80, v96
	v_mul_f32_e32 v97, v81, v97
	ds_read_b128 v[80:83], v235 offset:41168
	v_mul_f32_e32 v100, v112, v100
	v_mul_f32_e32 v101, v112, v101
	v_mul_f32_e32 v100, v84, v100
	v_mul_f32_e32 v101, v85, v101
	s_waitcnt lgkmcnt(1)
	v_mul_f32_e32 v84, v112, v86
	v_mul_f32_e32 v85, v112, v87
	v_mul_f32_e32 v104, v64, v84
	v_mul_f32_e32 v105, v65, v85
	s_waitcnt lgkmcnt(0)
	v_mul_f32_e32 v80, v112, v80
	v_mul_f32_e32 v81, v112, v81
	v_mul_f32_e32 v84, v112, v88
	v_mul_f32_e32 v85, v112, v89
	v_mul_f32_e32 v116, v68, v80
	v_mul_f32_e32 v117, v69, v81
	v_mul_f32_e32 v80, v112, v82
	v_mul_f32_e32 v81, v112, v83
	v_mul_f32_e32 v110, v66, v84
	v_mul_f32_e32 v111, v67, v85
	ds_read_b128 v[84:87], v235 offset:41184
	v_mul_f32_e32 v118, v70, v80
	v_mul_f32_e32 v119, v71, v81
	ds_read_b128 v[80:83], v235 offset:41200
	v_mul_f32_e32 v106, v112, v106
	v_mul_f32_e32 v107, v112, v107
	v_mul_f32_e32 v108, v112, v108
	v_mul_f32_e32 v109, v112, v109
	s_waitcnt lgkmcnt(1)
	v_mul_f32_e32 v84, v112, v84
	v_mul_f32_e32 v85, v112, v85
	v_mul_f32_e32 v92, v92, v108
	v_mul_f32_e32 v93, v93, v109
	s_waitcnt lgkmcnt(0)
	v_mul_f32_e32 v80, v112, v80
	v_mul_f32_e32 v81, v112, v81
	v_mul_f32_e32 v90, v90, v106
	v_mul_f32_e32 v91, v91, v107
	v_mul_f32_e32 v122, v72, v84
	v_mul_f32_e32 v123, v73, v85
	v_mul_f32_e32 v84, v112, v86
	v_mul_f32_e32 v85, v112, v87
	v_mul_f32_e32 v126, v76, v80
	v_mul_f32_e32 v127, v77, v81
	v_mul_f32_e32 v80, v112, v82
	v_mul_f32_e32 v124, v74, v84
	v_mul_f32_e32 v125, v75, v85
	v_mul_f32_e32 v189, v78, v80
	v_mul_f32_e32 v190, v112, v83
	v_mov_b32_e32 v121, v98
	v_mov_b32_e32 v120, v93
	v_mov_b32_e32 v115, v92
	v_mov_b32_e32 v114, v91
	v_mov_b32_e32 v113, v90
	v_mov_b32_e32 v112, v95
	v_mov_b32_e32 v109, v94
	v_mov_b32_e32 v108, v103
	v_mov_b32_e32 v107, v102
	v_mov_b32_e32 v106, v101
	v_mov_b32_e32 v103, v100
	v_mov_b32_e32 v102, v193
	v_mov_b32_e32 v101, v192
	v_mov_b32_e32 v100, v97

.LBB0_372:
	s_andn2_saveexec_b64 s[10:11], s[10:11]
	s_cbranch_execz .LBB0_374
	v_mul_f32_e32 v96, v237, v98
	v_exp_f32_e32 v112, v96
	ds_read_b128 v[96:99], v235 offset:40960
	ds_read_b128 v[100:103], v235 offset:40976
	ds_read_b128 v[104:107], v235 offset:40992
	ds_read_b128 v[108:111], v235 offset:41008
	s_waitcnt lgkmcnt(3)
	v_mul_f32_e32 v114, v112, v98
	v_mul_f32_e32 v115, v112, v99
	s_waitcnt lgkmcnt(2)
	v_mul_f32_e32 v102, v112, v102
	v_mul_f32_e32 v103, v112, v103
	s_waitcnt lgkmcnt(0)
	v_mul_f32_e32 v98, v112, v110
	v_mul_f32_e32 v99, v112, v111
	v_mul_f32_e32 v104, v112, v104
	v_mul_f32_e32 v105, v112, v105
	v_mul_f32_e32 v108, v112, v108
	v_mul_f32_e32 v109, v112, v109
	v_mul_f32_e32 v98, v94, v98
	v_mul_f32_e32 v99, v95, v99
	v_mul_f32_e32 v92, v92, v108
	v_mul_f32_e32 v93, v93, v109
	v_mul_f32_e32 v94, v88, v104
	v_mul_f32_e32 v95, v89, v105
	v_mul_f32_e32 v108, v86, v102
	v_mul_f32_e32 v109, v87, v103
	ds_read_b128 v[86:89], v235 offset:41024
	v_mul_f32_e32 v96, v112, v96
	v_mul_f32_e32 v97, v112, v97
	v_mul_f32_e32 v102, v82, v114
	v_mul_f32_e32 v103, v83, v115
	v_mul_f32_e32 v96, v80, v96
	v_mul_f32_e32 v97, v81, v97
	ds_read_b128 v[80:83], v235 offset:41040
	s_waitcnt lgkmcnt(1)
	v_mul_f32_e32 v86, v112, v86
	v_mul_f32_e32 v87, v112, v87
	v_mul_f32_e32 v104, v64, v86
	v_mul_f32_e32 v105, v65, v87
	v_mul_f32_e32 v64, v112, v88
	v_mul_f32_e32 v65, v112, v89
	v_mul_f32_e32 v110, v66, v64
	v_mul_f32_e32 v111, v67, v65
	s_waitcnt lgkmcnt(0)
	v_mul_f32_e32 v80, v112, v80
	v_mul_f32_e32 v81, v112, v81
	ds_read_b128 v[64:67], v235 offset:41056
	v_mul_f32_e32 v116, v68, v80
	v_mul_f32_e32 v117, v69, v81
	v_mul_f32_e32 v68, v112, v82
	v_mul_f32_e32 v69, v112, v83
	v_mul_f32_e32 v118, v70, v68
	v_mul_f32_e32 v119, v71, v69
	ds_read_b128 v[68:71], v235 offset:41072
	s_waitcnt lgkmcnt(1)
	v_mul_f32_e32 v64, v112, v64
	v_mul_f32_e32 v65, v112, v65
	v_mul_f32_e32 v122, v72, v64
	v_mul_f32_e32 v123, v73, v65
	v_mul_f32_e32 v64, v112, v66
	v_mul_f32_e32 v65, v112, v67
	v_mul_f32_e32 v106, v112, v106
	v_mul_f32_e32 v107, v112, v107
	v_mul_f32_e32 v100, v112, v100
	v_mul_f32_e32 v101, v112, v101
	v_mul_f32_e32 v124, v74, v64
	v_mul_f32_e32 v125, v75, v65
	s_waitcnt lgkmcnt(0)
	v_mul_f32_e32 v64, v112, v68
	v_mul_f32_e32 v65, v112, v69
	v_mul_f32_e32 v90, v90, v106
	v_mul_f32_e32 v91, v91, v107
	v_mul_f32_e32 v84, v84, v100
	v_mul_f32_e32 v85, v85, v101
	v_mul_f32_e32 v126, v76, v64
	v_mul_f32_e32 v127, v77, v65
	v_mul_f32_e32 v64, v112, v70
	v_mul_f32_e32 v189, v78, v64
	v_mul_f32_e32 v190, v112, v71
	v_mov_b32_e32 v100, v97
	v_mov_b32_e32 v101, v102
	v_mov_b32_e32 v102, v103
	v_mov_b32_e32 v103, v84
	v_mov_b32_e32 v106, v85
	v_mov_b32_e32 v107, v108
	v_mov_b32_e32 v108, v109
	v_mov_b32_e32 v109, v94
	v_mov_b32_e32 v112, v95
	v_mov_b32_e32 v113, v90
	v_mov_b32_e32 v114, v91
	v_mov_b32_e32 v115, v92
	v_mov_b32_e32 v120, v93
	v_mov_b32_e32 v121, v98

.LBB0_379:
	v_add_f32_e32 v70, 0, v197
	v_add_f32_e32 v70, v198, v70
	v_add_f32_e32 v70, v199, v70
	v_add_f32_e32 v70, v200, v70
	v_add_f32_e32 v70, v201, v70
	v_add_f32_e32 v70, v202, v70
	v_add_f32_e32 v70, v203, v70
	v_add_f32_e32 v70, v204, v70
	v_add_f32_e32 v70, v205, v70
	v_add_f32_e32 v70, v206, v70
	v_add_f32_e32 v70, v207, v70
	v_add_f32_e32 v70, v208, v70
	v_add_f32_e32 v70, v209, v70
	v_add_f32_e32 v70, v210, v70
	v_add_f32_e32 v70, v211, v70
	v_add_f32_e32 v70, v212, v70
	v_add_f32_e32 v70, v214, v70
	v_add_f32_e32 v70, v215, v70
	v_add_f32_e32 v70, v216, v70
	v_add_f32_e32 v70, v217, v70
	v_add_f32_e32 v70, v218, v70
	v_add_f32_e32 v71, v219, v70
	v_add_f32_e32 v70, 0, v80
	v_add_f32_e32 v70, v81, v70
	v_add_f32_e32 v70, v82, v70
	v_add_f32_e32 v70, v83, v70
	v_add_f32_e32 v70, v84, v70
	v_add_f32_e32 v70, v85, v70
	v_add_f32_e32 v70, v86, v70
	v_add_f32_e32 v70, v87, v70
	v_add_f32_e32 v70, v88, v70
	v_add_f32_e32 v70, v89, v70
	v_add_f32_e32 v70, v90, v70
	v_add_f32_e32 v70, v91, v70
	v_add_f32_e32 v70, v92, v70
	v_add_f32_e32 v70, v93, v70
	v_add_f32_e32 v70, v94, v70
	v_add_f32_e32 v70, v95, v70
	v_add_f32_e32 v70, v238, v70
	v_add_f32_e32 v65, v65, v70
	v_add_f32_e32 v65, v66, v65
	v_add_f32_e32 v65, v67, v65
	v_add_f32_e32 v65, v68, v65
	v_add_f32_e32 v70, v69, v65
	v_add_f32_e32 v66, v188, v70
	v_add_f32_e32 v67, v189, v71
	v_mov_b32_e32 v65, v190
	v_add_f32_e32 v66, v186, v66
	v_add_f32_e32 v67, v187, v67
	s_add_i32 s8, s8, 64
	v_add_f32_e32 v66, v184, v66
	v_add_f32_e32 v67, v185, v67
	s_cmp_lg_u32 s7, s9
	v_add_f32_e32 v66, v182, v66
	v_add_f32_e32 v67, v183, v67
	v_mov_b32_e32 v128, v196
	v_add_f32_e32 v66, v180, v66
	v_add_f32_e32 v67, v181, v67
	s_mov_b32 s10, s9
	v_add_f32_e32 v66, v174, v66
	v_add_f32_e32 v67, v175, v67
	s_waitcnt lgkmcnt(0)
	v_add_f32_e32 v66, v172, v66
	v_add_f32_e32 v67, v173, v67
	s_barrier
	v_add_f32_e32 v66, v170, v66
	v_add_f32_e32 v67, v171, v67
	s_nop 0
	v_add_f32_e32 v66, v168, v66
	v_add_f32_e32 v67, v169, v67
	s_nop 0
	v_add_f32_e32 v66, v166, v66
	v_add_f32_e32 v67, v167, v67
	v_mov_b32_e32 v166, v237
	v_fma_f32 v162, v162, v64, v66
	v_fma_f32 v163, v163, v65, v67
	s_cbranch_scc0 .LBB0_384

.LBB0_382:
	s_bitcmp1_b32 s10, 0
	s_cselect_b32 s10, 0x4800, 0
	s_add_i32 s10, s10, 16
	v_add_u32_e32 v129, s10, v176
	v_add_u32_e32 v168, v129, v194
	ds_read_b128 v[64:67], v168
	ds_read_b128 v[68:71], v168 offset:32
	s_andn2_b64 vcc, exec, s[4:5]
	s_waitcnt lgkmcnt(1)
	v_mfma_f32_32x32x16_bf16 v[80:95], v[64:67], v[96:99], 0
	ds_read_b128 v[64:67], v168 offset:4608
	ds_read_b128 v[130:133], v168 offset:4640
	s_waitcnt lgkmcnt(2)
	v_mfma_f32_32x32x16_bf16 v[80:95], v[68:71], v[100:103], v[80:95]
	s_waitcnt lgkmcnt(1)
	v_mfma_f32_32x32x16_bf16 v[64:79], v[64:67], v[96:99], 0
	s_waitcnt lgkmcnt(0)
	v_mfma_f32_32x32x16_bf16 v[64:79], v[130:133], v[100:103], v[64:79]
	s_nop 7
	v_max_f32_e32 v130, v81, v81
	v_max_f32_e32 v131, v80, v80
	v_max_f32_e32 v130, v131, v130
	v_max3_f32 v130, v130, v82, v83
	v_max3_f32 v130, v130, v84, v85
	v_max3_f32 v130, v130, v86, v87
	v_max3_f32 v130, v130, v88, v89
	v_max3_f32 v130, v130, v90, v91
	v_max3_f32 v130, v130, v92, v93
	v_max3_f32 v130, v130, v94, v95
	v_max3_f32 v130, v130, v64, v65
	v_max3_f32 v130, v130, v66, v67
	v_max3_f32 v130, v130, v68, v69
	v_max3_f32 v130, v130, v70, v71
	v_max3_f32 v130, v130, v72, v73
	v_max3_f32 v130, v130, v74, v75
	v_max3_f32 v130, v130, v76, v77
	v_max3_f32 v130, v130, v78, v79
	ds_bpermute_b32 v131, v192, v130
	s_waitcnt lgkmcnt(0)
	v_max3_f32 v196, v128, v130, v131
	v_sub_f32_e32 v80, v80, v196
	v_exp_f32_e32 v197, v80
	v_sub_f32_e32 v80, v81, v196
	v_exp_f32_e32 v198, v80
	v_sub_f32_e32 v80, v82, v196
	v_exp_f32_e32 v199, v80
	v_sub_f32_e32 v80, v83, v196
	v_exp_f32_e32 v200, v80
	v_sub_f32_e32 v80, v84, v196
	v_exp_f32_e32 v201, v80
	v_sub_f32_e32 v80, v85, v196
	v_exp_f32_e32 v202, v80
	v_sub_f32_e32 v80, v86, v196
	v_exp_f32_e32 v203, v80
	v_sub_f32_e32 v80, v87, v196
	v_exp_f32_e32 v204, v80
	v_sub_f32_e32 v80, v88, v196
	v_exp_f32_e32 v205, v80
	v_sub_f32_e32 v80, v89, v196
	v_exp_f32_e32 v206, v80
	v_sub_f32_e32 v80, v90, v196
	v_sub_f32_e32 v64, v64, v196
	v_exp_f32_e32 v207, v80
	v_sub_f32_e32 v80, v91, v196
	v_exp_f32_e32 v214, v64
	v_sub_f32_e32 v64, v65, v196
	v_exp_f32_e32 v208, v80
	v_sub_f32_e32 v80, v92, v196
	v_exp_f32_e32 v215, v64
	v_sub_f32_e32 v64, v66, v196
	v_exp_f32_e32 v209, v80
	v_sub_f32_e32 v80, v93, v196
	v_exp_f32_e32 v216, v64
	v_sub_f32_e32 v64, v67, v196
	v_exp_f32_e32 v210, v80
	v_sub_f32_e32 v80, v94, v196
	v_exp_f32_e32 v217, v64
	v_sub_f32_e32 v64, v68, v196
	v_exp_f32_e32 v211, v80
	v_sub_f32_e32 v80, v95, v196
	v_exp_f32_e32 v218, v64
	v_sub_f32_e32 v64, v69, v196
	v_sub_f32_e32 v128, v128, v196
	v_exp_f32_e32 v212, v80
	v_exp_f32_e32 v219, v64
	v_sub_f32_e32 v64, v70, v196
	v_add_u32_e32 v80, v129, v195
	v_exp_f32_e32 v189, v64
	v_sub_f32_e32 v64, v71, v196
	v_exp_f32_e32 v190, v128
	ds_read_b128 v[132:135], v80 offset:9216
	ds_read_b128 v[128:131], v80 offset:9248
	ds_read_b128 v[144:147], v80 offset:13824
	ds_read_b128 v[148:151], v80 offset:13856
	v_exp_f32_e32 v187, v64
	v_sub_f32_e32 v64, v72, v196
	v_exp_f32_e32 v185, v64
	v_sub_f32_e32 v64, v73, v196
	v_exp_f32_e32 v183, v64
	v_sub_f32_e32 v64, v74, v196
	v_exp_f32_e32 v181, v64
	v_sub_f32_e32 v64, v75, v196
	v_exp_f32_e32 v175, v64
	v_sub_f32_e32 v64, v76, v196
	v_exp_f32_e32 v173, v64
	v_sub_f32_e32 v64, v77, v196
	v_exp_f32_e32 v171, v64
	v_sub_f32_e32 v64, v78, v196
	v_exp_f32_e32 v169, v64
	v_sub_f32_e32 v64, v79, v196
	v_mul_f32_e32 v62, v62, v190
	v_mul_f32_e32 v63, v63, v190
	v_mul_f32_e32 v60, v60, v190
	v_mul_f32_e32 v61, v61, v190
	v_mul_f32_e32 v58, v58, v190
	v_mul_f32_e32 v59, v59, v190
	v_mul_f32_e32 v56, v56, v190
	v_mul_f32_e32 v57, v57, v190
	v_mul_f32_e32 v54, v54, v190
	v_mul_f32_e32 v55, v55, v190
	v_mul_f32_e32 v52, v52, v190
	v_mul_f32_e32 v53, v53, v190
	v_mul_f32_e32 v50, v50, v190
	v_mul_f32_e32 v51, v51, v190
	v_mul_f32_e32 v48, v48, v190
	v_mul_f32_e32 v49, v49, v190
	v_mul_f32_e32 v30, v30, v190
	v_mul_f32_e32 v31, v31, v190
	v_mul_f32_e32 v28, v28, v190
	v_mul_f32_e32 v29, v29, v190
	v_mul_f32_e32 v26, v26, v190
	v_mul_f32_e32 v27, v27, v190
	v_mul_f32_e32 v24, v24, v190
	v_mul_f32_e32 v25, v25, v190
	v_mul_f32_e32 v22, v22, v190
	v_mul_f32_e32 v23, v23, v190
	v_mul_f32_e32 v20, v20, v190
	v_mul_f32_e32 v21, v21, v190
	v_mul_f32_e32 v18, v18, v190
	v_mul_f32_e32 v19, v19, v190
	v_mul_f32_e32 v16, v16, v190
	v_mul_f32_e32 v17, v17, v190
	v_cvt_pk_bf16_f32 v76, v197, v198
	v_cvt_pk_bf16_f32 v77, v199, v200
	v_cvt_pk_bf16_f32 v78, v201, v202
	v_cvt_pk_bf16_f32 v79, v203, v204
	v_exp_f32_e32 v167, v64
	v_cvt_pk_bf16_f32 v64, v205, v206
	s_waitcnt lgkmcnt(3)
	v_mfma_f32_32x32x16_bf16 v[48:63], v[132:135], v[76:79], v[48:63]
	v_cvt_pk_bf16_f32 v65, v207, v208
	v_cvt_pk_bf16_f32 v66, v209, v210
	v_cvt_pk_bf16_f32 v67, v211, v212
	ds_read_b128 v[136:139], v80 offset:9280
	ds_read_b128 v[140:143], v80 offset:9312
	ds_read_b128 v[152:155], v80 offset:13888
	ds_read_b128 v[156:159], v80 offset:13920
	s_waitcnt lgkmcnt(5)
	v_mfma_f32_32x32x16_bf16 v[16:31], v[144:147], v[76:79], v[16:31]
	ds_read_b128 v[238:241], v168 offset:4704
	v_cvt_pk_bf16_f32 v72, v214, v215
	v_cvt_pk_bf16_f32 v73, v216, v217
	v_cvt_pk_bf16_f32 v74, v218, v219
	v_cvt_pk_bf16_f32 v75, v189, v187
	v_cvt_pk_bf16_f32 v68, v185, v183
	v_cvt_pk_bf16_f32 v69, v181, v175
	v_mfma_f32_32x32x16_bf16 v[48:63], v[128:131], v[64:67], v[48:63]
	v_cvt_pk_bf16_f32 v70, v173, v171
	v_cvt_pk_bf16_f32 v71, v169, v167
	s_waitcnt lgkmcnt(5)
	v_mfma_f32_32x32x16_bf16 v[16:31], v[148:151], v[64:67], v[16:31]
	ds_read_b128 v[64:67], v168 offset:64
	s_waitcnt lgkmcnt(0)
	v_mfma_f32_32x32x16_bf16 v[80:95], v[64:67], v[104:107], 0
	ds_read_b128 v[64:67], v168 offset:96
	s_waitcnt lgkmcnt(0)
	v_mfma_f32_32x32x16_bf16 v[80:95], v[64:67], v[108:111], v[80:95]
	ds_read_b128 v[64:67], v168 offset:4672
	v_mfma_f32_32x32x16_bf16 v[48:63], v[136:139], v[72:75], v[48:63]
	s_nop 9
	v_max_f32_e32 v168, v81, v81
	v_max_f32_e32 v170, v80, v80
	v_max_f32_e32 v168, v170, v168
	v_max3_f32 v168, v168, v82, v83
	v_max3_f32 v168, v168, v84, v85
	v_max3_f32 v168, v168, v86, v87
	v_max3_f32 v168, v168, v88, v89
	v_mfma_f32_32x32x16_bf16 v[16:31], v[152:155], v[72:75], v[16:31]
	v_max3_f32 v168, v168, v90, v91
	v_max3_f32 v168, v168, v92, v93
	v_max3_f32 v168, v168, v94, v95
	v_mfma_f32_32x32x16_bf16 v[48:63], v[140:143], v[68:71], v[48:63]
	v_mfma_f32_32x32x16_bf16 v[16:31], v[156:159], v[68:71], v[16:31]
	s_waitcnt lgkmcnt(0)
	v_mfma_f32_32x32x16_bf16 v[64:79], v[64:67], v[104:107], 0
	v_mfma_f32_32x32x16_bf16 v[64:79], v[238:241], v[108:111], v[64:79]
	s_nop 11
	v_max3_f32 v168, v168, v64, v65
	v_max3_f32 v168, v168, v66, v67
	v_max3_f32 v168, v168, v68, v69
	v_max3_f32 v168, v168, v70, v71
	v_max3_f32 v168, v168, v72, v73
	v_max3_f32 v168, v168, v74, v75
	v_max3_f32 v168, v168, v76, v77
	v_max3_f32 v168, v168, v78, v79
	ds_bpermute_b32 v170, v192, v168
	s_waitcnt lgkmcnt(0)
	v_max3_f32 v237, v166, v168, v170
	v_sub_f32_e32 v64, v64, v237
	v_exp_f32_e32 v238, v64
	v_sub_f32_e32 v64, v65, v237
	v_exp_f32_e32 v65, v64
	v_sub_f32_e32 v64, v66, v237
	v_exp_f32_e32 v66, v64
	v_sub_f32_e32 v64, v67, v237
	v_exp_f32_e32 v67, v64
	v_sub_f32_e32 v64, v68, v237
	v_exp_f32_e32 v68, v64
	v_sub_f32_e32 v64, v69, v237
	v_exp_f32_e32 v69, v64
	v_sub_f32_e32 v64, v70, v237
	v_exp_f32_e32 v188, v64
	v_sub_f32_e32 v64, v71, v237
	v_exp_f32_e32 v186, v64
	v_sub_f32_e32 v64, v72, v237
	v_exp_f32_e32 v184, v64
	v_sub_f32_e32 v64, v73, v237
	v_exp_f32_e32 v182, v64
	v_sub_f32_e32 v64, v74, v237
	v_exp_f32_e32 v180, v64
	v_sub_f32_e32 v64, v75, v237
	v_exp_f32_e32 v174, v64
	v_sub_f32_e32 v64, v76, v237
	v_exp_f32_e32 v172, v64
	v_sub_f32_e32 v64, v77, v237
	v_exp_f32_e32 v170, v64
	v_sub_f32_e32 v64, v78, v237
	v_sub_f32_e32 v232, v166, v237
	v_sub_f32_e32 v80, v80, v237
	v_sub_f32_e32 v81, v81, v237
	v_sub_f32_e32 v82, v82, v237
	v_sub_f32_e32 v83, v83, v237
	v_sub_f32_e32 v84, v84, v237
	v_sub_f32_e32 v85, v85, v237
	v_sub_f32_e32 v86, v86, v237
	v_sub_f32_e32 v87, v87, v237
	v_exp_f32_e32 v168, v64
	v_sub_f32_e32 v64, v79, v237
	v_exp_f32_e32 v80, v80
	v_exp_f32_e32 v81, v81
	v_exp_f32_e32 v82, v82
	v_exp_f32_e32 v83, v83
	v_exp_f32_e32 v84, v84
	v_exp_f32_e32 v85, v85
	v_exp_f32_e32 v86, v86
	v_exp_f32_e32 v87, v87
	v_exp_f32_e32 v166, v64
	v_exp_f32_e32 v64, v232
	v_cvt_pk_bf16_f32 v70, v80, v81
	v_cvt_pk_bf16_f32 v71, v82, v83
	v_cvt_pk_bf16_f32 v72, v84, v85
	v_mul_f32_e32 v46, v46, v64
	v_mul_f32_e32 v47, v47, v64
	v_mul_f32_e32 v44, v44, v64
	v_mul_f32_e32 v45, v45, v64
	v_mul_f32_e32 v42, v42, v64
	v_mul_f32_e32 v43, v43, v64
	v_mul_f32_e32 v40, v40, v64
	v_mul_f32_e32 v41, v41, v64
	v_mul_f32_e32 v38, v38, v64
	v_mul_f32_e32 v39, v39, v64
	v_mul_f32_e32 v36, v36, v64
	v_mul_f32_e32 v37, v37, v64
	v_mul_f32_e32 v34, v34, v64
	v_mul_f32_e32 v35, v35, v64
	v_mul_f32_e32 v32, v32, v64
	v_mul_f32_e32 v33, v33, v64
	v_mul_f32_e32 v14, v14, v64
	v_mul_f32_e32 v15, v15, v64
	v_mul_f32_e32 v12, v12, v64
	v_mul_f32_e32 v13, v13, v64
	v_mul_f32_e32 v10, v10, v64
	v_mul_f32_e32 v11, v11, v64
	v_mul_f32_e32 v8, v8, v64
	v_mul_f32_e32 v9, v9, v64
	v_mul_f32_e32 v6, v6, v64
	v_mul_f32_e32 v7, v7, v64
	v_mul_f32_e32 v4, v4, v64
	v_mul_f32_e32 v5, v5, v64
	v_mul_f32_e32 v2, v2, v64
	v_mul_f32_e32 v3, v3, v64
	v_mul_f32_e32 v0, v0, v64
	v_mul_f32_e32 v1, v1, v64
	v_cvt_pk_bf16_f32 v73, v86, v87
	v_sub_f32_e32 v88, v88, v237
	v_sub_f32_e32 v89, v89, v237
	v_mfma_f32_32x32x16_bf16 v[32:47], v[132:135], v[70:73], v[32:47]
	v_sub_f32_e32 v90, v90, v237
	v_sub_f32_e32 v91, v91, v237
	v_sub_f32_e32 v92, v92, v237
	v_sub_f32_e32 v93, v93, v237
	v_sub_f32_e32 v94, v94, v237
	v_sub_f32_e32 v95, v95, v237
	v_exp_f32_e32 v88, v88
	v_mfma_f32_32x32x16_bf16 v[0:15], v[144:147], v[70:73], v[0:15]
	v_exp_f32_e32 v89, v89
	v_exp_f32_e32 v90, v90
	v_exp_f32_e32 v91, v91
	v_exp_f32_e32 v92, v92
	v_exp_f32_e32 v93, v93
	v_exp_f32_e32 v94, v94
	v_exp_f32_e32 v95, v95
	v_cvt_pk_bf16_f32 v74, v88, v89
	v_cvt_pk_bf16_f32 v75, v90, v91
	v_cvt_pk_bf16_f32 v76, v92, v93
	v_cvt_pk_bf16_f32 v77, v94, v95
	v_cvt_pk_bf16_f32 v240, v238, v65
	v_cvt_pk_bf16_f32 v241, v66, v67
	v_mfma_f32_32x32x16_bf16 v[32:47], v[128:131], v[74:77], v[32:47]
	v_cvt_pk_bf16_f32 v242, v68, v69
	v_cvt_pk_bf16_f32 v243, v188, v186
	v_cvt_pk_bf16_f32 v244, v184, v182
	v_cvt_pk_bf16_f32 v245, v180, v174
	v_cvt_pk_bf16_f32 v246, v172, v170
	v_cvt_pk_bf16_f32 v247, v168, v166
	v_mfma_f32_32x32x16_bf16 v[0:15], v[148:151], v[74:77], v[0:15]
	v_mfma_f32_32x32x16_bf16 v[32:47], v[136:139], v[240:243], v[32:47]
	v_mfma_f32_32x32x16_bf16 v[0:15], v[152:155], v[240:243], v[0:15]
	v_mfma_f32_32x32x16_bf16 v[32:47], v[140:143], v[244:247], v[32:47]
	v_mfma_f32_32x32x16_bf16 v[0:15], v[156:159], v[244:247], v[0:15]
	s_cbranch_vccnz .LBB0_379
	s_bitcmp1_b32 s9, 0
	s_cselect_b32 s4, 0x4800, 0
	v_add_u32_e32 v70, s4, v193
	s_waitcnt vmcnt(3)
	ds_write_b128 v70, v[112:115]
	s_waitcnt vmcnt(2)
	ds_write_b128 v70, v[116:119] offset:9216
	s_waitcnt vmcnt(1)
	ds_write_b128 v70, v[120:123] offset:4608
	s_waitcnt vmcnt(0)
	ds_write_b128 v70, v[124:127] offset:13824
	s_branch .LBB0_379
.LBB0_384:
	s_lshl_b32 s4, s6, 7
	s_ashr_i32 s5, s4, 31
	v_readlane_b32 s48, v253, 26
	s_lshl_b64 s[4:5], s[4:5], 2
	v_readlane_b32 s52, v253, 30
	v_readlane_b32 s53, v253, 31
	s_add_u32 s4, s52, s4
	s_addc_u32 s5, s53, s5
	global_load_dwordx4 v[64:67], v177, s[4:5] offset:48
	global_load_dwordx4 v[68:71], v177, s[4:5] offset:32
	global_load_dwordx4 v[72:75], v177, s[4:5] offset:16
	global_load_dwordx4 v[76:79], v177, s[4:5]
	global_load_dwordx4 v[80:83], v177, s[4:5] offset:176
	global_load_dwordx4 v[84:87], v177, s[4:5] offset:160
	global_load_dwordx4 v[88:91], v177, s[4:5] offset:144
	global_load_dwordx4 v[92:95], v177, s[4:5] offset:128
	global_load_dwordx4 v[96:99], v177, s[4:5] offset:304
	global_load_dwordx4 v[100:103], v177, s[4:5] offset:288
	global_load_dwordx4 v[104:107], v177, s[4:5] offset:272
	global_load_dwordx4 v[108:111], v177, s[4:5] offset:256
	global_load_dwordx4 v[112:115], v177, s[4:5] offset:432
	global_load_dwordx4 v[116:119], v177, s[4:5] offset:416
	global_load_dwordx4 v[120:123], v177, s[4:5] offset:400
	global_load_dwordx4 v[124:127], v177, s[4:5] offset:384
	s_mov_b32 s7, 0x42b17218
	v_readlane_b32 s54, v253, 32
	v_readlane_b32 s55, v253, 33
	v_readlane_b32 s49, v253, 27
	v_readlane_b32 s50, v253, 28
	v_readlane_b32 s51, v253, 29
	v_readlane_b32 s56, v253, 34
	v_readlane_b32 s57, v253, 35
	v_readlane_b32 s58, v253, 36
	v_readlane_b32 s59, v253, 37
	v_readlane_b32 s60, v253, 38
	v_readlane_b32 s61, v253, 39
	v_readlane_b32 s62, v253, 40
	v_readlane_b32 s63, v253, 41
	s_waitcnt vmcnt(8)
	v_fma_f32 v128, v76, v92, 0
	v_fmac_f32_e32 v128, v77, v93
	s_waitcnt vmcnt(0)
	v_fma_f32 v129, v108, v124, 0
	v_fmac_f32_e32 v128, v78, v94
	v_fmac_f32_e32 v129, v109, v125
	v_fmac_f32_e32 v128, v79, v95
	v_fmac_f32_e32 v129, v110, v126
	v_fmac_f32_e32 v128, v72, v88
	v_fmac_f32_e32 v129, v111, v127
	v_fmac_f32_e32 v128, v73, v89
	v_fmac_f32_e32 v129, v104, v120
	v_fmac_f32_e32 v128, v74, v90
	v_fmac_f32_e32 v129, v105, v121
	v_fmac_f32_e32 v128, v75, v91
	v_fmac_f32_e32 v129, v106, v122
	v_fmac_f32_e32 v128, v68, v84
	v_fmac_f32_e32 v129, v107, v123
	v_fmac_f32_e32 v128, v69, v85
	v_fmac_f32_e32 v129, v100, v116
	v_fmac_f32_e32 v128, v70, v86
	v_fmac_f32_e32 v129, v101, v117
	v_fmac_f32_e32 v128, v71, v87
	v_fmac_f32_e32 v129, v102, v118
	v_fmac_f32_e32 v128, v64, v80
	v_fmac_f32_e32 v129, v103, v119
	v_fmac_f32_e32 v128, v65, v81
	v_fmac_f32_e32 v129, v96, v112
	v_fmac_f32_e32 v128, v66, v82
	v_fmac_f32_e32 v129, v97, v113
	v_fmac_f32_e32 v128, v67, v83
	global_load_dwordx4 v[64:67], v177, s[4:5] offset:80
	global_load_dwordx4 v[68:71], v177, s[4:5] offset:64
	global_load_dwordx4 v[72:75], v177, s[4:5] offset:112
	global_load_dwordx4 v[76:79], v177, s[4:5] offset:96
	global_load_dwordx4 v[80:83], v177, s[4:5] offset:208
	global_load_dwordx4 v[84:87], v177, s[4:5] offset:192
	global_load_dwordx4 v[88:91], v177, s[4:5] offset:240
	global_load_dwordx4 v[92:95], v177, s[4:5] offset:224
	v_fmac_f32_e32 v129, v98, v114
	v_fmac_f32_e32 v129, v99, v115
	global_load_dwordx4 v[96:99], v177, s[4:5] offset:336
	global_load_dwordx4 v[100:103], v177, s[4:5] offset:320
	global_load_dwordx4 v[104:107], v177, s[4:5] offset:368
	global_load_dwordx4 v[108:111], v177, s[4:5] offset:352
	global_load_dwordx4 v[112:115], v177, s[4:5] offset:464
	global_load_dwordx4 v[116:119], v177, s[4:5] offset:448
	global_load_dwordx4 v[120:123], v177, s[4:5] offset:496
	global_load_dwordx4 v[124:127], v177, s[4:5] offset:480
	s_mov_b32 s4, 0x3fb8aa3b
	s_mov_b32 s5, 0xc2ce8ed0
	s_waitcnt vmcnt(10)
	v_fmac_f32_e32 v128, v68, v84
	v_fmac_f32_e32 v128, v69, v85
	v_fmac_f32_e32 v128, v70, v86
	s_waitcnt vmcnt(2)
	v_fmac_f32_e32 v129, v100, v116
	v_fmac_f32_e32 v129, v101, v117
	v_fmac_f32_e32 v128, v71, v87
	v_fmac_f32_e32 v129, v102, v118
	v_fmac_f32_e32 v128, v64, v80
	v_fmac_f32_e32 v129, v103, v119
	v_fmac_f32_e32 v128, v65, v81
	v_mul_f32_e32 v64, v66, v82
	v_mul_f32_e32 v65, v67, v83
	v_fmac_f32_e32 v129, v96, v112
	v_add_f32_e32 v64, v128, v64
	v_fmac_f32_e32 v129, v97, v113
	v_add_f32_e32 v66, v64, v65
	v_mul_f32_e32 v64, v98, v114
	v_mul_f32_e32 v65, v99, v115
	s_nop 0
	v_add_f32_e32 v64, v129, v64
	v_add_f32_e32 v67, v64, v65
	v_mul_f32_e32 v64, v76, v92
	v_mul_f32_e32 v65, v77, v93
	s_nop 0
	v_add_f32_e32 v64, v66, v64
	v_add_f32_e32 v66, v64, v65
	s_waitcnt vmcnt(0)
	v_mul_f32_e32 v64, v108, v124
	v_mul_f32_e32 v65, v109, v125
	s_nop 0
	v_add_f32_e32 v64, v67, v64
	v_add_f32_e32 v67, v64, v65
	v_mul_f32_e32 v64, v78, v94
	v_mul_f32_e32 v65, v79, v95
	s_nop 0
	v_add_f32_e32 v64, v66, v64
	v_add_f32_e32 v66, v64, v65
	v_mul_f32_e32 v64, v110, v126
	v_mul_f32_e32 v65, v111, v127
	s_nop 0
	v_add_f32_e32 v64, v67, v64
	v_add_f32_e32 v67, v64, v65
	v_mul_f32_e32 v64, v72, v88
	v_mul_f32_e32 v65, v73, v89
	s_nop 0
	v_add_f32_e32 v64, v66, v64
	v_add_f32_e32 v66, v64, v65
	v_mul_f32_e32 v64, v104, v120
	v_mul_f32_e32 v65, v105, v121
	s_nop 0
	v_add_f32_e32 v64, v67, v64
	v_add_f32_e32 v67, v64, v65
	v_mul_f32_e32 v64, v74, v90
	v_mul_f32_e32 v65, v75, v91
	s_nop 0
	v_add_f32_e32 v64, v66, v64
	v_add_f32_e32 v66, v64, v65
	v_mul_f32_e32 v64, v106, v122
	v_mul_f32_e32 v65, v107, v123
	s_nop 0
	v_add_f32_e32 v64, v67, v64
	v_add_f32_e32 v65, v64, v65
	v_cvt_f32_i32_e32 v64, s6
	v_mul_f32_e32 v64, 0xbe99999a, v64
	v_mul_f32_e32 v67, 0x3fb8aa3b, v64
	v_fma_f32 v68, v64, s4, -v67
	v_rndne_f32_e32 v69, v67
	v_fmac_f32_e32 v68, 0x32a5705f, v64
	v_sub_f32_e32 v67, v67, v69
	v_add_f32_e32 v67, v67, v68
	v_exp_f32_e32 v67, v67
	v_cvt_i32_f32_e32 v68, v69
	v_cmp_ngt_f32_e32 vcc, s5, v64
	v_ldexp_f32 v67, v67, v68
	s_nop 0
	v_cndmask_b32_e32 v67, 0, v67, vcc
	v_cmp_nlt_f32_e32 vcc, s7, v64
	s_nop 1
	v_cndmask_b32_e32 v64, v236, v67, vcc
	v_mul_f32_e32 v67, 0x3fb8aa3b, v66
	v_fma_f32 v68, v66, s4, -v67
	v_rndne_f32_e32 v69, v67
	v_fmac_f32_e32 v68, 0x32a5705f, v66
	v_sub_f32_e32 v67, v67, v69
	v_add_f32_e32 v67, v67, v68
	v_exp_f32_e32 v67, v67
	v_cvt_i32_f32_e32 v68, v69
	v_cmp_ngt_f32_e32 vcc, s5, v66
	v_fmamk_f32 v64, v64, 0xbf19999a, v223
	v_ldexp_f32 v67, v67, v68
	v_cndmask_b32_e32 v67, 0, v67, vcc
	v_cmp_nlt_f32_e32 vcc, s7, v66
	s_nop 1
	v_cndmask_b32_e32 v66, v236, v67, vcc
	v_mul_f32_e32 v67, 0x3fb8aa3b, v65
	v_fma_f32 v68, v65, s4, -v67
	v_rndne_f32_e32 v69, v67
	v_fmac_f32_e32 v68, 0x32a5705f, v65
	v_sub_f32_e32 v67, v67, v69
	v_add_f32_e32 v67, v67, v68
	v_exp_f32_e32 v67, v67
	v_cvt_i32_f32_e32 v68, v69
	v_cmp_ngt_f32_e32 vcc, s5, v65
	v_ldexp_f32 v67, v67, v68
	s_nop 0
	v_cndmask_b32_e32 v67, 0, v67, vcc
	v_cmp_nlt_f32_e32 vcc, s7, v65
	s_nop 1
	v_cndmask_b32_e32 v65, v236, v67, vcc
	v_sub_f32_e32 v66, v66, v65
	ds_bpermute_b32 v65, v192, v163
	ds_bpermute_b32 v67, v192, v162
	s_waitcnt lgkmcnt(1)
	v_add_f32_e32 v68, v163, v65
	v_mov_b32_e32 v65, v162
	s_waitcnt lgkmcnt(0)
	v_add_f32_e32 v66, v64, v66
	v_add_f32_e32 v67, v65, v67
	v_div_scale_f32 v65, s[4:5], v68, v68, 1.0
	v_rcp_f32_e32 v69, v65
	s_nop 0
	v_fma_f32 v70, -v65, v69, 1.0
	v_fmac_f32_e32 v69, v70, v69
	v_div_scale_f32 v70, vcc, 1.0, v68, 1.0
	v_mul_f32_e32 v71, v70, v69
	v_fma_f32 v72, -v65, v71, v70
	v_fmac_f32_e32 v71, v72, v69
	v_fma_f32 v65, -v65, v71, v70
	v_div_fmas_f32 v65, v65, v69, v71
	v_div_fixup_f32 v68, v65, v68, 1.0
	v_div_scale_f32 v65, s[4:5], v67, v67, v66
	v_rcp_f32_e32 v69, v65
	s_lshl_b32 s4, s6, 6
	s_ashr_i32 s5, s4, 31
	s_lshl_b64 s[4:5], s[4:5], 2
	v_fma_f32 v70, -v65, v69, 1.0
	v_fmac_f32_e32 v69, v70, v69
	v_div_scale_f32 v70, vcc, v66, v67, v66
	v_mul_f32_e32 v71, v70, v69
	v_fma_f32 v72, -v65, v71, v70
	v_fmac_f32_e32 v71, v72, v69
	v_fma_f32 v65, -v65, v71, v70
	v_div_fmas_f32 v65, v65, v69, v71
	v_div_fixup_f32 v66, v65, v67, v66
	v_mul_f32_e32 v70, v32, v66
	v_mul_f32_e32 v71, v33, v66
	s_add_u32 s4, s54, s4
	v_mul_f32_e32 v74, v36, v66
	v_mul_f32_e32 v75, v37, v66
	v_mul_f32_e32 v32, v46, v66
	v_mul_f32_e32 v33, v47, v66
	v_fma_f32 v46, v48, v68, -v70
	v_fma_f32 v47, v49, v68, -v71
	v_mul_f32_e32 v48, v0, v66
	v_mul_f32_e32 v49, v1, v66
	v_mul_f32_e32 v12, v12, v66
	v_mul_f32_e32 v13, v13, v66
	v_mul_f32_e32 v0, v10, v66
	v_mul_f32_e32 v1, v11, v66
	v_mul_f32_e32 v6, v6, v66
	v_mul_f32_e32 v7, v7, v66
	s_addc_u32 s5, s55, s5
	v_mul_f32_e32 v36, v42, v66
	v_mul_f32_e32 v37, v43, v66
	v_fma_f32 v42, v52, v68, -v74
	v_fma_f32 v43, v53, v68, -v75
	v_mul_f32_e32 v52, v4, v66
	v_mul_f32_e32 v53, v5, v66
	v_mul_f32_e32 v4, v14, v66
	v_mul_f32_e32 v5, v15, v66
	v_fma_f32 v14, v22, v68, -v6
	v_fma_f32 v15, v23, v68, -v7
	v_fma_f32 v0, v26, v68, -v0
	v_fma_f32 v1, v27, v68, -v1
	v_fma_f32 v6, v28, v68, -v12
	v_fma_f32 v7, v29, v68, -v13
	global_load_dwordx4 v[26:29], v176, s[4:5] offset:64
	v_mul_f32_e32 v76, v38, v66
	v_mul_f32_e32 v77, v39, v66
	v_mul_f32_e32 v72, v34, v66
	v_mul_f32_e32 v73, v35, v66
	v_mul_f32_e32 v38, v40, v66
	v_mul_f32_e32 v39, v41, v66
	v_fma_f32 v40, v54, v68, -v76
	v_fma_f32 v41, v55, v68, -v77
	v_mul_f32_e32 v54, v47, v47
	v_mul_f32_e32 v34, v44, v66
	v_mul_f32_e32 v35, v45, v66
	v_fma_f32 v44, v50, v68, -v72
	v_fma_f32 v45, v51, v68, -v73
	v_fmac_f32_e32 v54, v46, v46
	v_fmac_f32_e32 v54, v44, v44
	v_fmac_f32_e32 v54, v45, v45
	v_fmac_f32_e32 v54, v42, v42
	v_fmac_f32_e32 v54, v43, v43
	v_fmac_f32_e32 v54, v40, v40
	v_fma_f32 v38, v56, v68, -v38
	v_fma_f32 v39, v57, v68, -v39
	v_fmac_f32_e32 v54, v41, v41
	v_fmac_f32_e32 v54, v38, v38
	v_fma_f32 v36, v58, v68, -v36
	v_fma_f32 v37, v59, v68, -v37
	v_fmac_f32_e32 v54, v39, v39
	v_fmac_f32_e32 v54, v36, v36
	v_fma_f32 v34, v60, v68, -v34
	v_fma_f32 v35, v61, v68, -v35
	v_fmac_f32_e32 v54, v37, v37
	v_fmac_f32_e32 v54, v34, v34
	v_fma_f32 v32, v62, v68, -v32
	v_fma_f32 v33, v63, v68, -v33
	v_fmac_f32_e32 v54, v35, v35
	v_fmac_f32_e32 v54, v32, v32
	v_mul_f32_e32 v50, v2, v66
	v_mul_f32_e32 v51, v3, v66
	v_mul_f32_e32 v2, v8, v66
	v_mul_f32_e32 v3, v9, v66
	v_fmac_f32_e32 v54, v33, v33
	v_fma_f32 v2, v24, v68, -v2
	v_fma_f32 v3, v25, v68, -v3
	v_fma_f32 v24, v16, v68, -v48
	v_fma_f32 v25, v17, v68, -v49
	v_fma_f32 v22, v18, v68, -v50
	v_fma_f32 v23, v19, v68, -v51
	v_fmac_f32_e32 v54, v24, v24
	v_fmac_f32_e32 v54, v25, v25
	v_fmac_f32_e32 v54, v22, v22
	v_fma_f32 v20, v20, v68, -v52
	v_fma_f32 v21, v21, v68, -v53
	v_fmac_f32_e32 v54, v23, v23
	v_fmac_f32_e32 v54, v20, v20
	v_fmac_f32_e32 v54, v21, v21
	v_mul_f32_e32 v18, v14, v14
	v_mul_f32_e32 v19, v15, v15
	v_mul_f32_e32 v16, v2, v2
	v_mul_f32_e32 v17, v3, v3
	v_add_f32_e32 v18, v18, v54
	v_add_f32_e32 v18, v19, v18
	v_add_f32_e32 v16, v16, v18
	v_mul_f32_e32 v12, v0, v0
	v_mul_f32_e32 v13, v1, v1
	v_add_f32_e32 v16, v17, v16
	v_add_f32_e32 v12, v12, v16
	v_mul_f32_e32 v10, v6, v6
	v_mul_f32_e32 v11, v7, v7
	v_add_f32_e32 v12, v13, v12
	v_fma_f32 v4, v30, v68, -v4
	v_fma_f32 v5, v31, v68, -v5
	v_add_f32_e32 v10, v10, v12
	v_mul_f32_e32 v8, v4, v4
	v_mul_f32_e32 v9, v5, v5
	v_add_f32_e32 v10, v11, v10
	v_add_f32_e32 v8, v8, v10
	v_add_f32_e32 v8, v9, v8
	ds_bpermute_b32 v9, v192, v8
	global_load_dwordx4 v[10:13], v176, s[4:5]
	global_load_dwordx4 v[16:19], v176, s[4:5] offset:32
	s_waitcnt lgkmcnt(0)
	v_add_f32_e32 v8, v8, v9
	v_fmamk_f32 v8, v8, 0x3c800000, v178
	v_cmp_gt_f32_e32 vcc, s44, v8
	v_mul_f32_e32 v9, 0x4b800000, v8
	s_nop 0
	v_cndmask_b32_e32 v8, v8, v9, vcc
	v_rsq_f32_e32 v8, v8
	s_nop 0
	v_mul_f32_e32 v9, 0x45800000, v8
	v_cndmask_b32_e32 v8, v8, v9, vcc
	v_sub_f32_e32 v9, 1.0, v64
	v_mul_f32_e32 v8, v9, v8
	s_waitcnt vmcnt(2)
	v_mul_f32_e32 v26, v26, v8
	v_mul_f32_e32 v27, v27, v8
	v_mul_f32_e32 v28, v28, v8
	v_mul_f32_e32 v29, v29, v8
	v_mul_f32_e32 v26, v38, v26
	v_mul_f32_e32 v27, v39, v27
	v_mul_f32_e32 v28, v36, v28
	v_mul_f32_e32 v29, v37, v29
	global_load_dwordx4 v[36:39], v176, s[4:5] offset:96
	s_waitcnt vmcnt(2)
	v_mul_f32_e32 v10, v10, v8
	v_mul_f32_e32 v11, v11, v8
	v_mul_f32_e32 v12, v12, v8
	v_mul_f32_e32 v13, v13, v8
	v_mul_f32_e32 v10, v46, v10
	v_mul_f32_e32 v11, v47, v11
	v_mul_f32_e32 v12, v44, v12
	v_mul_f32_e32 v13, v45, v13
	s_waitcnt vmcnt(1)
	v_mul_f32_e32 v16, v16, v8
	v_mul_f32_e32 v17, v17, v8
	v_mul_f32_e32 v18, v18, v8
	v_mul_f32_e32 v19, v19, v8
	v_mul_f32_e32 v16, v42, v16
	v_mul_f32_e32 v17, v43, v17
	v_mul_f32_e32 v18, v40, v18
	v_mul_f32_e32 v19, v41, v19
	s_waitcnt vmcnt(0)
	v_mul_f32_e32 v30, v36, v8
	v_mul_f32_e32 v31, v37, v8
	s_nop 0
	v_mul_f32_e32 v30, v34, v30
	v_mul_f32_e32 v31, v35, v31
	v_mul_f32_e32 v34, v38, v8
	v_mul_f32_e32 v35, v39, v8
	s_nop 0
	v_mul_f32_e32 v32, v32, v34
	v_mul_f32_e32 v33, v33, v35
	global_load_dwordx4 v[34:37], v176, s[4:5] offset:128
	s_waitcnt vmcnt(0)
	v_mul_f32_e32 v34, v34, v8
	v_mul_f32_e32 v35, v35, v8
	s_nop 0
	v_mul_f32_e32 v24, v24, v34
	v_mul_f32_e32 v25, v25, v35
	v_mul_f32_e32 v34, v36, v8
	v_mul_f32_e32 v35, v37, v8
	s_nop 0
	v_mul_f32_e32 v22, v22, v34
	v_mul_f32_e32 v23, v23, v35
	global_load_dwordx4 v[34:37], v176, s[4:5] offset:160
	s_waitcnt vmcnt(0)
	v_mul_f32_e32 v34, v34, v8
	v_mul_f32_e32 v35, v35, v8
	s_nop 0
	v_mul_f32_e32 v20, v20, v34
	v_mul_f32_e32 v21, v21, v35
	v_mul_f32_e32 v34, v36, v8
	v_mul_f32_e32 v35, v37, v8
	s_nop 0
	v_mul_f32_e32 v14, v14, v34
	v_mul_f32_e32 v15, v15, v35
	global_load_dwordx4 v[34:37], v176, s[4:5] offset:192
	s_waitcnt vmcnt(0)
	v_mul_f32_e32 v34, v34, v8
	v_mul_f32_e32 v35, v35, v8
	s_nop 0
	v_mul_f32_e32 v34, v2, v34
	v_mul_f32_e32 v35, v3, v35
	v_mul_f32_e32 v2, v36, v8
	v_mul_f32_e32 v3, v37, v8
	s_nop 0
	v_mul_f32_e32 v36, v0, v2
	v_mul_f32_e32 v37, v1, v3
	global_load_dwordx4 v[0:3], v176, s[4:5] offset:224
	v_lshlrev_b32_e32 v176, 3, v191
	s_waitcnt vmcnt(0)
	v_mul_f32_e32 v0, v0, v8
	v_mul_f32_e32 v1, v1, v8
	v_mul_f32_e32 v2, v2, v8
	v_mul_f32_e32 v3, v3, v8
	v_mul_f32_e32 v0, v6, v0
	v_mul_f32_e32 v1, v7, v1
	v_mul_f32_e32 v2, v4, v2
	v_mul_f32_e32 v3, v5, v3
	v_lshl_add_u64 v[4:5], v[160:161], 0, v[176:177]
	v_cvt_pk_bf16_f32 v6, v10, v11
	v_cvt_pk_bf16_f32 v7, v12, v13
	global_store_dwordx2 v[4:5], v[6:7], off offset:1024
	v_cvt_pk_bf16_f32 v6, v16, v17
	v_cvt_pk_bf16_f32 v7, v18, v19
	global_store_dwordx2 v[4:5], v[6:7], off offset:1040
	v_cvt_pk_bf16_f32 v6, v26, v27
	v_cvt_pk_bf16_f32 v7, v28, v29
	global_store_dwordx2 v[4:5], v[6:7], off offset:1056
	v_cvt_pk_bf16_f32 v6, v30, v31
	v_cvt_pk_bf16_f32 v7, v32, v33
	global_store_dwordx2 v[4:5], v[6:7], off offset:1072
	v_cvt_pk_bf16_f32 v6, v24, v25
	v_cvt_pk_bf16_f32 v7, v22, v23
	global_store_dwordx2 v[4:5], v[6:7], off offset:1088
	v_cvt_pk_bf16_f32 v6, v20, v21
	v_cvt_pk_bf16_f32 v7, v14, v15
	global_store_dwordx2 v[4:5], v[6:7], off offset:1104
	v_cvt_pk_bf16_f32 v6, v34, v35
	v_cvt_pk_bf16_f32 v7, v36, v37
	v_cvt_pk_bf16_f32 v0, v0, v1
	v_cvt_pk_bf16_f32 v1, v2, v3
	global_store_dwordx2 v[4:5], v[6:7], off offset:1120
	global_store_dwordx2 v[4:5], v[0:1], off offset:1136

.LBB0_388:
	v_add_f32_e32 v64, 0, v199
	v_add_f32_e32 v64, v200, v64
	v_add_f32_e32 v64, v201, v64
	v_add_f32_e32 v64, v202, v64
	v_add_f32_e32 v64, v203, v64
	v_add_f32_e32 v64, v204, v64
	v_add_f32_e32 v64, v205, v64
	v_add_f32_e32 v64, v206, v64
	v_add_f32_e32 v64, v207, v64
	v_add_f32_e32 v64, v208, v64
	v_add_f32_e32 v64, v209, v64
	v_add_f32_e32 v64, v210, v64
	v_add_f32_e32 v64, v211, v64
	v_add_f32_e32 v64, v212, v64
	v_add_f32_e32 v64, v214, v64
	v_add_f32_e32 v64, v215, v64
	v_add_f32_e32 v64, v216, v64
	v_add_f32_e32 v64, v217, v64
	v_add_f32_e32 v64, v218, v64
	v_add_f32_e32 v64, v219, v64
	v_add_f32_e32 v64, v237, v64
	v_add_f32_e32 v65, v238, v64
	v_add_f32_e32 v64, 0, v97
	v_add_f32_e32 v64, v81, v64
	v_add_f32_e32 v64, v82, v64
	v_add_f32_e32 v64, v83, v64
	v_add_f32_e32 v64, v84, v64
	v_add_f32_e32 v64, v85, v64
	v_add_f32_e32 v64, v86, v64
	v_add_f32_e32 v64, v87, v64
	v_add_f32_e32 v64, v88, v64
	v_add_f32_e32 v64, v89, v64
	v_add_f32_e32 v64, v90, v64
	v_add_f32_e32 v64, v91, v64
	v_add_f32_e32 v64, v92, v64
	v_add_f32_e32 v64, v93, v64
	v_add_f32_e32 v64, v94, v64
	v_add_f32_e32 v64, v95, v64
	v_add_f32_e32 v64, v98, v64
	v_add_f32_e32 v64, v99, v64
	v_add_f32_e32 v64, v100, v64
	v_add_f32_e32 v64, v101, v64
	v_add_f32_e32 v64, v102, v64
	v_add_f32_e32 v64, v103, v64
	v_add_f32_e32 v64, v190, v64
	v_add_f32_e32 v65, v191, v65
	v_mov_b32_e32 v81, v176
	v_add_f32_e32 v64, v188, v64
	v_add_f32_e32 v65, v189, v65
	s_add_i32 s9, s9, 64
	v_add_f32_e32 v64, v126, v64
	v_add_f32_e32 v65, v127, v65
	s_cmp_lg_u32 s8, s10
	v_add_f32_e32 v64, v124, v64
	v_add_f32_e32 v65, v125, v65
	v_mov_b32_e32 v188, v96
	v_add_f32_e32 v64, v122, v64
	v_add_f32_e32 v65, v123, v65
	v_mov_b32_e32 v176, v198
	v_add_f32_e32 v64, v120, v64
	v_add_f32_e32 v65, v121, v65
	s_mov_b32 s11, s10
	v_add_f32_e32 v64, v118, v64
	v_add_f32_e32 v65, v119, v65
	s_waitcnt lgkmcnt(0)
	v_add_f32_e32 v64, v116, v64
	v_add_f32_e32 v65, v117, v65
	s_barrier
	v_add_f32_e32 v64, v114, v64
	v_add_f32_e32 v65, v115, v65
	s_nop 0
	v_add_f32_e32 v64, v112, v64
	v_add_f32_e32 v65, v113, v65
	s_nop 0
	v_fma_f32 v186, v186, v80, v64
	v_fma_f32 v187, v187, v81, v65
	s_cbranch_scc0 .LBB0_393

.LBB0_391:
	s_bitcmp1_b32 s11, 0
	s_cselect_b32 s11, 0x4800, 0
	v_add_u32_e32 v190, s11, v197
	v_add_u32_e32 v189, v190, v195
	ds_read_b128 v[64:67], v189
	ds_read_b128 v[68:71], v189 offset:32
	s_waitcnt lgkmcnt(1)
	v_mfma_f32_32x32x16_bf16 v[112:127], v[64:67], v[128:131], 0
	ds_read_b128 v[198:201], v189 offset:4640
	v_mfma_f32_32x32x16_bf16 v[80:95], v[64:67], v[144:147], 0
	ds_read_b128 v[64:67], v189 offset:64
	s_waitcnt lgkmcnt(2)
	v_mfma_f32_32x32x16_bf16 v[112:127], v[68:71], v[132:135], v[112:127]
	v_mfma_f32_32x32x16_bf16 v[80:95], v[68:71], v[148:151], v[80:95]
	s_waitcnt lgkmcnt(0)
	v_mfma_f32_32x32x16_bf16 v[112:127], v[64:67], v[136:139], v[112:127]
	v_mfma_f32_32x32x16_bf16 v[80:95], v[64:67], v[152:155], v[80:95]
	ds_read_b128 v[64:67], v189 offset:96
	s_waitcnt lgkmcnt(0)
	v_mfma_f32_32x32x16_bf16 v[112:127], v[64:67], v[140:143], v[112:127]
	v_mfma_f32_32x32x16_bf16 v[80:95], v[64:67], v[156:159], v[80:95]
	ds_read_b128 v[64:67], v189 offset:4608
	s_waitcnt lgkmcnt(0)
	v_mfma_f32_32x32x16_bf16 v[96:111], v[64:67], v[128:131], 0
	v_mfma_f32_32x32x16_bf16 v[64:79], v[64:67], v[144:147], 0
	v_mfma_f32_32x32x16_bf16 v[96:111], v[198:201], v[132:135], v[96:111]
	v_mfma_f32_32x32x16_bf16 v[64:79], v[198:201], v[148:151], v[64:79]
	ds_read_b128 v[198:201], v189 offset:4672
	s_waitcnt lgkmcnt(0)
	v_mfma_f32_32x32x16_bf16 v[96:111], v[198:201], v[136:139], v[96:111]
	v_mfma_f32_32x32x16_bf16 v[64:79], v[198:201], v[152:155], v[64:79]
	ds_read_b128 v[198:201], v189 offset:4704
	s_waitcnt lgkmcnt(0)
	v_mfma_f32_32x32x16_bf16 v[96:111], v[198:201], v[140:143], v[96:111]
	v_mfma_f32_32x32x16_bf16 v[64:79], v[198:201], v[156:159], v[64:79]
	v_max_f32_e32 v189, v113, v113
	v_max_f32_e32 v191, v112, v112
	v_max_f32_e32 v189, v191, v189
	v_max3_f32 v189, v189, v114, v115
	v_max3_f32 v189, v189, v116, v117
	v_max3_f32 v189, v189, v118, v119
	v_max3_f32 v189, v189, v120, v121
	v_max3_f32 v189, v189, v122, v123
	v_max3_f32 v189, v189, v124, v125
	v_max3_f32 v189, v189, v126, v127
	s_nop 0
	v_max3_f32 v189, v189, v96, v97
	v_max3_f32 v189, v189, v98, v99
	v_max3_f32 v189, v189, v100, v101
	v_max3_f32 v189, v189, v102, v103
	v_max3_f32 v189, v189, v104, v105
	v_max3_f32 v189, v189, v106, v107
	v_max3_f32 v189, v189, v108, v109
	v_max3_f32 v189, v189, v110, v111
	ds_bpermute_b32 v191, v193, v189
	v_add_u32_e32 v239, v190, v196
	ds_read_b128 v[240:243], v239 offset:9216
	ds_read_b128 v[244:247], v239 offset:9248
	s_waitcnt lgkmcnt(2)
	v_max3_f32 v198, v176, v189, v191
	v_sub_f32_e32 v112, v112, v198
	v_exp_f32_e32 v199, v112
	v_sub_f32_e32 v112, v113, v198
	v_exp_f32_e32 v200, v112
	v_sub_f32_e32 v112, v114, v198
	v_exp_f32_e32 v201, v112
	v_sub_f32_e32 v112, v115, v198
	v_exp_f32_e32 v202, v112
	v_sub_f32_e32 v112, v116, v198
	v_exp_f32_e32 v203, v112
	v_sub_f32_e32 v112, v117, v198
	v_exp_f32_e32 v204, v112
	v_sub_f32_e32 v112, v118, v198
	v_sub_f32_e32 v96, v96, v198
	v_exp_f32_e32 v205, v112
	v_sub_f32_e32 v112, v119, v198
	v_exp_f32_e32 v216, v96
	v_sub_f32_e32 v96, v97, v198
	v_exp_f32_e32 v206, v112
	v_sub_f32_e32 v112, v120, v198
	v_exp_f32_e32 v217, v96
	v_sub_f32_e32 v96, v98, v198
	v_exp_f32_e32 v207, v112
	v_sub_f32_e32 v112, v121, v198
	v_exp_f32_e32 v218, v96
	v_sub_f32_e32 v96, v99, v198
	v_exp_f32_e32 v208, v112
	v_sub_f32_e32 v112, v122, v198
	v_exp_f32_e32 v219, v96
	v_sub_f32_e32 v96, v100, v198
	v_exp_f32_e32 v209, v112
	v_sub_f32_e32 v112, v123, v198
	v_exp_f32_e32 v237, v96
	v_sub_f32_e32 v96, v101, v198
	v_exp_f32_e32 v210, v112
	v_sub_f32_e32 v112, v124, v198
	v_exp_f32_e32 v238, v96
	v_sub_f32_e32 v96, v102, v198
	v_exp_f32_e32 v211, v112
	v_sub_f32_e32 v112, v125, v198
	v_exp_f32_e32 v191, v96
	v_sub_f32_e32 v96, v103, v198
	v_exp_f32_e32 v212, v112
	v_sub_f32_e32 v112, v126, v198
	v_exp_f32_e32 v189, v96
	v_sub_f32_e32 v96, v104, v198
	v_exp_f32_e32 v214, v112
	v_sub_f32_e32 v112, v127, v198
	v_exp_f32_e32 v127, v96
	v_sub_f32_e32 v96, v105, v198
	v_sub_f32_e32 v176, v176, v198
	v_exp_f32_e32 v125, v96
	v_sub_f32_e32 v96, v106, v198
	v_exp_f32_e32 v123, v96
	v_sub_f32_e32 v96, v107, v198
	v_exp_f32_e32 v176, v176
	v_exp_f32_e32 v121, v96
	v_sub_f32_e32 v96, v108, v198
	v_exp_f32_e32 v119, v96
	v_sub_f32_e32 v96, v109, v198
	v_exp_f32_e32 v117, v96
	v_sub_f32_e32 v96, v110, v198
	v_exp_f32_e32 v115, v96
	v_sub_f32_e32 v96, v111, v198
	v_mul_f32_e32 v62, v62, v176
	v_mul_f32_e32 v63, v63, v176
	v_mul_f32_e32 v60, v60, v176
	v_mul_f32_e32 v61, v61, v176
	v_mul_f32_e32 v58, v58, v176
	v_mul_f32_e32 v59, v59, v176
	v_mul_f32_e32 v56, v56, v176
	v_mul_f32_e32 v57, v57, v176
	v_mul_f32_e32 v54, v54, v176
	v_mul_f32_e32 v55, v55, v176
	v_mul_f32_e32 v52, v52, v176
	v_mul_f32_e32 v53, v53, v176
	v_mul_f32_e32 v50, v50, v176
	v_mul_f32_e32 v51, v51, v176
	v_mul_f32_e32 v48, v48, v176
	v_mul_f32_e32 v49, v49, v176
	v_cvt_pk_bf16_f32 v108, v199, v200
	v_cvt_pk_bf16_f32 v109, v201, v202
	v_cvt_pk_bf16_f32 v110, v203, v204
	v_cvt_pk_bf16_f32 v111, v205, v206
	v_exp_f32_e32 v215, v112
	v_cvt_pk_bf16_f32 v100, v207, v208
	s_waitcnt lgkmcnt(1)
	v_mfma_f32_32x32x16_bf16 v[48:63], v[240:243], v[108:111], v[48:63]
	v_cvt_pk_bf16_f32 v101, v209, v210
	v_cvt_pk_bf16_f32 v102, v211, v212
	v_cvt_pk_bf16_f32 v103, v214, v215
	ds_read_b128 v[240:243], v239 offset:9280
	v_cvt_pk_bf16_f32 v104, v216, v217
	v_cvt_pk_bf16_f32 v105, v218, v219
	v_cvt_pk_bf16_f32 v106, v237, v238
	s_waitcnt lgkmcnt(1)
	v_mfma_f32_32x32x16_bf16 v[48:63], v[244:247], v[100:103], v[48:63]
	v_cvt_pk_bf16_f32 v107, v191, v189
	v_exp_f32_e32 v113, v96
	v_cvt_pk_bf16_f32 v96, v127, v125
	v_cvt_pk_bf16_f32 v97, v123, v121
	v_cvt_pk_bf16_f32 v98, v119, v117
	v_cvt_pk_bf16_f32 v99, v115, v113
	v_mul_f32_e32 v46, v46, v176
	v_mul_f32_e32 v47, v47, v176
	s_waitcnt lgkmcnt(0)
	v_mfma_f32_32x32x16_bf16 v[48:63], v[240:243], v[104:107], v[48:63]
	ds_read_b128 v[240:243], v239 offset:9312
	v_mul_f32_e64 v44, v44, v176
	v_mul_f32_e64 v45, v45, v176
	v_mul_f32_e64 v42, v42, v176
	v_mul_f32_e64 v43, v43, v176
	v_mul_f32_e32 v40, v40, v176
	v_mul_f32_e32 v41, v41, v176
	v_mul_f32_e32 v38, v38, v176
	v_mul_f32_e32 v39, v39, v176
	v_mul_f32_e32 v36, v36, v176
	v_mul_f32_e32 v37, v37, v176
	v_mul_f32_e32 v34, v34, v176
	v_mul_f32_e32 v35, v35, v176
	s_waitcnt lgkmcnt(0)
	v_mfma_f32_32x32x16_bf16 v[48:63], v[240:243], v[96:99], v[48:63]
	ds_read_b128 v[240:243], v239 offset:13824
	v_mul_f32_e64 v32, v32, v176
	v_mul_f32_e64 v33, v33, v176
	s_waitcnt lgkmcnt(0)
	s_nop 0
	v_mfma_f32_32x32x16_bf16 v[32:47], v[240:243], v[108:111], v[32:47]
	ds_read_b128 v[108:111], v239 offset:13856
	s_waitcnt lgkmcnt(0)
	v_mfma_f32_32x32x16_bf16 v[32:47], v[108:111], v[100:103], v[32:47]
	ds_read_b128 v[100:103], v239 offset:13888
	s_waitcnt lgkmcnt(0)
	v_mfma_f32_32x32x16_bf16 v[32:47], v[100:103], v[104:107], v[32:47]
	ds_read_b128 v[100:103], v239 offset:13920
	s_waitcnt lgkmcnt(0)
	v_mfma_f32_32x32x16_bf16 v[32:47], v[100:103], v[96:99], v[32:47]
	v_max_f32_e32 v96, v81, v81
	v_max_f32_e32 v97, v80, v80
	v_max_f32_e32 v96, v97, v96
	v_max3_f32 v96, v96, v82, v83
	v_max3_f32 v96, v96, v84, v85
	v_max3_f32 v96, v96, v86, v87
	v_max3_f32 v96, v96, v88, v89
	v_max3_f32 v96, v96, v90, v91
	v_max3_f32 v96, v96, v92, v93
	v_max3_f32 v96, v96, v94, v95
	v_max3_f32 v96, v96, v64, v65
	v_max3_f32 v96, v96, v66, v67
	v_max3_f32 v96, v96, v68, v69
	v_max3_f32 v96, v96, v70, v71
	v_max3_f32 v96, v96, v72, v73
	v_max3_f32 v96, v96, v74, v75
	v_max3_f32 v96, v96, v76, v77
	v_max3_f32 v96, v96, v78, v79
	ds_bpermute_b32 v97, v193, v96
	s_waitcnt lgkmcnt(0)
	v_max3_f32 v96, v188, v96, v97
	v_sub_f32_e32 v80, v80, v96
	v_exp_f32_e32 v97, v80
	v_sub_f32_e32 v80, v81, v96
	v_exp_f32_e32 v81, v80
	v_sub_f32_e32 v80, v82, v96
	v_exp_f32_e32 v82, v80
	v_sub_f32_e32 v80, v83, v96
	v_exp_f32_e32 v83, v80
	v_sub_f32_e32 v80, v84, v96
	v_exp_f32_e32 v84, v80
	v_sub_f32_e32 v80, v85, v96
	v_sub_f32_e32 v64, v64, v96
	v_exp_f32_e32 v85, v80
	v_sub_f32_e32 v80, v86, v96
	v_exp_f32_e32 v98, v64
	v_sub_f32_e32 v64, v65, v96
	v_exp_f32_e32 v86, v80
	v_sub_f32_e32 v80, v87, v96
	v_exp_f32_e32 v99, v64
	v_sub_f32_e32 v64, v66, v96
	v_exp_f32_e32 v87, v80
	v_sub_f32_e32 v80, v88, v96
	v_exp_f32_e32 v100, v64
	v_sub_f32_e32 v64, v67, v96
	v_exp_f32_e32 v88, v80
	v_sub_f32_e32 v80, v89, v96
	v_exp_f32_e32 v101, v64
	v_sub_f32_e32 v64, v68, v96
	v_exp_f32_e32 v89, v80
	v_sub_f32_e32 v80, v90, v96
	v_exp_f32_e32 v102, v64
	v_sub_f32_e32 v64, v69, v96
	v_exp_f32_e32 v90, v80
	v_sub_f32_e32 v80, v91, v96
	v_exp_f32_e32 v103, v64
	v_sub_f32_e32 v64, v70, v96
	v_exp_f32_e32 v91, v80
	v_sub_f32_e32 v80, v92, v96
	v_exp_f32_e32 v190, v64
	v_sub_f32_e32 v64, v71, v96
	v_sub_f32_e32 v104, v188, v96
	v_exp_f32_e32 v92, v80
	v_sub_f32_e32 v80, v93, v96
	v_exp_f32_e32 v188, v64
	v_sub_f32_e32 v64, v72, v96
	v_exp_f32_e32 v93, v80
	v_sub_f32_e32 v80, v94, v96
	v_exp_f32_e32 v126, v64
	v_sub_f32_e32 v64, v73, v96
	v_exp_f32_e32 v94, v80
	v_sub_f32_e32 v80, v95, v96
	v_exp_f32_e32 v124, v64
	v_sub_f32_e32 v64, v74, v96
	v_exp_f32_e32 v95, v80
	v_exp_f32_e32 v122, v64
	v_sub_f32_e32 v64, v75, v96
	v_exp_f32_e32 v80, v104
	v_exp_f32_e32 v120, v64
	v_sub_f32_e32 v64, v76, v96
	ds_read_b128 v[104:107], v239 offset:9216
	ds_read_b128 v[108:111], v239 offset:9248
	v_exp_f32_e32 v118, v64
	v_sub_f32_e32 v64, v77, v96
	v_exp_f32_e32 v116, v64
	v_sub_f32_e32 v64, v78, v96
	v_exp_f32_e32 v114, v64
	v_sub_f32_e32 v64, v79, v96
	v_mul_f32_e32 v30, v30, v80
	v_mul_f32_e32 v31, v31, v80
	v_mul_f32_e32 v28, v28, v80
	v_mul_f32_e32 v29, v29, v80
	v_mul_f32_e32 v26, v26, v80
	v_mul_f32_e32 v27, v27, v80
	v_mul_f32_e32 v24, v24, v80
	v_mul_f32_e32 v25, v25, v80
	v_mul_f32_e32 v22, v22, v80
	v_mul_f32_e32 v23, v23, v80
	v_mul_f32_e32 v20, v20, v80
	v_mul_f32_e32 v21, v21, v80
	v_mul_f32_e32 v18, v18, v80
	v_mul_f32_e32 v19, v19, v80
	v_mul_f32_e32 v16, v16, v80
	v_mul_f32_e32 v17, v17, v80
	v_cvt_pk_bf16_f32 v76, v97, v81
	v_cvt_pk_bf16_f32 v77, v82, v83
	v_cvt_pk_bf16_f32 v78, v84, v85
	v_cvt_pk_bf16_f32 v79, v86, v87
	v_cvt_pk_bf16_f32 v68, v88, v89
	v_cvt_pk_bf16_f32 v69, v90, v91
	s_waitcnt lgkmcnt(1)
	v_mfma_f32_32x32x16_bf16 v[16:31], v[104:107], v[76:79], v[16:31]
	v_cvt_pk_bf16_f32 v70, v92, v93
	v_cvt_pk_bf16_f32 v71, v94, v95
	ds_read_b128 v[104:107], v239 offset:9280
	v_cvt_pk_bf16_f32 v72, v98, v99
	v_cvt_pk_bf16_f32 v73, v100, v101
	v_cvt_pk_bf16_f32 v74, v102, v103
	v_cvt_pk_bf16_f32 v75, v190, v188
	s_waitcnt lgkmcnt(1)
	v_mfma_f32_32x32x16_bf16 v[16:31], v[108:111], v[68:71], v[16:31]
	v_exp_f32_e32 v112, v64
	v_cvt_pk_bf16_f32 v64, v126, v124
	v_cvt_pk_bf16_f32 v65, v122, v120
	v_cvt_pk_bf16_f32 v66, v118, v116
	v_cvt_pk_bf16_f32 v67, v114, v112
	v_mul_f32_e32 v14, v14, v80
	v_mul_f32_e32 v15, v15, v80
	v_mul_f32_e32 v12, v12, v80
	v_mul_f32_e32 v13, v13, v80
	s_waitcnt lgkmcnt(0)
	v_mfma_f32_32x32x16_bf16 v[16:31], v[104:107], v[72:75], v[16:31]
	ds_read_b128 v[104:107], v239 offset:9312
	v_mul_f32_e64 v10, v10, v80
	v_mul_f32_e64 v11, v11, v80
	v_mul_f32_e64 v8, v8, v80
	v_mul_f32_e64 v9, v9, v80
	v_mul_f32_e32 v6, v6, v80
	v_mul_f32_e32 v7, v7, v80
	v_mul_f32_e32 v4, v4, v80
	v_mul_f32_e32 v5, v5, v80
	v_mul_f32_e32 v2, v2, v80
	v_mul_f32_e32 v3, v3, v80
	v_mul_f32_e32 v0, v0, v80
	v_mul_f32_e32 v1, v1, v80
	s_waitcnt lgkmcnt(0)
	v_mfma_f32_32x32x16_bf16 v[16:31], v[104:107], v[64:67], v[16:31]
	ds_read_b128 v[104:107], v239 offset:13824
	s_waitcnt lgkmcnt(0)
	v_mfma_f32_32x32x16_bf16 v[0:15], v[104:107], v[76:79], v[0:15]
	ds_read_b128 v[76:79], v239 offset:13856
	s_waitcnt lgkmcnt(0)
	v_mfma_f32_32x32x16_bf16 v[0:15], v[76:79], v[68:71], v[0:15]
	ds_read_b128 v[68:71], v239 offset:13888
	s_waitcnt lgkmcnt(0)
	v_mfma_f32_32x32x16_bf16 v[0:15], v[68:71], v[72:75], v[0:15]
	ds_read_b128 v[68:71], v239 offset:13920
	s_waitcnt lgkmcnt(0)
	v_mfma_f32_32x32x16_bf16 v[0:15], v[68:71], v[64:67], v[0:15]
	s_andn2_b64 vcc, exec, s[6:7]
	s_cbranch_vccnz .LBB0_388
	s_bitcmp1_b32 s10, 0
	s_cselect_b32 s6, 0x4800, 0
	v_add_u32_e32 v64, s6, v194
	s_waitcnt vmcnt(3)
	ds_write_b128 v64, v[160:163]
	s_waitcnt vmcnt(2)
	ds_write_b128 v64, v[164:167] offset:9216
	s_waitcnt vmcnt(1)
	ds_write_b128 v64, v[168:171] offset:4608
	s_waitcnt vmcnt(0)
	ds_write_b128 v64, v[172:175] offset:13824
	s_branch .LBB0_388
.LBB0_393:
	ds_bpermute_b32 v64, v193, v187
	v_lshlrev_b32_e32 v176, 3, v192
	s_waitcnt lgkmcnt(0)
	v_add_f32_e32 v66, v187, v64
	v_div_scale_f32 v67, s[6:7], v66, v66, 1.0
	v_rcp_f32_e32 v68, v67
	v_div_scale_f32 v69, vcc, 1.0, v66, 1.0
	v_lshl_add_u64 v[64:65], s[78:79], 0, v[182:183]
	v_fma_f32 v70, -v67, v68, 1.0
	v_fmac_f32_e32 v68, v70, v68
	v_mul_f32_e32 v70, v69, v68
	v_fma_f32 v71, -v67, v70, v69
	v_fmac_f32_e32 v70, v71, v68
	v_fma_f32 v67, -v67, v70, v69
	v_div_fmas_f32 v67, v67, v68, v70
	v_div_fixup_f32 v66, v67, v66, 1.0
	v_mul_f32_e32 v34, v34, v66
	v_mul_f32_e32 v35, v35, v66
	v_mul_f32_e32 v32, v32, v66
	v_mul_f32_e32 v33, v33, v66
	v_lshl_add_u64 v[64:65], v[64:65], 0, s[4:5]
	v_cvt_pk_bf16_f32 v32, v32, v33
	v_cvt_pk_bf16_f32 v33, v34, v35
	ds_bpermute_b32 v34, v193, v186
	v_mul_f32_e32 v36, v36, v66
	v_mul_f32_e32 v37, v37, v66
	v_lshl_add_u64 v[64:65], v[64:65], 0, v[176:177]
	global_store_dwordx2 v[64:65], v[32:33], off offset:64
	v_cvt_pk_bf16_f32 v32, v36, v37
	s_waitcnt lgkmcnt(0)
	v_add_f32_e32 v34, v186, v34
	v_div_scale_f32 v35, s[6:7], v34, v34, 1.0
	v_rcp_f32_e32 v36, v35
	v_mul_f32_e32 v38, v38, v66
	v_mul_f32_e32 v39, v39, v66
	v_mul_f32_e32 v42, v42, v66
	v_mul_f32_e32 v43, v43, v66
	v_cvt_pk_bf16_f32 v33, v38, v39
	v_fma_f32 v37, -v35, v36, 1.0
	v_fmac_f32_e32 v36, v37, v36
	v_div_scale_f32 v37, vcc, 1.0, v34, 1.0
	v_mul_f32_e32 v38, v37, v36
	v_fma_f32 v39, -v35, v38, v37
	v_mul_f32_e32 v40, v40, v66
	v_mul_f32_e32 v41, v41, v66
	v_fmac_f32_e32 v38, v39, v36
	v_mul_f32_e32 v46, v46, v66
	v_mul_f32_e32 v47, v47, v66
	v_mul_f32_e32 v44, v44, v66
	v_mul_f32_e32 v45, v45, v66
	global_store_dwordx2 v[64:65], v[32:33], off offset:80
	v_cvt_pk_bf16_f32 v32, v40, v41
	v_cvt_pk_bf16_f32 v33, v42, v43
	v_fma_f32 v35, -v35, v38, v37
	global_store_dwordx2 v[64:65], v[32:33], off offset:96
	v_cvt_pk_bf16_f32 v32, v44, v45
	v_cvt_pk_bf16_f32 v33, v46, v47
	v_div_fmas_f32 v35, v35, v36, v38
	global_store_dwordx2 v[64:65], v[32:33], off offset:112
	v_lshl_add_u64 v[32:33], s[78:79], 0, v[180:181]
	v_div_fixup_f32 v34, v35, v34, 1.0
	v_mul_f32_e32 v50, v50, v66
	v_mul_f32_e32 v51, v51, v66
	v_mul_f32_e32 v48, v48, v66
	v_mul_f32_e32 v49, v49, v66
	v_mul_f32_e32 v18, v18, v34
	v_mul_f32_e32 v19, v19, v34
	v_mul_f32_e32 v16, v16, v34
	v_mul_f32_e32 v17, v17, v34
	v_mul_f32_e32 v2, v2, v34
	v_mul_f32_e32 v3, v3, v34
	v_mul_f32_e32 v0, v0, v34
	v_mul_f32_e32 v1, v1, v34
	v_lshl_add_u64 v[32:33], v[32:33], 0, s[4:5]
	v_mul_f32_e32 v54, v54, v66
	v_mul_f32_e32 v55, v55, v66
	v_mul_f32_e32 v52, v52, v66
	v_mul_f32_e32 v53, v53, v66
	v_cvt_pk_bf16_f32 v48, v48, v49
	v_cvt_pk_bf16_f32 v49, v50, v51
	v_mul_f32_e32 v22, v22, v34
	v_mul_f32_e32 v23, v23, v34
	v_mul_f32_e32 v20, v20, v34
	v_mul_f32_e32 v21, v21, v34
	v_mul_f32_e32 v6, v6, v34
	v_mul_f32_e32 v7, v7, v34
	v_mul_f32_e32 v4, v4, v34
	v_mul_f32_e32 v5, v5, v34
	v_lshl_add_u64 v[32:33], v[32:33], 0, v[176:177]
	v_cvt_pk_bf16_f32 v16, v16, v17
	v_cvt_pk_bf16_f32 v17, v18, v19
	v_cvt_pk_bf16_f32 v0, v0, v1
	v_cvt_pk_bf16_f32 v1, v2, v3
	v_mul_f32_e32 v58, v58, v66
	v_mul_f32_e32 v59, v59, v66
	v_mul_f32_e32 v56, v56, v66
	v_mul_f32_e32 v57, v57, v66
	global_store_dwordx2 v[64:65], v[48:49], off
	v_cvt_pk_bf16_f32 v48, v52, v53
	v_cvt_pk_bf16_f32 v49, v54, v55
	v_mul_f32_e32 v26, v26, v34
	v_mul_f32_e32 v27, v27, v34
	v_mul_f32_e32 v24, v24, v34
	v_mul_f32_e32 v25, v25, v34
	v_mul_f32_e32 v10, v10, v34
	v_mul_f32_e32 v11, v11, v34
	v_mul_f32_e32 v8, v8, v34
	v_mul_f32_e32 v9, v9, v34
	global_store_dwordx2 v[32:33], v[16:17], off
	v_cvt_pk_bf16_f32 v16, v20, v21
	v_cvt_pk_bf16_f32 v17, v22, v23
	global_store_dwordx2 v[32:33], v[0:1], off offset:64
	v_cvt_pk_bf16_f32 v0, v4, v5
	v_cvt_pk_bf16_f32 v1, v6, v7
	v_mul_f32_e32 v62, v62, v66
	v_mul_f32_e32 v63, v63, v66
	v_mul_f32_e32 v60, v60, v66
	v_mul_f32_e32 v61, v61, v66
	global_store_dwordx2 v[64:65], v[48:49], off offset:16
	v_cvt_pk_bf16_f32 v48, v56, v57
	v_cvt_pk_bf16_f32 v49, v58, v59
	v_mul_f32_e32 v30, v30, v34
	v_mul_f32_e32 v31, v31, v34
	v_mul_f32_e32 v28, v28, v34
	v_mul_f32_e32 v29, v29, v34
	v_mul_f32_e32 v14, v14, v34
	v_mul_f32_e32 v15, v15, v34
	v_mul_f32_e32 v12, v12, v34
	v_mul_f32_e32 v13, v13, v34
	global_store_dwordx2 v[32:33], v[16:17], off offset:16
	v_cvt_pk_bf16_f32 v16, v24, v25
	v_cvt_pk_bf16_f32 v17, v26, v27
	global_store_dwordx2 v[32:33], v[0:1], off offset:80
	v_cvt_pk_bf16_f32 v0, v8, v9
	v_cvt_pk_bf16_f32 v1, v10, v11
	global_store_dwordx2 v[64:65], v[48:49], off offset:32
	v_cvt_pk_bf16_f32 v48, v60, v61
	v_cvt_pk_bf16_f32 v49, v62, v63
	global_store_dwordx2 v[32:33], v[16:17], off offset:32
	v_cvt_pk_bf16_f32 v16, v28, v29
	v_cvt_pk_bf16_f32 v17, v30, v31
	global_store_dwordx2 v[32:33], v[0:1], off offset:96
	v_cvt_pk_bf16_f32 v0, v12, v13
	v_cvt_pk_bf16_f32 v1, v14, v15
	global_store_dwordx2 v[64:65], v[48:49], off offset:48
	global_store_dwordx2 v[32:33], v[16:17], off offset:48
	global_store_dwordx2 v[32:33], v[0:1], off offset:112

.LBB0_402:
	s_bitcmp1_b32 s10, 0
	s_cselect_b32 s10, 0x4800, 0
	v_add_u32_e32 v249, s10, v245
	v_add_u32_e32 v192, v249, v240
	ds_read_b128 v[64:67], v192
	ds_read_b128 v[68:71], v192 offset:32
	s_waitcnt lgkmcnt(1)
	v_mfma_f32_32x32x16_bf16 v[112:127], v[64:67], v[128:131], 0
	ds_read_b128 v[188:191], v192 offset:4640
	v_mfma_f32_32x32x16_bf16 v[80:95], v[64:67], v[144:147], 0
	ds_read_b128 v[64:67], v192 offset:64
	s_waitcnt lgkmcnt(2)
	v_mfma_f32_32x32x16_bf16 v[112:127], v[68:71], v[132:135], v[112:127]
	v_mfma_f32_32x32x16_bf16 v[80:95], v[68:71], v[148:151], v[80:95]
	s_waitcnt lgkmcnt(0)
	v_mfma_f32_32x32x16_bf16 v[112:127], v[64:67], v[136:139], v[112:127]
	v_mfma_f32_32x32x16_bf16 v[80:95], v[64:67], v[152:155], v[80:95]
	ds_read_b128 v[64:67], v192 offset:96
	s_waitcnt lgkmcnt(0)
	v_mfma_f32_32x32x16_bf16 v[112:127], v[64:67], v[140:143], v[112:127]
	v_mfma_f32_32x32x16_bf16 v[80:95], v[64:67], v[156:159], v[80:95]
	ds_read_b128 v[64:67], v192 offset:4608
	s_waitcnt lgkmcnt(0)
	v_mfma_f32_32x32x16_bf16 v[96:111], v[64:67], v[128:131], 0
	v_mfma_f32_32x32x16_bf16 v[64:79], v[64:67], v[144:147], 0
	v_mfma_f32_32x32x16_bf16 v[96:111], v[188:191], v[132:135], v[96:111]
	v_mfma_f32_32x32x16_bf16 v[64:79], v[188:191], v[148:151], v[64:79]
	ds_read_b128 v[188:191], v192 offset:4672
	s_waitcnt lgkmcnt(0)
	v_mfma_f32_32x32x16_bf16 v[96:111], v[188:191], v[136:139], v[96:111]
	v_mfma_f32_32x32x16_bf16 v[64:79], v[188:191], v[152:155], v[64:79]
	ds_read_b128 v[188:191], v192 offset:4704
	s_waitcnt lgkmcnt(0)
	v_mfma_f32_32x32x16_bf16 v[96:111], v[188:191], v[140:143], v[96:111]
	v_mfma_f32_32x32x16_bf16 v[64:79], v[188:191], v[156:159], v[64:79]
	v_cvt_f32_i32_e32 v212, v247
	s_add_i32 s21, s17, 63
	v_add_u32_e32 v248, s17, v246
	v_cmp_ge_i32_e32 vcc, s21, v181
	s_and_saveexec_b64 s[10:11], vcc
	s_xor_b64 s[10:11], exec, s[10:11]
	s_cbranch_execz .LBB0_408
	v_cmp_le_i32_e32 vcc, s17, v241
	v_mul_f32_e64 v252, -v238, v212
	s_and_saveexec_b64 s[12:13], vcc
	s_xor_b64 s[12:13], exec, s[12:13]
	s_cbranch_execz .LBB0_405
	v_mul_f32_e32 v188, v237, v212
	v_min_f32_e32 v188, v188, v252
	v_exp_f32_e32 v188, v188
	s_mov_b32 s24, -1.0
	s_mov_b32 s25, -2.0
	v_add_f32_e32 v190, s24, v212
	v_add_f32_e32 v191, s25, v212
	v_cmp_ne_u32_e32 vcc, 0, v248
	v_mul_f32_e32 v192, v237, v191
	v_mul_f32_e64 v193, v191, -v238
	v_cndmask_b32_e32 v188, 2.0, v188, vcc
	v_mul_f32_e32 v189, v237, v190
	v_mul_f32_e32 v188, v188, v112
	v_mul_f32_e64 v112, v190, -v238
	v_min_f32_e32 v192, v192, v193
	v_exp_f32_e32 v192, v192
	v_min_f32_e32 v112, v189, v112
	v_exp_f32_e32 v112, v112
	v_cmp_neq_f32_e32 vcc, 0, v191
	s_mov_b32 s24, 0xc0400000
	s_mov_b32 s25, -4.0
	v_cndmask_b32_e32 v191, 2.0, v192, vcc
	v_cmp_neq_f32_e32 vcc, 0, v190
	s_nop 1
	v_cndmask_b32_e32 v190, 2.0, v112, vcc
	v_mov_b32_e32 v112, v113
	v_mov_b32_e32 v113, v114
	v_mul_f32_e32 v112, v190, v112
	v_mul_f32_e32 v113, v191, v113
	v_add_f32_e32 v190, s24, v212
	v_add_f32_e32 v191, s25, v212
	v_mul_f32_e32 v192, v237, v191
	v_mul_f32_e64 v193, v191, -v238
	v_mul_f32_e32 v114, v237, v190
	v_mul_f32_e64 v189, v190, -v238
	v_min_f32_e32 v192, v192, v193
	v_exp_f32_e32 v192, v192
	v_min_f32_e32 v114, v114, v189
	v_exp_f32_e32 v114, v114
	v_cmp_neq_f32_e32 vcc, 0, v191
	s_mov_b32 s24, 0xc0a00000
	s_mov_b32 s25, 0xc0c00000
	v_cndmask_b32_e32 v191, 2.0, v192, vcc
	v_cmp_neq_f32_e32 vcc, 0, v190
	v_mov_b32_e32 v214, v113
	s_nop 0
	v_cndmask_b32_e32 v190, 2.0, v114, vcc
	v_mov_b32_e32 v114, v115
	v_mov_b32_e32 v115, v116
	v_mul_f32_e32 v114, v190, v114
	v_mul_f32_e32 v115, v191, v115
	v_add_f32_e32 v190, s24, v212
	v_add_f32_e32 v191, s25, v212
	v_mul_f32_e32 v192, v237, v191
	v_mul_f32_e64 v193, v191, -v238
	v_mul_f32_e32 v116, v237, v190
	v_mul_f32_e64 v189, v190, -v238
	v_min_f32_e32 v192, v192, v193
	v_exp_f32_e32 v192, v192
	v_min_f32_e32 v116, v116, v189
	v_exp_f32_e32 v116, v116
	v_cmp_neq_f32_e32 vcc, 0, v191
	s_mov_b32 s24, 0xc0e00000
	s_mov_b32 s25, 0xc1800000
	v_cndmask_b32_e32 v191, 2.0, v192, vcc
	v_cmp_neq_f32_e32 vcc, 0, v190
	v_mov_b32_e32 v210, v115
	v_mov_b32_e32 v215, v114
	v_cndmask_b32_e32 v190, 2.0, v116, vcc
	v_mov_b32_e32 v116, v117
	v_mov_b32_e32 v117, v118
	v_mul_f32_e32 v116, v190, v116
	v_mul_f32_e32 v117, v191, v117
	v_add_f32_e32 v190, s24, v212
	v_add_f32_e32 v191, s25, v212
	v_mul_f32_e32 v192, v237, v191
	v_mul_f32_e64 v193, v191, -v238
	v_mul_f32_e32 v118, v237, v190
	v_mul_f32_e64 v189, v190, -v238
	v_min_f32_e32 v192, v192, v193
	v_exp_f32_e32 v192, v192
	v_min_f32_e32 v118, v118, v189
	v_exp_f32_e32 v118, v118
	v_cmp_neq_f32_e32 vcc, 0, v191
	s_mov_b32 s24, 0xc1880000
	s_mov_b32 s25, 0xc1900000
	v_cndmask_b32_e32 v191, 2.0, v192, vcc
	v_cmp_neq_f32_e32 vcc, 0, v190
	v_mov_b32_e32 v206, v117
	v_mov_b32_e32 v211, v116
	v_cndmask_b32_e32 v190, 2.0, v118, vcc
	v_mov_b32_e32 v118, v119
	v_mov_b32_e32 v119, v120
	v_mul_f32_e32 v118, v190, v118
	v_mul_f32_e32 v119, v191, v119
	v_add_f32_e32 v190, s24, v212
	v_add_f32_e32 v191, s25, v212
	v_mul_f32_e32 v192, v237, v191
	v_mul_f32_e64 v193, v191, -v238
	v_mul_f32_e32 v120, v237, v190
	v_mul_f32_e64 v189, v190, -v238
	v_min_f32_e32 v192, v192, v193
	v_exp_f32_e32 v192, v192
	v_min_f32_e32 v120, v120, v189
	v_exp_f32_e32 v120, v120
	v_cmp_neq_f32_e32 vcc, 0, v191
	s_mov_b32 s24, 0xc1980000
	s_mov_b32 s25, 0xc1a00000
	v_cndmask_b32_e32 v191, 2.0, v192, vcc
	v_cmp_neq_f32_e32 vcc, 0, v190
	v_mov_b32_e32 v204, v119
	v_mov_b32_e32 v207, v118
	v_cndmask_b32_e32 v190, 2.0, v120, vcc
	v_mov_b32_e32 v120, v121
	v_mov_b32_e32 v121, v122
	v_mul_f32_e32 v120, v190, v120
	v_mul_f32_e32 v121, v191, v121
	v_add_f32_e32 v190, s24, v212
	v_add_f32_e32 v191, s25, v212
	v_mul_f32_e32 v192, v237, v191
	v_mul_f32_e64 v193, v191, -v238
	v_mul_f32_e32 v122, v237, v190
	v_mul_f32_e64 v189, v190, -v238
	v_min_f32_e32 v192, v192, v193
	v_exp_f32_e32 v192, v192
	v_min_f32_e32 v122, v122, v189
	v_exp_f32_e32 v122, v122
	v_cmp_neq_f32_e32 vcc, 0, v191
	s_mov_b32 s24, 0xc1a80000
	s_mov_b32 s25, 0xc1b00000
	v_cndmask_b32_e32 v191, 2.0, v192, vcc
	v_cmp_neq_f32_e32 vcc, 0, v190
	v_mov_b32_e32 v200, v121
	v_mov_b32_e32 v205, v120
	v_cndmask_b32_e32 v190, 2.0, v122, vcc
	v_mov_b32_e32 v122, v123
	v_mov_b32_e32 v123, v124
	v_mul_f32_e32 v122, v190, v122
	v_mul_f32_e32 v123, v191, v123
	v_add_f32_e32 v190, s24, v212
	v_add_f32_e32 v191, s25, v212
	v_mul_f32_e32 v192, v237, v191
	v_mul_f32_e64 v193, v191, -v238
	v_mul_f32_e32 v124, v237, v190
	v_mul_f32_e64 v189, v190, -v238
	v_min_f32_e32 v192, v192, v193
	v_exp_f32_e32 v192, v192
	v_min_f32_e32 v124, v124, v189
	v_exp_f32_e32 v124, v124
	v_cmp_neq_f32_e32 vcc, 0, v191
	v_add_f32_e32 v189, 0xc1b80000, v212
	s_mov_b32 s24, 0xc2000000
	v_cndmask_b32_e32 v191, 2.0, v192, vcc
	v_cmp_neq_f32_e32 vcc, 0, v190
	v_mul_f32_e64 v192, v189, -v238
	s_mov_b32 s25, 0xc2040000
	v_cndmask_b32_e32 v190, 2.0, v124, vcc
	v_mov_b32_e32 v124, v125
	v_mul_f32_e32 v125, v237, v189
	v_min_f32_e32 v125, v125, v192
	v_exp_f32_e32 v192, v125
	v_cmp_neq_f32_e32 vcc, 0, v189
	v_mov_b32_e32 v125, v126
	v_mul_f32_e32 v124, v190, v124
	v_mul_f32_e32 v125, v191, v125
	v_cndmask_b32_e32 v126, 2.0, v192, vcc
	v_mul_f32_e32 v191, v126, v127
	v_add_f32_e32 v126, s24, v212
	v_add_f32_e32 v127, s25, v212
	v_mul_f32_e32 v192, v237, v127
	v_mul_f32_e64 v193, v127, -v238
	v_mul_f32_e32 v189, v237, v126
	v_mul_f32_e64 v190, v126, -v238
	v_min_f32_e32 v192, v192, v193
	v_exp_f32_e32 v192, v192
	v_min_f32_e32 v189, v189, v190
	v_exp_f32_e32 v189, v189
	v_cmp_neq_f32_e32 vcc, 0, v127
	s_mov_b32 s24, 0xc2080000
	s_mov_b32 s25, 0xc20c0000
	v_cndmask_b32_e32 v127, 2.0, v192, vcc
	v_cmp_neq_f32_e32 vcc, 0, v126
	v_mov_b32_e32 v201, v122
	s_nop 0
	v_cndmask_b32_e32 v126, 2.0, v189, vcc
	v_mul_f32_e32 v192, v126, v96
	v_mul_f32_e32 v193, v127, v97
	v_add_f32_e32 v126, s24, v212
	v_add_f32_e32 v127, s25, v212
	v_mul_f32_e32 v194, v237, v127
	v_mul_f32_e64 v195, v127, -v238
	v_mul_f32_e32 v189, v237, v126
	v_mul_f32_e64 v190, v126, -v238
	v_min_f32_e32 v194, v194, v195
	v_exp_f32_e32 v194, v194
	v_min_f32_e32 v189, v189, v190
	v_exp_f32_e32 v189, v189
	v_cmp_neq_f32_e32 vcc, 0, v127
	s_mov_b32 s24, 0xc2100000
	s_mov_b32 s25, 0xc2140000
	v_cndmask_b32_e32 v127, 2.0, v194, vcc
	v_cmp_neq_f32_e32 vcc, 0, v126
	s_nop 1
	v_cndmask_b32_e32 v126, 2.0, v189, vcc
	v_mul_f32_e32 v194, v126, v98
	v_mul_f32_e32 v195, v127, v99
	v_add_f32_e32 v126, s24, v212
	v_add_f32_e32 v127, s25, v212
	v_mul_f32_e32 v196, v237, v127
	v_mul_f32_e64 v197, v127, -v238
	v_mul_f32_e32 v189, v237, v126
	v_mul_f32_e64 v190, v126, -v238
	v_min_f32_e32 v196, v196, v197
	v_exp_f32_e32 v196, v196
	v_min_f32_e32 v189, v189, v190
	v_exp_f32_e32 v189, v189
	v_cmp_neq_f32_e32 vcc, 0, v127
	s_mov_b32 s24, 0xc2180000
	s_mov_b32 s25, 0xc21c0000
	v_cndmask_b32_e32 v127, 2.0, v196, vcc
	v_cmp_neq_f32_e32 vcc, 0, v126
	s_nop 1
	v_cndmask_b32_e32 v126, 2.0, v189, vcc
	v_mul_f32_e32 v196, v126, v100
	v_mul_f32_e32 v197, v127, v101
	v_add_f32_e32 v126, s24, v212
	v_add_f32_e32 v127, s25, v212
	v_mul_f32_e32 v198, v237, v127
	v_mul_f32_e64 v199, v127, -v238
	v_mul_f32_e32 v189, v237, v126
	v_mul_f32_e64 v190, v126, -v238
	v_min_f32_e32 v198, v198, v199
	v_exp_f32_e32 v198, v198
	v_min_f32_e32 v189, v189, v190
	v_exp_f32_e32 v189, v189
	v_cmp_neq_f32_e32 vcc, 0, v127
	s_mov_b32 s24, 0xc2400000
	s_mov_b32 s25, 0xc2440000
	v_cndmask_b32_e32 v127, 2.0, v198, vcc
	v_cmp_neq_f32_e32 vcc, 0, v126
	s_nop 1
	v_cndmask_b32_e32 v126, 2.0, v189, vcc
	v_mul_f32_e32 v202, v126, v102
	v_mul_f32_e32 v203, v127, v103
	v_add_f32_e32 v126, s24, v212
	v_add_f32_e32 v127, s25, v212
	v_mul_f32_e32 v198, v237, v127
	v_mul_f32_e64 v199, v127, -v238
	v_mul_f32_e32 v189, v237, v126
	v_mul_f32_e64 v190, v126, -v238
	v_min_f32_e32 v198, v198, v199
	v_exp_f32_e32 v198, v198
	v_min_f32_e32 v189, v189, v190
	v_exp_f32_e32 v189, v189
	v_cmp_neq_f32_e32 vcc, 0, v127
	s_mov_b32 s24, 0xc2480000
	s_mov_b32 s25, 0xc24c0000
	v_cndmask_b32_e32 v127, 2.0, v198, vcc
	v_cmp_neq_f32_e32 vcc, 0, v126
	s_nop 1
	v_cndmask_b32_e32 v126, 2.0, v189, vcc
	v_mul_f32_e32 v208, v126, v104
	v_mul_f32_e32 v209, v127, v105
	v_add_f32_e32 v126, s24, v212
	v_add_f32_e32 v127, s25, v212
	v_mul_f32_e32 v198, v237, v127
	v_mul_f32_e64 v199, v127, -v238
	v_mul_f32_e32 v189, v237, v126
	v_mul_f32_e64 v190, v126, -v238
	v_min_f32_e32 v198, v198, v199
	v_exp_f32_e32 v198, v198
	v_min_f32_e32 v189, v189, v190
	v_exp_f32_e32 v189, v189
	v_cmp_neq_f32_e32 vcc, 0, v127
	s_mov_b32 s24, 0xc2500000
	s_mov_b32 s25, 0xc2540000
	v_cndmask_b32_e32 v127, 2.0, v198, vcc
	v_cmp_neq_f32_e32 vcc, 0, v126
	s_nop 1
	v_cndmask_b32_e32 v126, 2.0, v189, vcc
	v_mul_f32_e32 v216, v126, v106
	v_mul_f32_e32 v217, v127, v107
	v_add_f32_e32 v126, s24, v212
	v_add_f32_e32 v127, s25, v212
	v_mul_f32_e32 v198, v237, v127
	v_mul_f32_e64 v199, v127, -v238
	v_mul_f32_e32 v189, v237, v126
	v_mul_f32_e64 v190, v126, -v238
	v_min_f32_e32 v198, v198, v199
	v_exp_f32_e32 v198, v198
	v_min_f32_e32 v189, v189, v190
	v_exp_f32_e32 v189, v189
	v_cmp_neq_f32_e32 vcc, 0, v127
	v_mov_b32_e32 v199, v124
	s_nop 0
	v_cndmask_b32_e32 v127, 2.0, v198, vcc
	v_cmp_neq_f32_e32 vcc, 0, v126
	s_nop 1
	v_cndmask_b32_e32 v126, 2.0, v189, vcc
	v_mul_f32_e32 v218, v126, v108
	v_mul_f32_e32 v219, v127, v109
	v_add_f32_e32 v126, 0xc2580000, v212
	v_mul_f32_e32 v127, v237, v126
	v_mul_f32_e64 v189, v126, -v238
	v_min_f32_e32 v127, v127, v189
	v_add_f32_e32 v189, 0xc25c0000, v212
	v_mul_f32_e32 v190, v237, v189
	v_mul_f32_e64 v198, v189, -v238
	v_exp_f32_e32 v127, v127
	v_min_f32_e32 v190, v190, v198
	v_exp_f32_e32 v190, v190
	v_cmp_neq_f32_e32 vcc, 0, v126
	v_mov_b32_e32 v198, v123
	s_nop 0
	v_cndmask_b32_e32 v126, 2.0, v127, vcc
	v_cmp_neq_f32_e32 vcc, 0, v189
	v_mul_f32_e32 v250, v126, v110
	v_mov_b32_e32 v189, v112
	v_cndmask_b32_e32 v251, 2.0, v190, vcc
	v_mov_b32_e32 v190, v125

.LBB0_410:
	s_or_b64 exec, exec, s[10:11]
	s_nop 0
	v_cvt_pk_bf16_f32 v108, v188, v189
	v_add_u32_e32 v188, v249, v242
	ds_read_b128 v[112:115], v188 offset:9216
	ds_read_b128 v[116:119], v188 offset:9248
	v_mul_f32_e32 v99, v111, v251
	v_cvt_pk_bf16_f32 v109, v214, v215
	v_cvt_pk_bf16_f32 v110, v210, v211
	v_cvt_pk_bf16_f32 v111, v206, v207
	v_cvt_pk_bf16_f32 v100, v204, v205
	v_cvt_pk_bf16_f32 v101, v200, v201
	s_waitcnt lgkmcnt(1)
	v_mfma_f32_32x32x16_bf16 v[48:63], v[112:115], v[108:111], v[48:63]
	v_cvt_pk_bf16_f32 v102, v198, v199
	v_cvt_pk_bf16_f32 v103, v190, v191
	ds_read_b128 v[112:115], v188 offset:9280
	v_cvt_pk_bf16_f32 v104, v192, v193
	v_cvt_pk_bf16_f32 v105, v194, v195
	v_cvt_pk_bf16_f32 v106, v196, v197
	v_cvt_pk_bf16_f32 v107, v202, v203
	s_waitcnt lgkmcnt(1)
	v_mfma_f32_32x32x16_bf16 v[48:63], v[116:119], v[100:103], v[48:63]
	v_cvt_pk_bf16_f32 v96, v208, v209
	v_cvt_pk_bf16_f32 v97, v216, v217
	v_cvt_pk_bf16_f32 v98, v218, v219
	v_cvt_pk_bf16_f32 v99, v250, v99
	s_waitcnt lgkmcnt(0)
	v_mfma_f32_32x32x16_bf16 v[48:63], v[112:115], v[104:107], v[48:63]
	ds_read_b128 v[112:115], v188 offset:9312
	s_waitcnt lgkmcnt(0)
	v_mfma_f32_32x32x16_bf16 v[48:63], v[112:115], v[96:99], v[48:63]
	ds_read_b128 v[112:115], v188 offset:13824
	s_waitcnt lgkmcnt(0)
	v_mfma_f32_32x32x16_bf16 v[32:47], v[112:115], v[108:111], v[32:47]
	ds_read_b128 v[108:111], v188 offset:13856
	s_waitcnt lgkmcnt(0)
	v_mfma_f32_32x32x16_bf16 v[32:47], v[108:111], v[100:103], v[32:47]
	ds_read_b128 v[100:103], v188 offset:13888
	s_waitcnt lgkmcnt(0)
	v_mfma_f32_32x32x16_bf16 v[32:47], v[100:103], v[104:107], v[32:47]
	ds_read_b128 v[100:103], v188 offset:13920
	s_waitcnt lgkmcnt(0)
	v_mfma_f32_32x32x16_bf16 v[32:47], v[100:103], v[96:99], v[32:47]
	v_add_u32_e32 v96, 32, v247
	v_cvt_f32_i32_e32 v98, v96
	v_cmp_ge_i32_e32 vcc, s21, v243
	s_and_saveexec_b64 s[10:11], vcc
	s_xor_b64 s[10:11], exec, s[10:11]
	s_cbranch_execz .LBB0_416
	v_cmp_le_i32_e32 vcc, s17, v244
	v_mul_f32_e64 v97, -v238, v98
	s_and_saveexec_b64 s[12:13], vcc
	s_xor_b64 s[12:13], exec, s[12:13]
	s_cbranch_execz .LBB0_413
	v_mul_f32_e32 v96, v237, v98
	v_min_f32_e32 v96, v96, v97
	v_exp_f32_e32 v96, v96
	s_mov_b32 s24, -1.0
	s_mov_b32 s25, -2.0
	v_add_f32_e32 v100, s24, v98
	v_add_f32_e32 v101, s25, v98
	v_cmp_ne_u32_e32 vcc, 32, v248
	v_mul_f32_e32 v99, v237, v101
	v_mul_f32_e64 v102, v101, -v238
	v_cndmask_b32_e32 v96, 2.0, v96, vcc
	v_mul_f32_e32 v97, v237, v100
	v_mul_f32_e32 v96, v96, v80
	v_mul_f32_e64 v80, v100, -v238
	v_min_f32_e32 v99, v99, v102
	v_exp_f32_e32 v99, v99
	v_min_f32_e32 v80, v97, v80
	v_exp_f32_e32 v80, v80
	v_cmp_neq_f32_e32 vcc, 0, v101
	s_mov_b32 s24, 0xc0400000
	s_mov_b32 s25, -4.0
	v_cndmask_b32_e32 v101, 2.0, v99, vcc
	v_cmp_neq_f32_e32 vcc, 0, v100
	s_nop 1
	v_cndmask_b32_e32 v100, 2.0, v80, vcc
	v_mov_b32_e32 v80, v81
	v_mov_b32_e32 v81, v82
	v_mul_f32_e32 v100, v100, v80
	v_mul_f32_e32 v101, v101, v81
	v_add_f32_e32 v80, s24, v98
	v_add_f32_e32 v81, s25, v98
	v_mul_f32_e32 v99, v237, v81
	v_mul_f32_e64 v102, v81, -v238
	v_mul_f32_e32 v82, v237, v80
	v_mul_f32_e64 v97, v80, -v238
	v_min_f32_e32 v99, v99, v102
	v_exp_f32_e32 v99, v99
	v_min_f32_e32 v82, v82, v97
	v_exp_f32_e32 v82, v82
	v_cmp_neq_f32_e32 vcc, 0, v81
	s_mov_b32 s24, 0xc0a00000
	s_mov_b32 s25, 0xc0c00000
	v_cndmask_b32_e32 v81, 2.0, v99, vcc
	v_cmp_neq_f32_e32 vcc, 0, v80
	s_nop 1
	v_cndmask_b32_e32 v80, 2.0, v82, vcc
	v_mov_b32_e32 v82, v83
	v_mov_b32_e32 v83, v84
	v_mul_f32_e32 v102, v80, v82
	v_mul_f32_e32 v103, v81, v83
	v_add_f32_e32 v80, s24, v98
	v_add_f32_e32 v81, s25, v98
	v_mul_f32_e32 v84, v237, v81
	v_mul_f32_e64 v97, v81, -v238
	v_mul_f32_e32 v82, v237, v80
	v_mul_f32_e64 v83, v80, -v238
	v_min_f32_e32 v84, v84, v97
	v_exp_f32_e32 v84, v84
	v_min_f32_e32 v82, v82, v83
	v_exp_f32_e32 v82, v82
	v_cmp_neq_f32_e32 vcc, 0, v81
	s_mov_b32 s24, 0xc0e00000
	v_mov_b32_e32 v83, v86
	v_cndmask_b32_e32 v81, 2.0, v84, vcc
	v_cmp_neq_f32_e32 vcc, 0, v80
	s_mov_b32 s25, 0xc1800000
	s_nop 0
	v_cndmask_b32_e32 v80, 2.0, v82, vcc
	v_mov_b32_e32 v82, v85
	v_mul_f32_e32 v106, v80, v82
	v_mul_f32_e32 v107, v81, v83
	v_add_f32_e32 v80, s24, v98
	v_add_f32_e32 v81, s25, v98
	v_mul_f32_e32 v84, v237, v81
	v_mul_f32_e64 v85, v81, -v238
	v_mul_f32_e32 v82, v237, v80
	v_mul_f32_e64 v83, v80, -v238
	v_min_f32_e32 v84, v84, v85
	v_exp_f32_e32 v84, v84
	v_min_f32_e32 v82, v82, v83
	v_exp_f32_e32 v82, v82
	v_cmp_neq_f32_e32 vcc, 0, v81
	s_mov_b32 s24, 0xc1880000
	v_mov_b32_e32 v83, v88
	v_cndmask_b32_e32 v81, 2.0, v84, vcc
	v_cmp_neq_f32_e32 vcc, 0, v80
	s_mov_b32 s25, 0xc1900000
	s_nop 0
	v_cndmask_b32_e32 v80, 2.0, v82, vcc
	v_mov_b32_e32 v82, v87
	v_mul_f32_e32 v108, v80, v82
	v_mul_f32_e32 v109, v81, v83
	v_add_f32_e32 v80, s24, v98
	v_add_f32_e32 v81, s25, v98
	v_mul_f32_e32 v84, v237, v81
	v_mul_f32_e64 v85, v81, -v238
	v_mul_f32_e32 v82, v237, v80
	v_mul_f32_e64 v83, v80, -v238
	v_min_f32_e32 v84, v84, v85
	v_exp_f32_e32 v84, v84
	v_min_f32_e32 v82, v82, v83
	v_exp_f32_e32 v82, v82
	v_cmp_neq_f32_e32 vcc, 0, v81
	s_mov_b32 s24, 0xc1980000
	v_mov_b32_e32 v83, v90
	v_cndmask_b32_e32 v81, 2.0, v84, vcc
	v_cmp_neq_f32_e32 vcc, 0, v80
	s_mov_b32 s25, 0xc1a00000
	s_nop 0
	v_cndmask_b32_e32 v80, 2.0, v82, vcc
	v_mov_b32_e32 v82, v89
	v_mul_f32_e32 v112, v80, v82
	v_mul_f32_e32 v113, v81, v83
	v_add_f32_e32 v80, s24, v98
	v_add_f32_e32 v81, s25, v98
	v_mul_f32_e32 v84, v237, v81
	v_mul_f32_e64 v85, v81, -v238
	v_mul_f32_e32 v82, v237, v80
	v_mul_f32_e64 v83, v80, -v238
	v_min_f32_e32 v84, v84, v85
	v_exp_f32_e32 v84, v84
	v_min_f32_e32 v82, v82, v83
	v_exp_f32_e32 v82, v82
	v_cmp_neq_f32_e32 vcc, 0, v81
	s_mov_b32 s24, 0xc1a80000
	v_mov_b32_e32 v83, v92
	v_cndmask_b32_e32 v81, 2.0, v84, vcc
	v_cmp_neq_f32_e32 vcc, 0, v80
	s_mov_b32 s25, 0xc1b00000
	s_nop 0
	v_cndmask_b32_e32 v80, 2.0, v82, vcc
	v_mov_b32_e32 v82, v91
	v_mul_f32_e32 v114, v80, v82
	v_mul_f32_e32 v115, v81, v83
	v_add_f32_e32 v80, s24, v98
	v_add_f32_e32 v81, s25, v98
	v_mul_f32_e32 v84, v237, v81
	v_mul_f32_e64 v85, v81, -v238
	v_min_f32_e32 v84, v84, v85
	v_exp_f32_e32 v84, v84
	v_cmp_neq_f32_e32 vcc, 0, v81
	v_mul_f32_e32 v82, v237, v80
	v_mul_f32_e64 v83, v80, -v238
	v_cndmask_b32_e32 v81, 2.0, v84, vcc
	v_add_f32_e32 v84, 0xc1b80000, v98
	v_min_f32_e32 v82, v82, v83
	v_mul_f32_e32 v83, v237, v84
	v_mul_f32_e64 v85, v84, -v238
	v_exp_f32_e32 v82, v82
	v_min_f32_e32 v83, v83, v85
	v_exp_f32_e32 v85, v83
	v_cmp_neq_f32_e32 vcc, 0, v80
	v_mov_b32_e32 v83, v94
	s_mov_b32 s24, 0xc2000000
	v_cndmask_b32_e32 v80, 2.0, v82, vcc
	v_mov_b32_e32 v82, v93
	v_cmp_neq_f32_e32 vcc, 0, v84
	v_mul_f32_e32 v120, v80, v82
	v_mul_f32_e32 v121, v81, v83
	s_mov_b32 s25, 0xc2040000
	v_cndmask_b32_e32 v80, 2.0, v85, vcc
	v_mul_f32_e32 v99, v80, v95
	v_add_f32_e32 v80, s24, v98
	v_add_f32_e32 v81, s25, v98
	v_mul_f32_e32 v84, v237, v81
	v_mul_f32_e64 v85, v81, -v238
	v_mul_f32_e32 v82, v237, v80
	v_mul_f32_e64 v83, v80, -v238
	v_min_f32_e32 v84, v84, v85
	v_exp_f32_e32 v84, v84
	v_min_f32_e32 v82, v82, v83
	v_exp_f32_e32 v82, v82
	v_cmp_neq_f32_e32 vcc, 0, v81
	s_mov_b32 s24, 0xc2080000
	s_mov_b32 s25, 0xc20c0000
	v_cndmask_b32_e32 v81, 2.0, v84, vcc
	v_cmp_neq_f32_e32 vcc, 0, v80
	s_nop 1
	v_cndmask_b32_e32 v80, 2.0, v82, vcc
	v_mul_f32_e32 v104, v80, v64
	v_mul_f32_e32 v105, v81, v65
	v_add_f32_e32 v80, s24, v98
	v_add_f32_e32 v81, s25, v98
	v_mul_f32_e32 v84, v237, v81
	v_mul_f32_e64 v85, v81, -v238
	v_mul_f32_e32 v82, v237, v80
	v_mul_f32_e64 v83, v80, -v238
	v_min_f32_e32 v84, v84, v85
	v_exp_f32_e32 v84, v84
	v_min_f32_e32 v82, v82, v83
	v_exp_f32_e32 v82, v82
	v_cmp_neq_f32_e32 vcc, 0, v81
	s_mov_b32 s24, 0xc2100000
	s_mov_b32 s25, 0xc2140000
	v_cndmask_b32_e32 v81, 2.0, v84, vcc
	v_cmp_neq_f32_e32 vcc, 0, v80
	s_nop 1
	v_cndmask_b32_e32 v80, 2.0, v82, vcc
	v_mul_f32_e32 v110, v80, v66
	v_mul_f32_e32 v111, v81, v67
	v_add_f32_e32 v80, s24, v98
	v_add_f32_e32 v81, s25, v98
	v_mul_f32_e32 v84, v237, v81
	v_mul_f32_e64 v85, v81, -v238
	v_mul_f32_e32 v82, v237, v80
	v_mul_f32_e64 v83, v80, -v238
	v_min_f32_e32 v84, v84, v85
	v_exp_f32_e32 v84, v84
	v_min_f32_e32 v82, v82, v83
	v_exp_f32_e32 v82, v82
	v_cmp_neq_f32_e32 vcc, 0, v81
	s_mov_b32 s24, 0xc2180000
	s_mov_b32 s25, 0xc21c0000
	v_cndmask_b32_e32 v81, 2.0, v84, vcc
	v_cmp_neq_f32_e32 vcc, 0, v80
	s_nop 1
	v_cndmask_b32_e32 v80, 2.0, v82, vcc
	v_mul_f32_e32 v116, v80, v68
	v_mul_f32_e32 v117, v81, v69
	v_add_f32_e32 v80, s24, v98
	v_add_f32_e32 v81, s25, v98
	v_mul_f32_e32 v84, v237, v81
	v_mul_f32_e64 v85, v81, -v238
	v_mul_f32_e32 v82, v237, v80
	v_mul_f32_e64 v83, v80, -v238
	v_min_f32_e32 v84, v84, v85
	v_exp_f32_e32 v84, v84
	v_min_f32_e32 v82, v82, v83
	v_exp_f32_e32 v82, v82
	v_cmp_neq_f32_e32 vcc, 0, v81
	s_mov_b32 s24, 0xc2400000
	s_mov_b32 s25, 0xc2440000
	v_cndmask_b32_e32 v81, 2.0, v84, vcc
	v_cmp_neq_f32_e32 vcc, 0, v80
	s_nop 1
	v_cndmask_b32_e32 v80, 2.0, v82, vcc
	v_mul_f32_e32 v118, v80, v70
	v_mul_f32_e32 v119, v81, v71
	v_add_f32_e32 v80, s24, v98
	v_add_f32_e32 v81, s25, v98
	v_mul_f32_e32 v84, v237, v81
	v_mul_f32_e64 v85, v81, -v238
	v_mul_f32_e32 v82, v237, v80
	v_mul_f32_e64 v83, v80, -v238
	v_min_f32_e32 v84, v84, v85
	v_exp_f32_e32 v84, v84
	v_min_f32_e32 v82, v82, v83
	v_exp_f32_e32 v82, v82
	v_cmp_neq_f32_e32 vcc, 0, v81
	s_mov_b32 s24, 0xc2480000
	s_mov_b32 s25, 0xc24c0000
	v_cndmask_b32_e32 v81, 2.0, v84, vcc
	v_cmp_neq_f32_e32 vcc, 0, v80
	s_nop 1
	v_cndmask_b32_e32 v80, 2.0, v82, vcc
	v_mul_f32_e32 v122, v80, v72
	v_mul_f32_e32 v123, v81, v73
	v_add_f32_e32 v80, s24, v98
	v_add_f32_e32 v81, s25, v98
	v_mul_f32_e32 v84, v237, v81
	v_mul_f32_e64 v85, v81, -v238
	v_mul_f32_e32 v82, v237, v80
	v_mul_f32_e64 v83, v80, -v238
	v_min_f32_e32 v84, v84, v85
	v_exp_f32_e32 v84, v84
	v_min_f32_e32 v82, v82, v83
	v_exp_f32_e32 v82, v82
	v_cmp_neq_f32_e32 vcc, 0, v81
	s_mov_b32 s24, 0xc2500000
	s_mov_b32 s25, 0xc2540000
	v_cndmask_b32_e32 v81, 2.0, v84, vcc
	v_cmp_neq_f32_e32 vcc, 0, v80
	s_nop 1
	v_cndmask_b32_e32 v80, 2.0, v82, vcc
	v_mul_f32_e32 v124, v80, v74
	v_mul_f32_e32 v125, v81, v75
	v_add_f32_e32 v80, s24, v98
	v_add_f32_e32 v81, s25, v98
	v_mul_f32_e32 v84, v237, v81
	v_mul_f32_e64 v85, v81, -v238
	v_mul_f32_e32 v82, v237, v80
	v_mul_f32_e64 v83, v80, -v238
	v_min_f32_e32 v84, v84, v85
	v_exp_f32_e32 v84, v84
	v_min_f32_e32 v82, v82, v83
	v_exp_f32_e32 v82, v82
	v_cmp_neq_f32_e32 vcc, 0, v81
	s_nop 1
	v_cndmask_b32_e32 v81, 2.0, v84, vcc
	v_cmp_neq_f32_e32 vcc, 0, v80
	s_nop 1
	v_cndmask_b32_e32 v80, 2.0, v82, vcc
	v_mul_f32_e32 v126, v80, v76
	v_mul_f32_e32 v127, v81, v77
	v_add_f32_e32 v80, 0xc2580000, v98
	v_mul_f32_e32 v81, v237, v80
	v_mul_f32_e64 v82, v80, -v238
	v_min_f32_e32 v81, v81, v82
	v_add_f32_e32 v82, 0xc25c0000, v98
	v_mul_f32_e32 v83, v237, v82
	v_mul_f32_e64 v84, v82, -v238
	v_exp_f32_e32 v81, v81
	v_min_f32_e32 v83, v83, v84
	v_exp_f32_e32 v83, v83
	v_cmp_neq_f32_e32 vcc, 0, v80
	s_nop 1
	v_cndmask_b32_e32 v80, 2.0, v81, vcc
	v_cmp_neq_f32_e32 vcc, 0, v82
	v_mul_f32_e32 v189, v80, v78
	s_nop 0
	v_cndmask_b32_e32 v190, 2.0, v83, vcc

.LBB0_420:
	v_and_b32_e32 v65, 64, v229
	v_xor_b32_e32 v64, 32, v229
	v_add_u32_e32 v65, 64, v65
	v_cmp_lt_i32_e32 vcc, v64, v65
	v_mov_b32_e32 v181, v177
	s_movk_i32 s10, 0x1000
	v_cndmask_b32_e32 v64, v229, v64, vcc
	v_lshlrev_b32_e32 v142, 2, v64
	v_lshl_add_u64 v[64:65], s[78:79], 0, v[184:185]
	v_lshl_add_u64 v[64:65], v[64:65], 0, s[8:9]
	v_lshl_add_u64 v[96:97], v[64:65], 0, v[180:181]
	v_add_co_u32_e32 v64, vcc, s10, v96
	s_lshl_b32 s6, s15, 8
	s_nop 0
	v_addc_co_u32_e32 v65, vcc, 0, v97, vcc
	global_load_dwordx2 v[68:69], v[64:65], off
	s_ashr_i32 s7, s6, 31
	v_readlane_b32 s48, v253, 26
	s_lshl_b64 s[6:7], s[6:7], 2
	v_readlane_b32 s56, v253, 34
	v_readlane_b32 s57, v253, 35
	s_add_u32 s6, s56, s6
	s_addc_u32 s7, s57, s7
	s_lshl_b64 s[4:5], s[4:5], 2
	s_add_u32 s6, s6, s4
	s_addc_u32 s7, s7, s5
	v_lshl_add_u64 v[92:93], v[96:97], 0, s[64:65]
	v_mul_f32_e32 v106, v38, v38
	v_mul_f32_e32 v107, v39, v39
	v_mul_f32_e32 v156, v6, v6
	v_mul_f32_e32 v157, v7, v7
	v_mul_f32_e32 v104, v40, v40
	v_mul_f32_e32 v105, v41, v41
	v_mul_f32_e32 v154, v8, v8
	v_mul_f32_e32 v155, v9, v9
	v_mul_f32_e32 v102, v42, v42
	v_mul_f32_e32 v103, v43, v43
	v_mul_f32_e32 v152, v10, v10
	v_mul_f32_e32 v153, v11, v11
	v_mul_f32_e32 v100, v44, v44
	v_mul_f32_e32 v101, v45, v45
	v_mul_f32_e32 v150, v12, v12
	v_mul_f32_e32 v151, v13, v13
	v_mul_f32_e32 v98, v46, v46
	v_mul_f32_e32 v99, v47, v47
	v_mul_f32_e32 v148, v14, v14
	v_mul_f32_e32 v149, v15, v15
	v_readlane_b32 s49, v253, 27
	v_readlane_b32 s50, v253, 28
	v_readlane_b32 s51, v253, 29
	v_readlane_b32 s52, v253, 30
	v_readlane_b32 s53, v253, 31
	v_readlane_b32 s54, v253, 32
	v_readlane_b32 s55, v253, 33
	v_readlane_b32 s58, v253, 36
	v_readlane_b32 s59, v253, 37
	v_readlane_b32 s60, v253, 38
	v_readlane_b32 s61, v253, 39
	v_readlane_b32 s62, v253, 40
	v_readlane_b32 s63, v253, 41
	s_waitcnt vmcnt(0)
	v_lshlrev_b32_e32 v72, 16, v68
	v_and_b32_e32 v68, 0xffff0000, v68
	v_mul_f32_e32 v64, 0xbfb8aa3b, v72
	v_mul_f32_e32 v71, 0xbfb8aa3b, v68
	v_exp_f32_e32 v70, v64
	v_exp_f32_e32 v71, v71
	global_load_dwordx4 v[64:67], v176, s[6:7]
	v_add_f32_e32 v70, 1.0, v70
	v_add_f32_e32 v71, 1.0, v71
	s_nop 0
	v_div_scale_f32 v73, s[4:5], v71, v71, v68
	v_rcp_f32_e32 v74, v73
	s_nop 0
	v_fma_f32 v75, -v73, v74, 1.0
	v_fmac_f32_e32 v74, v75, v74
	v_div_scale_f32 v75, vcc, v68, v71, v68
	v_mul_f32_e32 v76, v75, v74
	v_fma_f32 v77, -v73, v76, v75
	v_fmac_f32_e32 v76, v77, v74
	v_fma_f32 v73, -v73, v76, v75
	v_div_fmas_f32 v73, v73, v74, v76
	v_div_fixup_f32 v109, v73, v71, v68
	v_div_scale_f32 v68, s[4:5], v70, v70, v72
	v_rcp_f32_e32 v71, v68
	s_nop 0
	v_fma_f32 v73, -v68, v71, 1.0
	v_fmac_f32_e32 v71, v73, v71
	v_div_scale_f32 v73, vcc, v72, v70, v72
	v_mul_f32_e32 v74, v73, v71
	v_fma_f32 v75, -v68, v74, v73
	v_fmac_f32_e32 v74, v75, v71
	v_fma_f32 v68, -v68, v74, v73
	v_div_fmas_f32 v68, v68, v71, v74
	v_div_fixup_f32 v108, v68, v70, v72
	v_lshlrev_b32_e32 v70, 16, v69
	v_and_b32_e32 v71, 0xffff0000, v69
	v_mul_f32_e32 v68, 0xbfb8aa3b, v70
	v_mul_f32_e32 v69, 0xbfb8aa3b, v71
	v_exp_f32_e32 v68, v68
	v_exp_f32_e32 v69, v69
	s_nop 0
	v_add_f32_e32 v68, 1.0, v68
	v_add_f32_e32 v69, 1.0, v69
	s_nop 0
	v_div_scale_f32 v72, s[4:5], v69, v69, v71
	v_rcp_f32_e32 v73, v72
	s_nop 0
	v_fma_f32 v74, -v72, v73, 1.0
	v_fmac_f32_e32 v73, v74, v73
	v_div_scale_f32 v74, vcc, v71, v69, v71
	v_mul_f32_e32 v75, v74, v73
	v_fma_f32 v76, -v72, v75, v74
	v_fmac_f32_e32 v75, v76, v73
	v_fma_f32 v72, -v72, v75, v74
	v_div_fmas_f32 v72, v72, v73, v75
	v_div_fixup_f32 v111, v72, v69, v71
	v_div_scale_f32 v69, s[4:5], v68, v68, v70
	v_rcp_f32_e32 v71, v69
	s_nop 0
	v_fma_f32 v72, -v69, v71, 1.0
	v_fmac_f32_e32 v71, v72, v71
	v_div_scale_f32 v72, vcc, v70, v68, v70
	v_mul_f32_e32 v73, v72, v71
	v_fma_f32 v74, -v69, v73, v72
	v_fmac_f32_e32 v73, v74, v71
	v_fma_f32 v69, -v69, v73, v72
	v_div_fmas_f32 v69, v69, v71, v73
	global_load_dwordx2 v[72:73], v[92:93], off offset:16
	v_div_fixup_f32 v110, v69, v68, v70
	s_waitcnt vmcnt(0)
	v_lshlrev_b32_e32 v76, 16, v72
	v_and_b32_e32 v72, 0xffff0000, v72
	v_mul_f32_e32 v68, 0xbfb8aa3b, v76
	v_mul_f32_e32 v75, 0xbfb8aa3b, v72
	v_exp_f32_e32 v74, v68
	v_exp_f32_e32 v75, v75
	global_load_dwordx4 v[68:71], v176, s[6:7] offset:32
	v_add_f32_e32 v74, 1.0, v74
	v_add_f32_e32 v75, 1.0, v75
	s_nop 0
	v_div_scale_f32 v77, s[4:5], v75, v75, v72
	v_rcp_f32_e32 v78, v77
	s_nop 0
	v_fma_f32 v79, -v77, v78, 1.0
	v_fmac_f32_e32 v78, v79, v78
	v_div_scale_f32 v79, vcc, v72, v75, v72
	v_mul_f32_e32 v80, v79, v78
	v_fma_f32 v81, -v77, v80, v79
	v_fmac_f32_e32 v80, v81, v78
	v_fma_f32 v77, -v77, v80, v79
	v_div_fmas_f32 v77, v77, v78, v80
	v_div_fixup_f32 v113, v77, v75, v72
	v_div_scale_f32 v72, s[4:5], v74, v74, v76
	v_rcp_f32_e32 v75, v72
	s_nop 0
	v_fma_f32 v77, -v72, v75, 1.0
	v_fmac_f32_e32 v75, v77, v75
	v_div_scale_f32 v77, vcc, v76, v74, v76
	v_mul_f32_e32 v78, v77, v75
	v_fma_f32 v79, -v72, v78, v77
	v_fmac_f32_e32 v78, v79, v75
	v_fma_f32 v72, -v72, v78, v77
	v_div_fmas_f32 v72, v72, v75, v78
	v_div_fixup_f32 v112, v72, v74, v76
	v_lshlrev_b32_e32 v74, 16, v73
	v_and_b32_e32 v75, 0xffff0000, v73
	v_mul_f32_e32 v72, 0xbfb8aa3b, v74
	v_mul_f32_e32 v73, 0xbfb8aa3b, v75
	v_exp_f32_e32 v72, v72
	v_exp_f32_e32 v73, v73
	s_nop 0
	v_add_f32_e32 v72, 1.0, v72
	v_add_f32_e32 v73, 1.0, v73
	s_nop 0
	v_div_scale_f32 v76, s[4:5], v73, v73, v75
	v_rcp_f32_e32 v77, v76
	s_nop 0
	v_fma_f32 v78, -v76, v77, 1.0
	v_fmac_f32_e32 v77, v78, v77
	v_div_scale_f32 v78, vcc, v75, v73, v75
	v_mul_f32_e32 v79, v78, v77
	v_fma_f32 v80, -v76, v79, v78
	v_fmac_f32_e32 v79, v80, v77
	v_fma_f32 v76, -v76, v79, v78
	v_div_fmas_f32 v76, v76, v77, v79
	v_div_fixup_f32 v115, v76, v73, v75
	v_div_scale_f32 v73, s[4:5], v72, v72, v74
	v_rcp_f32_e32 v75, v73
	s_nop 0
	v_fma_f32 v76, -v73, v75, 1.0
	v_fmac_f32_e32 v75, v76, v75
	v_div_scale_f32 v76, vcc, v74, v72, v74
	v_mul_f32_e32 v77, v76, v75
	v_fma_f32 v78, -v73, v77, v76
	v_fmac_f32_e32 v77, v78, v75
	v_fma_f32 v73, -v73, v77, v76
	v_div_fmas_f32 v73, v73, v75, v77
	global_load_dwordx2 v[76:77], v[92:93], off offset:32
	v_div_fixup_f32 v114, v73, v72, v74
	s_waitcnt vmcnt(0)
	v_lshlrev_b32_e32 v80, 16, v76
	v_and_b32_e32 v76, 0xffff0000, v76
	v_mul_f32_e32 v72, 0xbfb8aa3b, v80
	v_mul_f32_e32 v79, 0xbfb8aa3b, v76
	v_exp_f32_e32 v78, v72
	v_exp_f32_e32 v79, v79
	global_load_dwordx4 v[72:75], v176, s[6:7] offset:64
	v_add_f32_e32 v78, 1.0, v78
	v_add_f32_e32 v79, 1.0, v79
	s_nop 0
	v_div_scale_f32 v81, s[4:5], v79, v79, v76
	v_rcp_f32_e32 v82, v81
	s_nop 0
	v_fma_f32 v83, -v81, v82, 1.0
	v_fmac_f32_e32 v82, v83, v82
	v_div_scale_f32 v83, vcc, v76, v79, v76
	v_mul_f32_e32 v84, v83, v82
	v_fma_f32 v85, -v81, v84, v83
	v_fmac_f32_e32 v84, v85, v82
	v_fma_f32 v81, -v81, v84, v83
	v_div_fmas_f32 v81, v81, v82, v84
	v_div_fixup_f32 v117, v81, v79, v76
	v_div_scale_f32 v76, s[4:5], v78, v78, v80
	v_rcp_f32_e32 v79, v76
	s_nop 0
	v_fma_f32 v81, -v76, v79, 1.0
	v_fmac_f32_e32 v79, v81, v79
	v_div_scale_f32 v81, vcc, v80, v78, v80
	v_mul_f32_e32 v82, v81, v79
	v_fma_f32 v83, -v76, v82, v81
	v_fmac_f32_e32 v82, v83, v79
	v_fma_f32 v76, -v76, v82, v81
	v_div_fmas_f32 v76, v76, v79, v82
	v_div_fixup_f32 v116, v76, v78, v80
	v_lshlrev_b32_e32 v78, 16, v77
	v_and_b32_e32 v79, 0xffff0000, v77
	v_mul_f32_e32 v76, 0xbfb8aa3b, v78
	v_mul_f32_e32 v77, 0xbfb8aa3b, v79
	v_exp_f32_e32 v76, v76
	v_exp_f32_e32 v77, v77
	s_nop 0
	v_add_f32_e32 v76, 1.0, v76
	v_add_f32_e32 v77, 1.0, v77
	s_nop 0
	v_div_scale_f32 v80, s[4:5], v77, v77, v79
	v_rcp_f32_e32 v81, v80
	s_nop 0
	v_fma_f32 v82, -v80, v81, 1.0
	v_fmac_f32_e32 v81, v82, v81
	v_div_scale_f32 v82, vcc, v79, v77, v79
	v_mul_f32_e32 v83, v82, v81
	v_fma_f32 v84, -v80, v83, v82
	v_fmac_f32_e32 v83, v84, v81
	v_fma_f32 v80, -v80, v83, v82
	v_div_fmas_f32 v80, v80, v81, v83
	v_div_fixup_f32 v119, v80, v77, v79
	v_div_scale_f32 v77, s[4:5], v76, v76, v78
	v_rcp_f32_e32 v79, v77
	s_nop 0
	v_fma_f32 v80, -v77, v79, 1.0
	v_fmac_f32_e32 v79, v80, v79
	v_div_scale_f32 v80, vcc, v78, v76, v78
	v_mul_f32_e32 v81, v80, v79
	v_fma_f32 v82, -v77, v81, v80
	v_fmac_f32_e32 v81, v82, v79
	v_fma_f32 v77, -v77, v81, v80
	v_div_fmas_f32 v77, v77, v79, v81
	global_load_dwordx2 v[80:81], v[92:93], off offset:48
	v_div_fixup_f32 v118, v77, v76, v78
	s_waitcnt vmcnt(0)
	v_lshlrev_b32_e32 v84, 16, v80
	v_and_b32_e32 v80, 0xffff0000, v80
	v_mul_f32_e32 v76, 0xbfb8aa3b, v84
	v_mul_f32_e32 v83, 0xbfb8aa3b, v80
	v_exp_f32_e32 v82, v76
	v_exp_f32_e32 v83, v83
	global_load_dwordx4 v[76:79], v176, s[6:7] offset:96
	v_add_f32_e32 v82, 1.0, v82
	v_add_f32_e32 v83, 1.0, v83
	s_nop 0
	v_div_scale_f32 v85, s[4:5], v83, v83, v80
	v_rcp_f32_e32 v86, v85
	s_nop 0
	v_fma_f32 v87, -v85, v86, 1.0
	v_fmac_f32_e32 v86, v87, v86
	v_div_scale_f32 v87, vcc, v80, v83, v80
	v_mul_f32_e32 v88, v87, v86
	v_fma_f32 v89, -v85, v88, v87
	v_fmac_f32_e32 v88, v89, v86
	v_fma_f32 v85, -v85, v88, v87
	v_div_fmas_f32 v85, v85, v86, v88
	v_div_fixup_f32 v121, v85, v83, v80
	v_div_scale_f32 v80, s[4:5], v82, v82, v84
	v_rcp_f32_e32 v83, v80
	s_nop 0
	v_fma_f32 v85, -v80, v83, 1.0
	v_fmac_f32_e32 v83, v85, v83
	v_div_scale_f32 v85, vcc, v84, v82, v84
	v_mul_f32_e32 v86, v85, v83
	v_fma_f32 v87, -v80, v86, v85
	v_fmac_f32_e32 v86, v87, v83
	v_fma_f32 v80, -v80, v86, v85
	v_div_fmas_f32 v80, v80, v83, v86
	v_div_fixup_f32 v120, v80, v82, v84
	v_lshlrev_b32_e32 v82, 16, v81
	v_and_b32_e32 v83, 0xffff0000, v81
	v_mul_f32_e32 v80, 0xbfb8aa3b, v82
	v_mul_f32_e32 v81, 0xbfb8aa3b, v83
	v_exp_f32_e32 v80, v80
	v_exp_f32_e32 v81, v81
	s_nop 0
	v_add_f32_e32 v80, 1.0, v80
	v_add_f32_e32 v81, 1.0, v81
	s_nop 0
	v_div_scale_f32 v84, s[4:5], v81, v81, v83
	v_rcp_f32_e32 v85, v84
	s_nop 0
	v_fma_f32 v86, -v84, v85, 1.0
	v_fmac_f32_e32 v85, v86, v85
	v_div_scale_f32 v86, vcc, v83, v81, v83
	v_mul_f32_e32 v87, v86, v85
	v_fma_f32 v88, -v84, v87, v86
	v_fmac_f32_e32 v87, v88, v85
	v_fma_f32 v84, -v84, v87, v86
	v_div_fmas_f32 v84, v84, v85, v87
	v_div_fixup_f32 v123, v84, v81, v83
	v_div_scale_f32 v81, s[4:5], v80, v80, v82
	v_rcp_f32_e32 v83, v81
	s_nop 0
	v_fma_f32 v84, -v81, v83, 1.0
	v_fmac_f32_e32 v83, v84, v83
	v_div_scale_f32 v84, vcc, v82, v80, v82
	v_mul_f32_e32 v85, v84, v83
	v_fma_f32 v86, -v81, v85, v84
	v_fmac_f32_e32 v85, v86, v83
	v_fma_f32 v81, -v81, v85, v84
	v_div_fmas_f32 v81, v81, v83, v85
	global_load_dwordx2 v[84:85], v[92:93], off offset:64
	v_div_fixup_f32 v122, v81, v80, v82
	s_waitcnt vmcnt(0)
	v_lshlrev_b32_e32 v88, 16, v84
	v_and_b32_e32 v84, 0xffff0000, v84
	v_mul_f32_e32 v80, 0xbfb8aa3b, v88
	v_mul_f32_e32 v87, 0xbfb8aa3b, v84
	v_exp_f32_e32 v86, v80
	v_exp_f32_e32 v87, v87
	global_load_dwordx4 v[80:83], v176, s[6:7] offset:128
	v_add_f32_e32 v86, 1.0, v86
	v_add_f32_e32 v87, 1.0, v87
	s_nop 0
	v_div_scale_f32 v89, s[4:5], v87, v87, v84
	v_rcp_f32_e32 v90, v89
	s_nop 0
	v_fma_f32 v91, -v89, v90, 1.0
	v_fmac_f32_e32 v90, v91, v90
	v_div_scale_f32 v91, vcc, v84, v87, v84
	v_mul_f32_e32 v94, v91, v90
	v_fma_f32 v95, -v89, v94, v91
	v_fmac_f32_e32 v94, v95, v90
	v_fma_f32 v89, -v89, v94, v91
	v_div_fmas_f32 v89, v89, v90, v94
	v_div_fixup_f32 v125, v89, v87, v84
	v_div_scale_f32 v84, s[4:5], v86, v86, v88
	v_rcp_f32_e32 v87, v84
	s_nop 0
	v_fma_f32 v89, -v84, v87, 1.0
	v_fmac_f32_e32 v87, v89, v87
	v_div_scale_f32 v89, vcc, v88, v86, v88
	v_mul_f32_e32 v90, v89, v87
	v_fma_f32 v91, -v84, v90, v89
	v_fmac_f32_e32 v90, v91, v87
	v_fma_f32 v84, -v84, v90, v89
	v_div_fmas_f32 v84, v84, v87, v90
	v_div_fixup_f32 v124, v84, v86, v88
	v_lshlrev_b32_e32 v86, 16, v85
	v_and_b32_e32 v87, 0xffff0000, v85
	v_mul_f32_e32 v84, 0xbfb8aa3b, v86
	v_mul_f32_e32 v85, 0xbfb8aa3b, v87
	v_exp_f32_e32 v84, v84
	v_exp_f32_e32 v85, v85
	s_nop 0
	v_add_f32_e32 v84, 1.0, v84
	v_add_f32_e32 v85, 1.0, v85
	s_nop 0
	v_div_scale_f32 v88, s[4:5], v85, v85, v87
	v_rcp_f32_e32 v89, v88
	s_nop 0
	v_fma_f32 v90, -v88, v89, 1.0
	v_fmac_f32_e32 v89, v90, v89
	v_div_scale_f32 v90, vcc, v87, v85, v87
	v_mul_f32_e32 v91, v90, v89
	v_fma_f32 v94, -v88, v91, v90
	v_fmac_f32_e32 v91, v94, v89
	v_fma_f32 v88, -v88, v91, v90
	v_div_fmas_f32 v88, v88, v89, v91
	v_div_fixup_f32 v127, v88, v85, v87
	v_div_scale_f32 v85, s[4:5], v84, v84, v86
	v_rcp_f32_e32 v87, v85
	s_nop 0
	v_fma_f32 v88, -v85, v87, 1.0
	v_fmac_f32_e32 v87, v88, v87
	v_div_scale_f32 v88, vcc, v86, v84, v86
	v_mul_f32_e32 v89, v88, v87
	v_fma_f32 v90, -v85, v89, v88
	v_fmac_f32_e32 v89, v90, v87
	v_fma_f32 v85, -v85, v89, v88
	v_div_fmas_f32 v85, v85, v87, v89
	global_load_dwordx2 v[88:89], v[92:93], off offset:80
	v_div_fixup_f32 v126, v85, v84, v86
	s_waitcnt vmcnt(0)
	v_lshlrev_b32_e32 v94, 16, v88
	v_and_b32_e32 v88, 0xffff0000, v88
	v_mul_f32_e32 v84, 0xbfb8aa3b, v94
	v_mul_f32_e32 v91, 0xbfb8aa3b, v88
	v_exp_f32_e32 v90, v84
	v_exp_f32_e32 v91, v91
	global_load_dwordx4 v[84:87], v176, s[6:7] offset:160
	v_add_f32_e32 v90, 1.0, v90
	v_add_f32_e32 v91, 1.0, v91
	s_nop 0
	v_div_scale_f32 v95, s[4:5], v91, v91, v88
	v_rcp_f32_e32 v128, v95
	s_nop 0
	v_fma_f32 v129, -v95, v128, 1.0
	v_fmac_f32_e32 v128, v129, v128
	v_div_scale_f32 v129, vcc, v88, v91, v88
	v_mul_f32_e32 v130, v129, v128
	v_fma_f32 v131, -v95, v130, v129
	v_fmac_f32_e32 v130, v131, v128
	v_fma_f32 v95, -v95, v130, v129
	v_div_fmas_f32 v95, v95, v128, v130
	v_div_fixup_f32 v129, v95, v91, v88
	v_div_scale_f32 v88, s[4:5], v90, v90, v94
	v_rcp_f32_e32 v91, v88
	s_nop 0
	v_fma_f32 v95, -v88, v91, 1.0
	v_fmac_f32_e32 v91, v95, v91
	v_div_scale_f32 v95, vcc, v94, v90, v94
	v_mul_f32_e32 v128, v95, v91
	v_fma_f32 v130, -v88, v128, v95
	v_fmac_f32_e32 v128, v130, v91
	v_fma_f32 v88, -v88, v128, v95
	v_div_fmas_f32 v88, v88, v91, v128
	v_div_fixup_f32 v128, v88, v90, v94
	v_lshlrev_b32_e32 v90, 16, v89
	v_and_b32_e32 v91, 0xffff0000, v89
	v_mul_f32_e32 v88, 0xbfb8aa3b, v90
	v_mul_f32_e32 v89, 0xbfb8aa3b, v91
	v_exp_f32_e32 v88, v88
	v_exp_f32_e32 v89, v89
	s_nop 0
	v_add_f32_e32 v88, 1.0, v88
	v_add_f32_e32 v89, 1.0, v89
	s_nop 0
	v_div_scale_f32 v94, s[4:5], v89, v89, v91
	v_rcp_f32_e32 v95, v94
	s_nop 0
	v_fma_f32 v130, -v94, v95, 1.0
	v_fmac_f32_e32 v95, v130, v95
	v_div_scale_f32 v130, vcc, v91, v89, v91
	v_mul_f32_e32 v131, v130, v95
	v_fma_f32 v132, -v94, v131, v130
	v_fmac_f32_e32 v131, v132, v95
	v_fma_f32 v94, -v94, v131, v130
	v_div_fmas_f32 v94, v94, v95, v131
	v_div_fixup_f32 v131, v94, v89, v91
	v_div_scale_f32 v89, s[4:5], v88, v88, v90
	v_rcp_f32_e32 v91, v89
	s_nop 0
	v_fma_f32 v94, -v89, v91, 1.0
	v_fmac_f32_e32 v91, v94, v91
	v_div_scale_f32 v94, vcc, v90, v88, v90
	v_mul_f32_e32 v95, v94, v91
	v_fma_f32 v130, -v89, v95, v94
	v_fmac_f32_e32 v95, v130, v91
	v_fma_f32 v89, -v89, v95, v94
	v_div_fmas_f32 v89, v89, v91, v95
	global_load_dwordx2 v[94:95], v[92:93], off offset:96
	v_div_fixup_f32 v130, v89, v88, v90
	s_waitcnt vmcnt(0)
	v_lshlrev_b32_e32 v134, 16, v94
	v_and_b32_e32 v94, 0xffff0000, v94
	v_mul_f32_e32 v88, 0xbfb8aa3b, v134
	v_mul_f32_e32 v133, 0xbfb8aa3b, v94
	v_exp_f32_e32 v132, v88
	v_exp_f32_e32 v133, v133
	global_load_dwordx4 v[88:91], v176, s[6:7] offset:192
	v_add_f32_e32 v132, 1.0, v132
	v_add_f32_e32 v133, 1.0, v133
	s_nop 0
	v_div_scale_f32 v135, s[4:5], v133, v133, v94
	v_rcp_f32_e32 v136, v135
	s_nop 0
	v_fma_f32 v137, -v135, v136, 1.0
	v_fmac_f32_e32 v136, v137, v136
	v_div_scale_f32 v137, vcc, v94, v133, v94
	v_mul_f32_e32 v138, v137, v136
	v_fma_f32 v139, -v135, v138, v137
	v_fmac_f32_e32 v138, v139, v136
	v_fma_f32 v135, -v135, v138, v137
	v_div_fmas_f32 v135, v135, v136, v138
	v_div_fixup_f32 v133, v135, v133, v94
	v_div_scale_f32 v94, s[4:5], v132, v132, v134
	v_rcp_f32_e32 v135, v94
	s_nop 0
	v_fma_f32 v136, -v94, v135, 1.0
	v_fmac_f32_e32 v135, v136, v135
	v_div_scale_f32 v136, vcc, v134, v132, v134
	v_mul_f32_e32 v137, v136, v135
	v_fma_f32 v138, -v94, v137, v136
	v_fmac_f32_e32 v137, v138, v135
	v_fma_f32 v94, -v94, v137, v136
	v_div_fmas_f32 v94, v94, v135, v137
	v_div_fixup_f32 v132, v94, v132, v134
	v_lshlrev_b32_e32 v134, 16, v95
	v_and_b32_e32 v135, 0xffff0000, v95
	v_mul_f32_e32 v94, 0xbfb8aa3b, v134
	v_mul_f32_e32 v95, 0xbfb8aa3b, v135
	v_exp_f32_e32 v94, v94
	v_exp_f32_e32 v95, v95
	s_nop 0
	v_add_f32_e32 v94, 1.0, v94
	v_add_f32_e32 v95, 1.0, v95
	s_nop 0
	v_div_scale_f32 v136, s[4:5], v95, v95, v135
	v_rcp_f32_e32 v137, v136
	s_nop 0
	v_fma_f32 v138, -v136, v137, 1.0
	v_fmac_f32_e32 v137, v138, v137
	v_div_scale_f32 v138, vcc, v135, v95, v135
	v_mul_f32_e32 v139, v138, v137
	v_fma_f32 v140, -v136, v139, v138
	v_fmac_f32_e32 v139, v140, v137
	v_fma_f32 v136, -v136, v139, v138
	v_div_fmas_f32 v136, v136, v137, v139
	v_div_fixup_f32 v135, v136, v95, v135
	v_div_scale_f32 v95, s[4:5], v94, v94, v134
	v_rcp_f32_e32 v136, v95
	s_nop 0
	v_fma_f32 v137, -v95, v136, 1.0
	v_fmac_f32_e32 v136, v137, v136
	v_div_scale_f32 v137, vcc, v134, v94, v134
	v_mul_f32_e32 v138, v137, v136
	v_fma_f32 v139, -v95, v138, v137
	v_fmac_f32_e32 v138, v139, v136
	v_fma_f32 v95, -v95, v138, v137
	v_div_fmas_f32 v95, v95, v136, v138
	global_load_dwordx2 v[136:137], v[92:93], off offset:112
	v_div_fixup_f32 v134, v95, v94, v134
	s_waitcnt vmcnt(0)
	v_lshlrev_b32_e32 v140, 16, v136
	v_and_b32_e32 v136, 0xffff0000, v136
	v_mul_f32_e32 v92, 0xbfb8aa3b, v140
	v_mul_f32_e32 v139, 0xbfb8aa3b, v136
	v_exp_f32_e32 v138, v92
	v_exp_f32_e32 v139, v139
	global_load_dwordx4 v[92:95], v176, s[6:7] offset:224
	v_add_f32_e32 v138, 1.0, v138
	v_add_f32_e32 v139, 1.0, v139
	s_nop 0
	v_div_scale_f32 v141, s[4:5], v139, v139, v136
	v_rcp_f32_e32 v143, v141
	s_nop 0
	v_fma_f32 v144, -v141, v143, 1.0
	v_fmac_f32_e32 v143, v144, v143
	v_div_scale_f32 v144, vcc, v136, v139, v136
	v_mul_f32_e32 v145, v144, v143
	v_fma_f32 v146, -v141, v145, v144
	v_fmac_f32_e32 v145, v146, v143
	v_fma_f32 v141, -v141, v145, v144
	v_div_fmas_f32 v141, v141, v143, v145
	v_div_fixup_f32 v139, v141, v139, v136
	v_div_scale_f32 v136, s[4:5], v138, v138, v140
	v_rcp_f32_e32 v141, v136
	s_nop 0
	v_fma_f32 v143, -v136, v141, 1.0
	v_fmac_f32_e32 v141, v143, v141
	v_div_scale_f32 v143, vcc, v140, v138, v140
	v_mul_f32_e32 v144, v143, v141
	v_fma_f32 v145, -v136, v144, v143
	v_fmac_f32_e32 v144, v145, v141
	v_fma_f32 v136, -v136, v144, v143
	v_div_fmas_f32 v136, v136, v141, v144
	v_div_fixup_f32 v138, v136, v138, v140
	v_lshlrev_b32_e32 v140, 16, v137
	v_and_b32_e32 v141, 0xffff0000, v137
	v_mul_f32_e32 v136, 0xbfb8aa3b, v140
	v_mul_f32_e32 v137, 0xbfb8aa3b, v141
	v_exp_f32_e32 v136, v136
	v_exp_f32_e32 v137, v137
	s_nop 0
	v_add_f32_e32 v136, 1.0, v136
	v_add_f32_e32 v137, 1.0, v137
	s_nop 0
	v_div_scale_f32 v143, s[4:5], v137, v137, v141
	v_rcp_f32_e32 v144, v143
	s_nop 0
	v_fma_f32 v145, -v143, v144, 1.0
	v_fmac_f32_e32 v144, v145, v144
	v_div_scale_f32 v145, vcc, v141, v137, v141
	v_mul_f32_e32 v146, v145, v144
	v_fma_f32 v147, -v143, v146, v145
	v_fmac_f32_e32 v146, v147, v144
	v_fma_f32 v143, -v143, v146, v145
	v_div_fmas_f32 v143, v143, v144, v146
	v_div_fixup_f32 v141, v143, v137, v141
	v_div_scale_f32 v137, s[4:5], v136, v136, v140
	v_rcp_f32_e32 v143, v137
	v_mov_b32_e32 v147, v49
	s_mov_b32 s4, 0x3c800000
	v_fma_f32 v144, -v137, v143, 1.0
	v_fmac_f32_e32 v143, v144, v143
	v_div_scale_f32 v144, vcc, v140, v136, v140
	v_mul_f32_e32 v145, v144, v143
	v_fma_f32 v146, -v137, v145, v144
	v_fmac_f32_e32 v145, v146, v143
	v_fma_f32 v137, -v137, v145, v144
	v_mov_b32_e32 v146, v17
	v_div_fmas_f32 v137, v137, v143, v145
	v_mov_b32_e32 v144, v16
	v_mov_b32_e32 v145, v48
	v_mul_f32_e32 v146, v146, v146
	v_mul_f32_e32 v147, v147, v147
	v_div_fixup_f32 v140, v137, v136, v140
	v_fma_f32 v144, v144, v144, v146
	v_fma_f32 v145, v145, v145, v147
	v_mov_b32_e32 v146, v18
	v_mov_b32_e32 v147, v50
	v_fma_f32 v144, v146, v146, v144
	v_fma_f32 v145, v147, v147, v145
	v_mov_b32_e32 v146, v19
	v_mov_b32_e32 v147, v51
	v_fma_f32 v144, v146, v146, v144
	v_fma_f32 v145, v147, v147, v145
	v_mov_b32_e32 v146, v20
	v_mov_b32_e32 v147, v52
	v_fma_f32 v144, v146, v146, v144
	v_fma_f32 v145, v147, v147, v145
	v_mov_b32_e32 v146, v21
	v_mov_b32_e32 v147, v53
	v_fma_f32 v144, v146, v146, v144
	v_fma_f32 v145, v147, v147, v145
	v_mov_b32_e32 v146, v22
	v_mov_b32_e32 v147, v54
	v_fma_f32 v144, v146, v146, v144
	v_fma_f32 v145, v147, v147, v145
	v_mov_b32_e32 v146, v23
	v_mov_b32_e32 v147, v55
	v_fma_f32 v144, v146, v146, v144
	v_fma_f32 v145, v147, v147, v145
	v_mov_b32_e32 v146, v24
	v_mov_b32_e32 v147, v56
	v_fma_f32 v144, v146, v146, v144
	v_fma_f32 v145, v147, v147, v145
	v_mov_b32_e32 v146, v25
	v_mov_b32_e32 v147, v57
	v_fma_f32 v144, v146, v146, v144
	v_fma_f32 v145, v147, v147, v145
	v_mov_b32_e32 v146, v26
	v_mov_b32_e32 v147, v58
	v_fma_f32 v144, v146, v146, v144
	v_fma_f32 v145, v147, v147, v145
	v_mov_b32_e32 v146, v27
	v_mov_b32_e32 v147, v59
	v_fma_f32 v144, v146, v146, v144
	v_fma_f32 v145, v147, v147, v145
	v_mov_b32_e32 v146, v28
	v_mov_b32_e32 v147, v60
	v_fma_f32 v144, v146, v146, v144
	v_fma_f32 v145, v147, v147, v145
	v_mov_b32_e32 v146, v29
	v_mov_b32_e32 v147, v61
	v_fma_f32 v144, v146, v146, v144
	v_fma_f32 v145, v147, v147, v145
	v_mov_b32_e32 v146, v30
	v_mov_b32_e32 v147, v62
	v_fma_f32 v144, v146, v146, v144
	v_fma_f32 v145, v147, v147, v145
	v_mov_b32_e32 v146, v31
	v_mov_b32_e32 v147, v63
	v_fma_f32 v144, v146, v146, v144
	v_fma_f32 v145, v147, v147, v145
	v_mov_b32_e32 v146, v0
	v_mov_b32_e32 v147, v32
	v_fma_f32 v144, v146, v146, v144
	v_fma_f32 v145, v147, v147, v145
	v_mov_b32_e32 v146, v1
	v_mov_b32_e32 v147, v33
	v_fma_f32 v144, v146, v146, v144
	v_fma_f32 v145, v147, v147, v145
	v_mov_b32_e32 v146, v2
	v_mov_b32_e32 v147, v34
	v_fma_f32 v144, v146, v146, v144
	v_fma_f32 v145, v147, v147, v145
	v_mov_b32_e32 v146, v3
	v_mov_b32_e32 v147, v35
	v_fma_f32 v144, v146, v146, v144
	v_fma_f32 v145, v147, v147, v145
	v_mov_b32_e32 v146, v4
	v_mov_b32_e32 v147, v36
	v_fma_f32 v144, v146, v146, v144
	v_fma_f32 v145, v147, v147, v145
	v_mov_b32_e32 v146, v5
	v_mov_b32_e32 v147, v37
	v_fma_f32 v144, v146, v146, v144
	v_fma_f32 v145, v147, v147, v145
	v_mov_b32_e32 v146, v156
	v_mov_b32_e32 v147, v106
	v_add_f32_e32 v144, v146, v144
	v_add_f32_e32 v145, v147, v145
	v_mov_b32_e32 v106, v157
	v_add_f32_e32 v106, v106, v144
	v_add_f32_e32 v107, v107, v145
	v_mov_b32_e32 v144, v154
	v_mov_b32_e32 v145, v104
	v_add_f32_e32 v106, v144, v106
	v_add_f32_e32 v107, v145, v107
	v_mov_b32_e32 v104, v155
	v_add_f32_e32 v104, v104, v106
	v_add_f32_e32 v105, v105, v107
	v_mov_b32_e32 v106, v152
	v_mov_b32_e32 v107, v102
	v_add_f32_e32 v104, v106, v104
	v_add_f32_e32 v105, v107, v105
	v_mov_b32_e32 v102, v153
	v_add_f32_e32 v102, v102, v104
	v_add_f32_e32 v103, v103, v105
	v_mov_b32_e32 v104, v150
	v_mov_b32_e32 v105, v100
	v_add_f32_e32 v102, v104, v102
	v_add_f32_e32 v103, v105, v103
	v_mov_b32_e32 v100, v151
	v_add_f32_e32 v100, v100, v102
	v_add_f32_e32 v101, v101, v103
	v_mov_b32_e32 v102, v148
	v_mov_b32_e32 v103, v98
	v_add_f32_e32 v100, v102, v100
	v_add_f32_e32 v101, v103, v101
	v_mov_b32_e32 v98, v149
	v_add_f32_e32 v98, v98, v100
	v_add_f32_e32 v99, v99, v101
	ds_bpermute_b32 v101, v142, v99
	ds_bpermute_b32 v100, v142, v98
	v_lshl_add_u64 v[136:137], s[78:79], 0, v[182:183]
	s_waitcnt lgkmcnt(0)
	v_add_f32_e32 v98, v98, v100
	v_add_f32_e32 v99, v99, v101
	s_nop 0
	v_fma_f32 v98, v98, s4, v178
	v_fma_f32 v99, v99, s4, v178
	s_nop 0
	v_mul_f32_e32 v100, 0x4b800000, v99
	v_cmp_gt_f32_e64 s[4:5], s44, v99
	v_cmp_gt_f32_e32 vcc, s44, v98
	s_nop 0
	v_cndmask_b32_e64 v99, v99, v100, s[4:5]
	v_rsq_f32_e32 v99, v99
	s_nop 0
	v_mul_f32_e32 v100, 0x45800000, v99
	v_cndmask_b32_e64 v100, v99, v100, s[4:5]
	v_mul_f32_e32 v32, v32, v100
	v_mul_f32_e32 v33, v33, v100
	v_mul_f32_e32 v34, v34, v100
	v_mul_f32_e32 v35, v35, v100
	v_mul_f32_e32 v32, v32, v80
	v_mul_f32_e32 v33, v33, v81
	v_mul_f32_e32 v34, v34, v82
	v_mul_f32_e32 v35, v35, v83
	v_mul_f32_e32 v36, v36, v100
	v_mul_f32_e32 v37, v37, v100
	v_mul_f32_e32 v38, v38, v100
	v_mul_f32_e32 v39, v39, v100
	v_mul_f32_e32 v32, v32, v124
	v_mul_f32_e32 v33, v33, v125
	v_mul_f32_e32 v34, v34, v126
	v_mul_f32_e32 v35, v35, v127
	v_mul_f32_e32 v36, v36, v84
	v_mul_f32_e32 v37, v37, v85
	v_mul_f32_e32 v38, v38, v86
	v_mul_f32_e32 v39, v39, v87
	v_mul_f32_e32 v40, v40, v100
	v_mul_f32_e32 v41, v41, v100
	v_mul_f32_e32 v42, v42, v100
	v_mul_f32_e32 v43, v43, v100
	v_mul_f32_e32 v36, v36, v128
	v_mul_f32_e32 v37, v37, v129
	v_mul_f32_e32 v38, v38, v130
	v_mul_f32_e32 v39, v39, v131
	v_mul_f32_e32 v40, v40, v88
	v_mul_f32_e32 v41, v41, v89
	v_mul_f32_e32 v42, v42, v90
	v_mul_f32_e32 v43, v43, v91
	v_mul_f32_e32 v44, v44, v100
	v_mul_f32_e32 v45, v45, v100
	v_mul_f32_e32 v46, v46, v100
	v_mul_f32_e32 v47, v47, v100
	v_cvt_pk_bf16_f32 v32, v32, v33
	v_cvt_pk_bf16_f32 v33, v34, v35
	v_mul_f32_e32 v40, v40, v132
	v_mul_f32_e32 v41, v41, v133
	v_mul_f32_e32 v42, v42, v134
	v_mul_f32_e32 v43, v43, v135
	s_waitcnt vmcnt(0)
	v_mul_f32_e32 v44, v44, v92
	v_mul_f32_e32 v45, v45, v93
	v_mul_f32_e32 v46, v46, v94
	v_mul_f32_e32 v47, v47, v95
	global_store_dwordx2 v[96:97], v[32:33], off offset:2624
	v_cvt_pk_bf16_f32 v32, v36, v37
	v_cvt_pk_bf16_f32 v33, v38, v39
	v_mul_f32_e32 v44, v44, v138
	v_mul_f32_e32 v45, v45, v139
	v_mul_f32_e32 v46, v46, v140
	v_mul_f32_e32 v47, v47, v141
	global_store_dwordx2 v[96:97], v[32:33], off offset:2640
	v_cvt_pk_bf16_f32 v32, v40, v41
	v_cvt_pk_bf16_f32 v33, v42, v43
	global_store_dwordx2 v[96:97], v[32:33], off offset:2656
	v_cvt_pk_bf16_f32 v32, v44, v45
	v_cvt_pk_bf16_f32 v33, v46, v47
	global_store_dwordx2 v[96:97], v[32:33], off offset:2672
	v_mul_f32_e32 v32, 0x4b800000, v98
	v_cndmask_b32_e32 v32, v98, v32, vcc
	v_rsq_f32_e32 v32, v32
	v_mul_f32_e32 v48, v48, v100
	v_mul_f32_e32 v49, v49, v100
	v_mul_f32_e32 v50, v50, v100
	v_mul_f32_e32 v51, v51, v100
	v_mul_f32_e32 v48, v64, v48
	v_mul_f32_e32 v49, v65, v49
	v_mul_f32_e32 v33, 0x45800000, v32
	v_cndmask_b32_e32 v34, v32, v33, vcc
	v_lshl_add_u64 v[32:33], v[136:137], 0, s[8:9]
	v_lshl_add_u64 v[32:33], v[32:33], 0, v[180:181]
	v_add_co_u32_e32 v36, vcc, s10, v32
	v_mul_f32_e32 v50, v66, v50
	v_mul_f32_e32 v51, v67, v51
	s_nop 0
	v_addc_co_u32_e32 v37, vcc, 0, v33, vcc
	global_load_dwordx2 v[42:43], v[36:37], off
	v_mul_f32_e32 v52, v52, v100
	v_mul_f32_e32 v53, v53, v100
	v_mul_f32_e32 v54, v54, v100
	v_mul_f32_e32 v55, v55, v100
	v_mul_f32_e32 v48, v108, v48
	v_mul_f32_e32 v49, v109, v49
	v_mul_f32_e32 v50, v110, v50
	v_mul_f32_e32 v51, v111, v51
	v_mul_f32_e32 v52, v68, v52
	v_mul_f32_e32 v53, v69, v53
	v_mul_f32_e32 v54, v70, v54
	v_mul_f32_e32 v55, v71, v55
	v_mul_f32_e32 v56, v56, v100
	v_mul_f32_e32 v57, v57, v100
	v_mul_f32_e32 v58, v58, v100
	v_mul_f32_e32 v59, v59, v100
	v_mul_f32_e32 v52, v52, v112
	v_mul_f32_e32 v53, v53, v113
	v_mul_f32_e32 v54, v54, v114
	v_mul_f32_e32 v55, v55, v115
	v_mul_f32_e32 v56, v56, v72
	v_mul_f32_e32 v57, v57, v73
	v_mul_f32_e32 v58, v58, v74
	v_mul_f32_e32 v59, v59, v75
	v_mul_f32_e32 v60, v60, v100
	v_mul_f32_e32 v61, v61, v100
	v_mul_f32_e32 v62, v62, v100
	v_mul_f32_e32 v63, v63, v100
	v_cvt_pk_bf16_f32 v48, v48, v49
	v_cvt_pk_bf16_f32 v49, v50, v51
	v_mul_f32_e32 v56, v56, v116
	v_mul_f32_e32 v57, v57, v117
	v_mul_f32_e32 v58, v58, v118
	v_mul_f32_e32 v59, v59, v119
	v_mul_f32_e32 v60, v60, v76
	v_mul_f32_e32 v61, v61, v77
	v_mul_f32_e32 v62, v62, v78
	v_mul_f32_e32 v63, v63, v79
	global_store_dwordx2 v[96:97], v[48:49], off offset:2560
	v_cvt_pk_bf16_f32 v48, v52, v53
	v_cvt_pk_bf16_f32 v49, v54, v55
	v_mul_f32_e32 v60, v60, v120
	v_mul_f32_e32 v61, v61, v121
	v_mul_f32_e32 v62, v62, v122
	v_mul_f32_e32 v63, v63, v123
	global_store_dwordx2 v[96:97], v[48:49], off offset:2576
	v_cvt_pk_bf16_f32 v48, v56, v57
	v_cvt_pk_bf16_f32 v49, v58, v59
	global_store_dwordx2 v[96:97], v[48:49], off offset:2592
	v_cvt_pk_bf16_f32 v48, v60, v61
	v_cvt_pk_bf16_f32 v49, v62, v63
	global_store_dwordx2 v[96:97], v[48:49], off offset:2608
	v_lshl_add_u64 v[40:41], v[32:33], 0, s[64:65]
	s_waitcnt vmcnt(4)
	v_lshlrev_b32_e32 v35, 16, v42
	v_mul_f32_e32 v36, 0xbfb8aa3b, v35
	v_exp_f32_e32 v44, v36
	global_load_dwordx4 v[36:39], v176, s[6:7]
	v_and_b32_e32 v42, 0xffff0000, v42
	v_mul_f32_e32 v16, v16, v34
	v_mul_f32_e32 v17, v17, v34
	s_waitcnt vmcnt(0)
	v_mul_f32_e32 v16, v36, v16
	v_mul_f32_e32 v17, v37, v17
	v_mul_f32_e32 v36, 0xbfb8aa3b, v42
	v_exp_f32_e32 v45, v36
	s_nop 0
	v_add_f32_e32 v36, 1.0, v44
	v_add_f32_e32 v37, 1.0, v45
	s_nop 0
	v_div_scale_f32 v44, s[4:5], v37, v37, v42
	v_rcp_f32_e32 v45, v44
	s_nop 0
	v_fma_f32 v46, -v44, v45, 1.0
	v_fmac_f32_e32 v45, v46, v45
	v_div_scale_f32 v46, vcc, v42, v37, v42
	v_mul_f32_e32 v47, v46, v45
	v_fma_f32 v48, -v44, v47, v46
	v_fmac_f32_e32 v47, v48, v45
	v_fma_f32 v44, -v44, v47, v46
	v_div_fmas_f32 v44, v44, v45, v47
	v_div_fixup_f32 v37, v44, v37, v42
	v_div_scale_f32 v42, s[4:5], v36, v36, v35
	v_rcp_f32_e32 v44, v42
	s_nop 0
	v_fma_f32 v45, -v42, v44, 1.0
	v_fmac_f32_e32 v44, v45, v44
	v_div_scale_f32 v45, vcc, v35, v36, v35
	v_mul_f32_e32 v46, v45, v44
	v_fma_f32 v47, -v42, v46, v45
	v_fmac_f32_e32 v46, v47, v44
	v_fma_f32 v42, -v42, v46, v45
	v_div_fmas_f32 v42, v42, v44, v46
	v_div_fixup_f32 v36, v42, v36, v35
	v_lshlrev_b32_e32 v35, 16, v43
	v_and_b32_e32 v42, 0xffff0000, v43
	v_mul_f32_e32 v16, v36, v16
	v_mul_f32_e32 v17, v37, v17
	v_mul_f32_e32 v36, 0xbfb8aa3b, v35
	v_mul_f32_e32 v37, 0xbfb8aa3b, v42
	v_exp_f32_e32 v36, v36
	v_exp_f32_e32 v37, v37
	v_mul_f32_e32 v18, v18, v34
	v_mul_f32_e32 v19, v19, v34
	v_add_f32_e32 v36, 1.0, v36
	v_add_f32_e32 v37, 1.0, v37
	v_mul_f32_e32 v18, v38, v18
	v_mul_f32_e32 v19, v39, v19
	v_div_scale_f32 v38, s[4:5], v37, v37, v42
	v_rcp_f32_e32 v39, v38
	s_nop 0
	v_fma_f32 v43, -v38, v39, 1.0
	v_fmac_f32_e32 v39, v43, v39
	v_div_scale_f32 v43, vcc, v42, v37, v42
	v_mul_f32_e32 v44, v43, v39
	v_fma_f32 v45, -v38, v44, v43
	v_fmac_f32_e32 v44, v45, v39
	v_fma_f32 v38, -v38, v44, v43
	v_div_fmas_f32 v38, v38, v39, v44
	v_div_fixup_f32 v37, v38, v37, v42
	v_div_scale_f32 v38, s[4:5], v36, v36, v35
	v_rcp_f32_e32 v39, v38
	s_nop 0
	v_fma_f32 v42, -v38, v39, 1.0
	v_fmac_f32_e32 v39, v42, v39
	v_div_scale_f32 v42, vcc, v35, v36, v35
	v_mul_f32_e32 v43, v42, v39
	v_fma_f32 v44, -v38, v43, v42
	v_fmac_f32_e32 v43, v44, v39
	v_fma_f32 v38, -v38, v43, v42
	v_div_fmas_f32 v38, v38, v39, v43
	global_load_dwordx2 v[42:43], v[40:41], off offset:16
	v_div_fixup_f32 v36, v38, v36, v35
	v_mul_f32_e32 v18, v36, v18
	v_mul_f32_e32 v19, v37, v19
	s_waitcnt vmcnt(0)
	v_lshlrev_b32_e32 v35, 16, v42
	v_mul_f32_e32 v36, 0xbfb8aa3b, v35
	v_exp_f32_e32 v44, v36
	global_load_dwordx4 v[36:39], v176, s[6:7] offset:32
	v_and_b32_e32 v42, 0xffff0000, v42
	v_mul_f32_e32 v20, v20, v34
	v_mul_f32_e32 v21, v21, v34
	s_waitcnt vmcnt(0)
	v_mul_f32_e32 v20, v36, v20
	v_mul_f32_e32 v21, v37, v21
	v_mul_f32_e32 v36, 0xbfb8aa3b, v42
	v_exp_f32_e32 v45, v36
	s_nop 0
	v_add_f32_e32 v36, 1.0, v44
	v_add_f32_e32 v37, 1.0, v45
	s_nop 0
	v_div_scale_f32 v44, s[4:5], v37, v37, v42
	v_rcp_f32_e32 v45, v44
	s_nop 0
	v_fma_f32 v46, -v44, v45, 1.0
	v_fmac_f32_e32 v45, v46, v45
	v_div_scale_f32 v46, vcc, v42, v37, v42
	v_mul_f32_e32 v47, v46, v45
	v_fma_f32 v48, -v44, v47, v46
	v_fmac_f32_e32 v47, v48, v45
	v_fma_f32 v44, -v44, v47, v46
	v_div_fmas_f32 v44, v44, v45, v47
	v_div_fixup_f32 v37, v44, v37, v42
	v_div_scale_f32 v42, s[4:5], v36, v36, v35
	v_rcp_f32_e32 v44, v42
	s_nop 0
	v_fma_f32 v45, -v42, v44, 1.0
	v_fmac_f32_e32 v44, v45, v44
	v_div_scale_f32 v45, vcc, v35, v36, v35
	v_mul_f32_e32 v46, v45, v44
	v_fma_f32 v47, -v42, v46, v45
	v_fmac_f32_e32 v46, v47, v44
	v_fma_f32 v42, -v42, v46, v45
	v_div_fmas_f32 v42, v42, v44, v46
	v_div_fixup_f32 v36, v42, v36, v35
	v_lshlrev_b32_e32 v35, 16, v43
	v_and_b32_e32 v42, 0xffff0000, v43
	v_mul_f32_e32 v20, v20, v36
	v_mul_f32_e32 v21, v21, v37
	v_mul_f32_e32 v36, 0xbfb8aa3b, v35
	v_mul_f32_e32 v37, 0xbfb8aa3b, v42
	v_exp_f32_e32 v36, v36
	v_exp_f32_e32 v37, v37
	v_mul_f32_e32 v22, v22, v34
	v_mul_f32_e32 v23, v23, v34
	v_add_f32_e32 v36, 1.0, v36
	v_add_f32_e32 v37, 1.0, v37
	v_mul_f32_e32 v22, v38, v22
	v_mul_f32_e32 v23, v39, v23
	v_div_scale_f32 v38, s[4:5], v37, v37, v42
	v_rcp_f32_e32 v39, v38
	s_nop 0
	v_fma_f32 v43, -v38, v39, 1.0
	v_fmac_f32_e32 v39, v43, v39
	v_div_scale_f32 v43, vcc, v42, v37, v42
	v_mul_f32_e32 v44, v43, v39
	v_fma_f32 v45, -v38, v44, v43
	v_fmac_f32_e32 v44, v45, v39
	v_fma_f32 v38, -v38, v44, v43
	v_div_fmas_f32 v38, v38, v39, v44
	v_div_fixup_f32 v37, v38, v37, v42
	v_div_scale_f32 v38, s[4:5], v36, v36, v35
	v_rcp_f32_e32 v39, v38
	s_nop 0
	v_fma_f32 v42, -v38, v39, 1.0
	v_fmac_f32_e32 v39, v42, v39
	v_div_scale_f32 v42, vcc, v35, v36, v35
	v_mul_f32_e32 v43, v42, v39
	v_fma_f32 v44, -v38, v43, v42
	v_fmac_f32_e32 v43, v44, v39
	v_fma_f32 v38, -v38, v43, v42
	v_div_fmas_f32 v38, v38, v39, v43
	global_load_dwordx2 v[42:43], v[40:41], off offset:32
	v_div_fixup_f32 v36, v38, v36, v35
	v_mul_f32_e32 v22, v22, v36
	v_mul_f32_e32 v23, v23, v37
	s_waitcnt vmcnt(0)
	v_lshlrev_b32_e32 v35, 16, v42
	v_mul_f32_e32 v36, 0xbfb8aa3b, v35
	v_exp_f32_e32 v44, v36
	global_load_dwordx4 v[36:39], v176, s[6:7] offset:64
	v_and_b32_e32 v42, 0xffff0000, v42
	v_mul_f32_e32 v24, v24, v34
	v_mul_f32_e32 v25, v25, v34
	s_waitcnt vmcnt(0)
	v_mul_f32_e32 v24, v24, v36
	v_mul_f32_e32 v25, v25, v37
	v_mul_f32_e32 v36, 0xbfb8aa3b, v42
	v_exp_f32_e32 v45, v36
	s_nop 0
	v_add_f32_e32 v36, 1.0, v44
	v_add_f32_e32 v37, 1.0, v45
	s_nop 0
	v_div_scale_f32 v44, s[4:5], v37, v37, v42
	v_rcp_f32_e32 v45, v44
	s_nop 0
	v_fma_f32 v46, -v44, v45, 1.0
	v_fmac_f32_e32 v45, v46, v45
	v_div_scale_f32 v46, vcc, v42, v37, v42
	v_mul_f32_e32 v47, v46, v45
	v_fma_f32 v48, -v44, v47, v46
	v_fmac_f32_e32 v47, v48, v45
	v_fma_f32 v44, -v44, v47, v46
	v_div_fmas_f32 v44, v44, v45, v47
	v_div_fixup_f32 v37, v44, v37, v42
	v_div_scale_f32 v42, s[4:5], v36, v36, v35
	v_rcp_f32_e32 v44, v42
	s_nop 0
	v_fma_f32 v45, -v42, v44, 1.0
	v_fmac_f32_e32 v44, v45, v44
	v_div_scale_f32 v45, vcc, v35, v36, v35
	v_mul_f32_e32 v46, v45, v44
	v_fma_f32 v47, -v42, v46, v45
	v_fmac_f32_e32 v46, v47, v44
	v_fma_f32 v42, -v42, v46, v45
	v_div_fmas_f32 v42, v42, v44, v46
	v_div_fixup_f32 v36, v42, v36, v35
	v_lshlrev_b32_e32 v35, 16, v43
	v_and_b32_e32 v42, 0xffff0000, v43
	v_mul_f32_e32 v24, v24, v36
	v_mul_f32_e32 v25, v25, v37
	v_mul_f32_e32 v36, 0xbfb8aa3b, v35
	v_mul_f32_e32 v37, 0xbfb8aa3b, v42
	v_exp_f32_e32 v36, v36
	v_exp_f32_e32 v37, v37
	v_mul_f32_e32 v26, v26, v34
	v_mul_f32_e32 v27, v27, v34
	v_add_f32_e32 v36, 1.0, v36
	v_add_f32_e32 v37, 1.0, v37
	v_mul_f32_e32 v26, v26, v38
	v_mul_f32_e32 v27, v27, v39
	v_div_scale_f32 v38, s[4:5], v37, v37, v42
	v_rcp_f32_e32 v39, v38
	s_nop 0
	v_fma_f32 v43, -v38, v39, 1.0
	v_fmac_f32_e32 v39, v43, v39
	v_div_scale_f32 v43, vcc, v42, v37, v42
	v_mul_f32_e32 v44, v43, v39
	v_fma_f32 v45, -v38, v44, v43
	v_fmac_f32_e32 v44, v45, v39
	v_fma_f32 v38, -v38, v44, v43
	v_div_fmas_f32 v38, v38, v39, v44
	v_div_fixup_f32 v37, v38, v37, v42
	v_div_scale_f32 v38, s[4:5], v36, v36, v35
	v_rcp_f32_e32 v39, v38
	s_nop 0
	v_fma_f32 v42, -v38, v39, 1.0
	v_fmac_f32_e32 v39, v42, v39
	v_div_scale_f32 v42, vcc, v35, v36, v35
	v_mul_f32_e32 v43, v42, v39
	v_fma_f32 v44, -v38, v43, v42
	v_fmac_f32_e32 v43, v44, v39
	v_fma_f32 v38, -v38, v43, v42
	v_div_fmas_f32 v38, v38, v39, v43
	global_load_dwordx2 v[42:43], v[40:41], off offset:48
	v_div_fixup_f32 v36, v38, v36, v35
	v_mul_f32_e32 v26, v26, v36
	v_mul_f32_e32 v27, v27, v37
	s_waitcnt vmcnt(0)
	v_lshlrev_b32_e32 v35, 16, v42
	v_mul_f32_e32 v36, 0xbfb8aa3b, v35
	v_exp_f32_e32 v44, v36
	global_load_dwordx4 v[36:39], v176, s[6:7] offset:96
	v_and_b32_e32 v42, 0xffff0000, v42
	v_mul_f32_e32 v28, v28, v34
	v_mul_f32_e32 v29, v29, v34
	s_waitcnt vmcnt(0)
	v_mul_f32_e32 v28, v28, v36
	v_mul_f32_e32 v29, v29, v37
	v_mul_f32_e32 v36, 0xbfb8aa3b, v42
	v_exp_f32_e32 v45, v36
	s_nop 0
	v_add_f32_e32 v36, 1.0, v44
	v_add_f32_e32 v37, 1.0, v45
	s_nop 0
	v_div_scale_f32 v44, s[4:5], v37, v37, v42
	v_rcp_f32_e32 v45, v44
	s_nop 0
	v_fma_f32 v46, -v44, v45, 1.0
	v_fmac_f32_e32 v45, v46, v45
	v_div_scale_f32 v46, vcc, v42, v37, v42
	v_mul_f32_e32 v47, v46, v45
	v_fma_f32 v48, -v44, v47, v46
	v_fmac_f32_e32 v47, v48, v45
	v_fma_f32 v44, -v44, v47, v46
	v_div_fmas_f32 v44, v44, v45, v47
	v_div_fixup_f32 v37, v44, v37, v42
	v_div_scale_f32 v42, s[4:5], v36, v36, v35
	v_rcp_f32_e32 v44, v42
	s_nop 0
	v_fma_f32 v45, -v42, v44, 1.0
	v_fmac_f32_e32 v44, v45, v44
	v_div_scale_f32 v45, vcc, v35, v36, v35
	v_mul_f32_e32 v46, v45, v44
	v_fma_f32 v47, -v42, v46, v45
	v_fmac_f32_e32 v46, v47, v44
	v_fma_f32 v42, -v42, v46, v45
	v_div_fmas_f32 v42, v42, v44, v46
	v_div_fixup_f32 v36, v42, v36, v35
	v_lshlrev_b32_e32 v35, 16, v43
	v_and_b32_e32 v42, 0xffff0000, v43
	v_mul_f32_e32 v28, v28, v36
	v_mul_f32_e32 v29, v29, v37
	v_mul_f32_e32 v36, 0xbfb8aa3b, v35
	v_mul_f32_e32 v37, 0xbfb8aa3b, v42
	v_exp_f32_e32 v36, v36
	v_exp_f32_e32 v37, v37
	v_mul_f32_e32 v30, v30, v34
	v_mul_f32_e32 v31, v31, v34
	v_add_f32_e32 v36, 1.0, v36
	v_add_f32_e32 v37, 1.0, v37
	v_mul_f32_e32 v30, v30, v38
	v_mul_f32_e32 v31, v31, v39
	v_div_scale_f32 v38, s[4:5], v37, v37, v42
	v_rcp_f32_e32 v39, v38
	s_nop 0
	v_fma_f32 v43, -v38, v39, 1.0
	v_fmac_f32_e32 v39, v43, v39
	v_div_scale_f32 v43, vcc, v42, v37, v42
	v_mul_f32_e32 v44, v43, v39
	v_fma_f32 v45, -v38, v44, v43
	v_fmac_f32_e32 v44, v45, v39
	v_fma_f32 v38, -v38, v44, v43
	v_div_fmas_f32 v38, v38, v39, v44
	v_div_fixup_f32 v37, v38, v37, v42
	v_div_scale_f32 v38, s[4:5], v36, v36, v35
	v_rcp_f32_e32 v39, v38
	s_nop 0
	v_fma_f32 v42, -v38, v39, 1.0
	v_fmac_f32_e32 v39, v42, v39
	v_div_scale_f32 v42, vcc, v35, v36, v35
	v_mul_f32_e32 v43, v42, v39
	v_fma_f32 v44, -v38, v43, v42
	v_fmac_f32_e32 v43, v44, v39
	v_fma_f32 v38, -v38, v43, v42
	v_div_fmas_f32 v38, v38, v39, v43
	global_load_dwordx2 v[42:43], v[40:41], off offset:64
	v_div_fixup_f32 v36, v38, v36, v35
	v_mul_f32_e32 v30, v30, v36
	v_mul_f32_e32 v31, v31, v37
	s_waitcnt vmcnt(0)
	v_lshlrev_b32_e32 v35, 16, v42
	v_mul_f32_e32 v36, 0xbfb8aa3b, v35
	v_exp_f32_e32 v44, v36
	global_load_dwordx4 v[36:39], v176, s[6:7] offset:128
	v_and_b32_e32 v42, 0xffff0000, v42
	v_mul_f32_e32 v0, v0, v34
	v_mul_f32_e32 v1, v1, v34
	s_waitcnt vmcnt(0)
	v_mul_f32_e32 v0, v0, v36
	v_mul_f32_e32 v1, v1, v37
	v_mul_f32_e32 v36, 0xbfb8aa3b, v42
	v_exp_f32_e32 v45, v36
	s_nop 0
	v_add_f32_e32 v36, 1.0, v44
	v_add_f32_e32 v37, 1.0, v45
	s_nop 0
	v_div_scale_f32 v44, s[4:5], v37, v37, v42
	v_rcp_f32_e32 v45, v44
	s_nop 0
	v_fma_f32 v46, -v44, v45, 1.0
	v_fmac_f32_e32 v45, v46, v45
	v_div_scale_f32 v46, vcc, v42, v37, v42
	v_mul_f32_e32 v47, v46, v45
	v_fma_f32 v48, -v44, v47, v46
	v_fmac_f32_e32 v47, v48, v45
	v_fma_f32 v44, -v44, v47, v46
	v_div_fmas_f32 v44, v44, v45, v47
	v_div_fixup_f32 v37, v44, v37, v42
	v_div_scale_f32 v42, s[4:5], v36, v36, v35
	v_rcp_f32_e32 v44, v42
	s_nop 0
	v_fma_f32 v45, -v42, v44, 1.0
	v_fmac_f32_e32 v44, v45, v44
	v_div_scale_f32 v45, vcc, v35, v36, v35
	v_mul_f32_e32 v46, v45, v44
	v_fma_f32 v47, -v42, v46, v45
	v_fmac_f32_e32 v46, v47, v44
	v_fma_f32 v42, -v42, v46, v45
	v_div_fmas_f32 v42, v42, v44, v46
	v_div_fixup_f32 v36, v42, v36, v35
	v_lshlrev_b32_e32 v35, 16, v43
	v_and_b32_e32 v42, 0xffff0000, v43
	v_mul_f32_e32 v36, v0, v36
	v_mul_f32_e32 v37, v1, v37
	v_mul_f32_e32 v0, 0xbfb8aa3b, v35
	v_mul_f32_e32 v1, 0xbfb8aa3b, v42
	v_exp_f32_e32 v0, v0
	v_exp_f32_e32 v1, v1
	v_mul_f32_e32 v2, v2, v34
	v_mul_f32_e32 v3, v3, v34
	v_add_f32_e32 v0, 1.0, v0
	v_add_f32_e32 v1, 1.0, v1
	v_mul_f32_e32 v2, v2, v38
	v_mul_f32_e32 v3, v3, v39
	v_div_scale_f32 v38, s[4:5], v1, v1, v42
	v_rcp_f32_e32 v39, v38
	s_nop 0
	v_fma_f32 v43, -v38, v39, 1.0
	v_fmac_f32_e32 v39, v43, v39
	v_div_scale_f32 v43, vcc, v42, v1, v42
	v_mul_f32_e32 v44, v43, v39
	v_fma_f32 v45, -v38, v44, v43
	v_fmac_f32_e32 v44, v45, v39
	v_fma_f32 v38, -v38, v44, v43
	v_div_fmas_f32 v38, v38, v39, v44
	v_div_fixup_f32 v1, v38, v1, v42
	v_div_scale_f32 v38, s[4:5], v0, v0, v35
	v_rcp_f32_e32 v39, v38
	s_nop 0
	v_fma_f32 v42, -v38, v39, 1.0
	v_fmac_f32_e32 v39, v42, v39
	v_div_scale_f32 v42, vcc, v35, v0, v35
	v_mul_f32_e32 v43, v42, v39
	v_fma_f32 v44, -v38, v43, v42
	v_fmac_f32_e32 v43, v44, v39
	v_fma_f32 v38, -v38, v43, v42
	v_div_fmas_f32 v38, v38, v39, v43
	global_load_dwordx2 v[42:43], v[40:41], off offset:80
	v_div_fixup_f32 v0, v38, v0, v35
	v_mul_f32_e32 v38, v2, v0
	v_mul_f32_e32 v39, v3, v1
	s_waitcnt vmcnt(0)
	v_lshlrev_b32_e32 v35, 16, v42
	v_mul_f32_e32 v0, 0xbfb8aa3b, v35
	v_exp_f32_e32 v44, v0
	global_load_dwordx4 v[0:3], v176, s[6:7] offset:160
	v_and_b32_e32 v42, 0xffff0000, v42
	v_mul_f32_e32 v4, v4, v34
	v_mul_f32_e32 v5, v5, v34
	s_waitcnt vmcnt(0)
	v_mul_f32_e32 v0, v4, v0
	v_mul_f32_e32 v1, v5, v1
	v_mul_f32_e32 v4, 0xbfb8aa3b, v42
	v_exp_f32_e32 v45, v4
	s_nop 0
	v_add_f32_e32 v4, 1.0, v44
	v_add_f32_e32 v5, 1.0, v45
	s_nop 0
	v_div_scale_f32 v44, s[4:5], v5, v5, v42
	v_rcp_f32_e32 v45, v44
	s_nop 0
	v_fma_f32 v46, -v44, v45, 1.0
	v_fmac_f32_e32 v45, v46, v45
	v_div_scale_f32 v46, vcc, v42, v5, v42
	v_mul_f32_e32 v47, v46, v45
	v_fma_f32 v48, -v44, v47, v46
	v_fmac_f32_e32 v47, v48, v45
	v_fma_f32 v44, -v44, v47, v46
	v_div_fmas_f32 v44, v44, v45, v47
	v_div_fixup_f32 v5, v44, v5, v42
	v_div_scale_f32 v42, s[4:5], v4, v4, v35
	v_rcp_f32_e32 v44, v42
	s_nop 0
	v_fma_f32 v45, -v42, v44, 1.0
	v_fmac_f32_e32 v44, v45, v44
	v_div_scale_f32 v45, vcc, v35, v4, v35
	v_mul_f32_e32 v46, v45, v44
	v_fma_f32 v47, -v42, v46, v45
	v_fmac_f32_e32 v46, v47, v44
	v_fma_f32 v42, -v42, v46, v45
	v_div_fmas_f32 v42, v42, v44, v46
	v_div_fixup_f32 v4, v42, v4, v35
	v_lshlrev_b32_e32 v35, 16, v43
	v_and_b32_e32 v42, 0xffff0000, v43
	v_mul_f32_e32 v4, v0, v4
	v_mul_f32_e32 v5, v1, v5
	v_mul_f32_e32 v0, 0xbfb8aa3b, v35
	v_mul_f32_e32 v1, 0xbfb8aa3b, v42
	v_exp_f32_e32 v0, v0
	v_exp_f32_e32 v1, v1
	v_mul_f32_e32 v6, v6, v34
	v_mul_f32_e32 v7, v7, v34
	v_cvt_pk_bf16_f32 v4, v4, v5
	v_mul_f32_e32 v2, v6, v2
	v_mul_f32_e32 v3, v7, v3
	v_add_f32_e32 v0, 1.0, v0
	v_add_f32_e32 v1, 1.0, v1
	s_nop 0
	v_div_scale_f32 v6, s[4:5], v1, v1, v42
	v_rcp_f32_e32 v7, v6
	s_nop 0
	v_fma_f32 v43, -v6, v7, 1.0
	v_fmac_f32_e32 v7, v43, v7
	v_div_scale_f32 v43, vcc, v42, v1, v42
	v_mul_f32_e32 v44, v43, v7
	v_fma_f32 v45, -v6, v44, v43
	v_fmac_f32_e32 v44, v45, v7
	v_fma_f32 v6, -v6, v44, v43
	v_div_fmas_f32 v6, v6, v7, v44
	v_div_fixup_f32 v1, v6, v1, v42
	v_div_scale_f32 v6, s[4:5], v0, v0, v35
	v_rcp_f32_e32 v7, v6
	s_nop 0
	v_fma_f32 v42, -v6, v7, 1.0
	v_fmac_f32_e32 v7, v42, v7
	v_div_scale_f32 v42, vcc, v35, v0, v35
	v_mul_f32_e32 v43, v42, v7
	v_fma_f32 v44, -v6, v43, v42
	v_fmac_f32_e32 v43, v44, v7
	v_fma_f32 v6, -v6, v43, v42
	v_div_fmas_f32 v6, v6, v7, v43
	global_load_dwordx2 v[42:43], v[40:41], off offset:96
	v_div_fixup_f32 v0, v6, v0, v35
	v_mul_f32_e32 v6, v2, v0
	v_mul_f32_e32 v7, v3, v1
	global_load_dwordx2 v[40:41], v[40:41], off offset:112
	v_cvt_pk_bf16_f32 v5, v6, v7
	s_waitcnt vmcnt(1)
	v_lshlrev_b32_e32 v35, 16, v42
	v_mul_f32_e32 v0, 0xbfb8aa3b, v35
	v_exp_f32_e32 v44, v0
	global_load_dwordx4 v[0:3], v176, s[6:7] offset:192
	v_and_b32_e32 v42, 0xffff0000, v42
	v_mul_f32_e32 v8, v8, v34
	v_mul_f32_e32 v9, v9, v34
	s_waitcnt vmcnt(0)
	v_mul_f32_e32 v0, v8, v0
	v_mul_f32_e32 v1, v9, v1
	v_mul_f32_e32 v8, 0xbfb8aa3b, v42
	v_exp_f32_e32 v45, v8
	s_nop 0
	v_add_f32_e32 v8, 1.0, v44
	v_add_f32_e32 v9, 1.0, v45
	s_nop 0
	v_div_scale_f32 v44, s[4:5], v9, v9, v42
	v_rcp_f32_e32 v45, v44
	s_nop 0
	v_fma_f32 v46, -v44, v45, 1.0
	v_fmac_f32_e32 v45, v46, v45
	v_div_scale_f32 v46, vcc, v42, v9, v42
	v_mul_f32_e32 v47, v46, v45
	v_fma_f32 v48, -v44, v47, v46
	v_fmac_f32_e32 v47, v48, v45
	v_fma_f32 v44, -v44, v47, v46
	v_div_fmas_f32 v44, v44, v45, v47
	v_div_fixup_f32 v9, v44, v9, v42
	v_div_scale_f32 v42, s[4:5], v8, v8, v35
	v_rcp_f32_e32 v44, v42
	s_nop 0
	v_fma_f32 v45, -v42, v44, 1.0
	v_fmac_f32_e32 v44, v45, v44
	v_div_scale_f32 v45, vcc, v35, v8, v35
	v_mul_f32_e32 v46, v45, v44
	v_fma_f32 v47, -v42, v46, v45
	v_fmac_f32_e32 v46, v47, v44
	v_fma_f32 v42, -v42, v46, v45
	v_div_fmas_f32 v42, v42, v44, v46
	v_div_fixup_f32 v8, v42, v8, v35
	v_lshlrev_b32_e32 v35, 16, v43
	v_and_b32_e32 v42, 0xffff0000, v43
	v_mul_f32_e32 v8, v0, v8
	v_mul_f32_e32 v9, v1, v9
	v_mul_f32_e32 v0, 0xbfb8aa3b, v35
	v_mul_f32_e32 v1, 0xbfb8aa3b, v42
	v_exp_f32_e32 v0, v0
	v_exp_f32_e32 v1, v1
	v_mul_f32_e32 v10, v10, v34
	v_mul_f32_e32 v11, v11, v34
	v_add_f32_e32 v0, 1.0, v0
	v_add_f32_e32 v1, 1.0, v1
	v_mul_f32_e32 v2, v10, v2
	v_mul_f32_e32 v3, v11, v3
	v_div_scale_f32 v10, s[4:5], v1, v1, v42
	v_rcp_f32_e32 v11, v10
	s_nop 0
	v_fma_f32 v43, -v10, v11, 1.0
	v_fmac_f32_e32 v11, v43, v11
	v_div_scale_f32 v43, vcc, v42, v1, v42
	v_mul_f32_e32 v44, v43, v11
	v_fma_f32 v45, -v10, v44, v43
	v_fmac_f32_e32 v44, v45, v11
	v_fma_f32 v10, -v10, v44, v43
	v_div_fmas_f32 v10, v10, v11, v44
	v_div_fixup_f32 v1, v10, v1, v42
	v_div_scale_f32 v10, s[4:5], v0, v0, v35
	v_rcp_f32_e32 v11, v10
	s_nop 0
	v_fma_f32 v42, -v10, v11, 1.0
	v_fmac_f32_e32 v11, v42, v11
	v_div_scale_f32 v42, vcc, v35, v0, v35
	v_mul_f32_e32 v43, v42, v11
	v_fma_f32 v44, -v10, v43, v42
	v_fmac_f32_e32 v43, v44, v11
	v_fma_f32 v10, -v10, v43, v42
	v_div_fmas_f32 v10, v10, v11, v43
	v_div_fixup_f32 v0, v10, v0, v35
	v_lshlrev_b32_e32 v35, 16, v40
	v_mul_f32_e32 v10, v2, v0
	v_mul_f32_e32 v11, v3, v1
	v_mul_f32_e32 v0, 0xbfb8aa3b, v35
	v_exp_f32_e32 v42, v0
	global_load_dwordx4 v[0:3], v176, s[6:7] offset:224
	v_and_b32_e32 v40, 0xffff0000, v40
	v_mul_f32_e32 v12, v12, v34
	v_mul_f32_e32 v13, v13, v34
	global_store_dwordx2 v[32:33], v[4:5], off offset:2640
	v_cvt_pk_bf16_f32 v4, v8, v9
	v_cvt_pk_bf16_f32 v5, v10, v11
	global_store_dwordx2 v[32:33], v[4:5], off offset:2656
	s_waitcnt vmcnt(2)
	v_mul_f32_e32 v0, v12, v0
	v_mul_f32_e32 v1, v13, v1
	v_mul_f32_e32 v12, 0xbfb8aa3b, v40
	v_exp_f32_e32 v43, v12
	s_nop 0
	v_add_f32_e32 v12, 1.0, v42
	v_add_f32_e32 v13, 1.0, v43
	s_nop 0
	v_div_scale_f32 v42, s[4:5], v13, v13, v40
	v_rcp_f32_e32 v43, v42
	s_nop 0
	v_fma_f32 v44, -v42, v43, 1.0
	v_fmac_f32_e32 v43, v44, v43
	v_div_scale_f32 v44, vcc, v40, v13, v40
	v_mul_f32_e32 v45, v44, v43
	v_fma_f32 v46, -v42, v45, v44
	v_fmac_f32_e32 v45, v46, v43
	v_fma_f32 v42, -v42, v45, v44
	v_div_fmas_f32 v42, v42, v43, v45
	v_div_fixup_f32 v13, v42, v13, v40
	v_div_scale_f32 v40, s[4:5], v12, v12, v35
	v_rcp_f32_e32 v42, v40
	s_nop 0
	v_fma_f32 v43, -v40, v42, 1.0
	v_fmac_f32_e32 v42, v43, v42
	v_div_scale_f32 v43, vcc, v35, v12, v35
	v_mul_f32_e32 v44, v43, v42
	v_fma_f32 v45, -v40, v44, v43
	v_fmac_f32_e32 v44, v45, v42
	v_fma_f32 v40, -v40, v44, v43
	v_div_fmas_f32 v40, v40, v42, v44
	v_div_fixup_f32 v12, v40, v12, v35
	v_lshlrev_b32_e32 v35, 16, v41
	v_and_b32_e32 v40, 0xffff0000, v41
	v_mul_f32_e32 v0, v0, v12
	v_mul_f32_e32 v1, v1, v13
	v_mul_f32_e32 v12, 0xbfb8aa3b, v35
	v_mul_f32_e32 v13, 0xbfb8aa3b, v40
	v_exp_f32_e32 v12, v12
	v_exp_f32_e32 v13, v13
	v_mul_f32_e32 v14, v14, v34
	v_mul_f32_e32 v15, v15, v34
	v_cvt_pk_bf16_f32 v0, v0, v1
	v_mul_f32_e32 v2, v14, v2
	v_mul_f32_e32 v3, v15, v3
	v_add_f32_e32 v12, 1.0, v12
	v_add_f32_e32 v13, 1.0, v13
	s_nop 0
	v_div_scale_f32 v14, s[4:5], v13, v13, v40
	v_rcp_f32_e32 v15, v14
	s_nop 0
	v_fma_f32 v34, -v14, v15, 1.0
	v_fmac_f32_e32 v15, v34, v15
	v_div_scale_f32 v34, vcc, v40, v13, v40
	v_mul_f32_e32 v41, v34, v15
	v_fma_f32 v42, -v14, v41, v34
	v_fmac_f32_e32 v41, v42, v15
	v_fma_f32 v14, -v14, v41, v34
	v_div_fmas_f32 v14, v14, v15, v41
	v_div_fixup_f32 v13, v14, v13, v40
	v_div_scale_f32 v14, s[4:5], v12, v12, v35
	v_rcp_f32_e32 v15, v14
	s_nop 0
	v_fma_f32 v34, -v14, v15, 1.0
	v_fmac_f32_e32 v15, v34, v15
	v_div_scale_f32 v34, vcc, v35, v12, v35
	v_mul_f32_e32 v40, v34, v15
	v_fma_f32 v41, -v14, v40, v34
	v_fmac_f32_e32 v40, v41, v15
	v_fma_f32 v14, -v14, v40, v34
	v_div_fmas_f32 v14, v14, v15, v40
	v_div_fixup_f32 v12, v14, v12, v35
	v_mul_f32_e32 v2, v2, v12
	v_mul_f32_e32 v3, v3, v13
	v_cvt_pk_bf16_f32 v12, v16, v17
	v_cvt_pk_bf16_f32 v13, v18, v19
	global_store_dwordx2 v[32:33], v[12:13], off offset:2560
	v_cvt_pk_bf16_f32 v12, v20, v21
	v_cvt_pk_bf16_f32 v13, v22, v23
	global_store_dwordx2 v[32:33], v[12:13], off offset:2576
	v_cvt_pk_bf16_f32 v12, v24, v25
	v_cvt_pk_bf16_f32 v13, v26, v27
	global_store_dwordx2 v[32:33], v[12:13], off offset:2592
	v_cvt_pk_bf16_f32 v12, v28, v29
	v_cvt_pk_bf16_f32 v13, v30, v31
	global_store_dwordx2 v[32:33], v[12:13], off offset:2608
	v_cvt_pk_bf16_f32 v12, v36, v37
	v_cvt_pk_bf16_f32 v13, v38, v39
	v_cvt_pk_bf16_f32 v1, v2, v3
	global_store_dwordx2 v[32:33], v[12:13], off offset:2624
	global_store_dwordx2 v[32:33], v[0:1], off offset:2672
